# GDN prep stores w/kT/qk in MFMA-fragment order; scan LDS fragment reads b128 instead of 2x b64
# speedup vs baseline: 1.0231x; 1.0231x over previous
; DEVI bf16_t f2bf(float a) { return (bf16_t)(pack2(a, 0.f) & 0xffff); }
; #define MFMA16(a, b, c) __builtin_amdgcn_mfma_f32_16x16x32_bf16((a), (b), (c), 0, 0, 0)
; DEVI void scan_item(const Params& p, int h, int sl, char* smem) {
;     ...
;       for (int m = 0; m < 2; ++m) {
;         const int mt = cw * 2 + m;
;         bf16x8 qkf[2];
; #pragma unroll
;         for (int s2 = 0; s2 < 2; ++s2) {
;           const char* a = qksm + (mt * 16 + l15) * 144 + s2 * 64 + quad * 8;
;           qkf[s2] = mk8(*(const u32x2*)a, *(const u32x2*)(a + 32));
;         }
;         const f32x4 ge4 = *(const f32x4*)(gsm + mt * 16 + quad * 4);
; #pragma unroll
;         for (int ct = 0; ct < NW; ++ct) {
;           f32x4 a2 = f32x4{0.f, 0.f, 0.f, 0.f};
; #pragma unroll
;           for (int s2 = 0; s2 < 2; ++s2) {
;             const bf16x8 vb = *(const bf16x8*)(vbx + ((ct * 2 + s2) * 64 + lane) * 16);
;             a2 = MFMA16(qkf[s2], vb, a2);
;           }
; #pragma unroll
;           for (int jj = 0; jj < 4; ++jj) {
;             const int t = t0 + mt * 16 + quad * 4 + jj;
;             const float o = ge4[jj] * acco[m][ct][jj] + a2[jj];
;             if (t >= 0) r1[(size_t)t * 3072 + 2048 + h * 128 + vb0 + ct * 16 + l15] = f2bf(o);
;           }
;         }
.LBB0_1213:
	s_or_b64 exec, exec, s[0:1]
	v_add_u32_e32 v0, v179, v190
	v_add_u32_e32 v0, v179, v0
	v_subrev_u32_e32 v0, 32, v0
	s_barrier
	ds_read_b128 v[148:151], v0 offset:17408
	ds_read_b128 v[152:155], v0 offset:17472
	ds_read_b128 v[132:135], v234 offset:59392
	ds_read_b128 v[144:147], v189 offset:50176
	ds_read_b128 v[136:139], v234 offset:60416
	s_waitcnt lgkmcnt(2)
	v_mfma_f32_16x16x32_bf16 v[140:143], v[148:151], v[132:135], 0
	v_add_u32_e32 v0, s9, v180
	v_subrev_u32_e32 v0, 48, v0
	v_cmp_lt_i32_e64 s[0:1], -1, v0
	s_waitcnt lgkmcnt(0)
	v_mfma_f32_16x16x32_bf16 v[140:143], v[152:155], v[136:139], v[140:143]
	v_add_u32_e32 v0, s9, v203
	v_subrev_u32_e32 v235, 48, v0
	v_subrev_u32_e32 v3, 47, v0
	v_subrev_u32_e32 v2, 46, v0
	v_subrev_u32_e32 v0, 45, v0
	s_and_saveexec_b64 s[46:47], s[0:1]
	s_cbranch_execz .LBB0_1215
	v_readlane_b32 s24, v247, 26
	v_readlane_b32 s25, v247, 27
	s_movk_i32 s13, 0x1800
	s_lshl_b32 s62, s5, 1
	v_mov_b64_e32 v[236:237], s[24:25]
	v_mad_u64_u32 v[238:239], s[24:25], v235, s13, v[236:237]
	v_lshl_add_u64 v[238:239], v[238:239], 0, s[62:63]
	v_lshl_add_u64 v[238:239], v[238:239], 0, s[10:11]
	v_lshlrev_b32_e32 v240, 1, v156
	v_mov_b32_e32 v241, v1
	v_lshl_add_u64 v[238:239], v[238:239], 0, v[240:241]
	v_fma_f32 v128, v128, v144, v140
	v_add_co_u32_e32 v238, vcc, s55, v238
	v_cvt_pk_bf16_f32 v128, v128, s0
	s_nop 0
	v_addc_co_u32_e32 v239, vcc, 0, v239, vcc
	global_store_short v[238:239], v128, off
	v_fma_f32 v128, v129, v145, v141
	v_cvt_pk_bf16_f32 v140, v128, s0
	v_mad_u64_u32 v[128:129], s[24:25], v3, s13, v[236:237]
	v_lshl_add_u64 v[128:129], v[128:129], 0, s[62:63]
	v_lshl_add_u64 v[128:129], v[128:129], 0, s[10:11]
	v_lshl_add_u64 v[128:129], v[128:129], 0, v[240:241]
	v_add_co_u32_e32 v128, vcc, s55, v128
	v_fmac_f32_e32 v143, v131, v147
	s_nop 0
	v_addc_co_u32_e32 v129, vcc, 0, v129, vcc
	global_store_short v[128:129], v140, off
	v_fma_f32 v128, v130, v146, v142
	v_cvt_pk_bf16_f32 v130, v128, s0
	v_mad_u64_u32 v[128:129], s[24:25], v2, s13, v[236:237]
	v_lshl_add_u64 v[128:129], v[128:129], 0, s[62:63]
	v_lshl_add_u64 v[128:129], v[128:129], 0, s[10:11]
	v_lshl_add_u64 v[128:129], v[128:129], 0, v[240:241]
	v_add_co_u32_e32 v128, vcc, s55, v128
	s_nop 1
	v_addc_co_u32_e32 v129, vcc, 0, v129, vcc
	global_store_short v[128:129], v130, off
	v_mad_u64_u32 v[128:129], s[24:25], v0, s13, v[236:237]
	v_lshl_add_u64 v[128:129], v[128:129], 0, s[62:63]
	v_lshl_add_u64 v[128:129], v[128:129], 0, s[10:11]
	v_lshl_add_u64 v[128:129], v[128:129], 0, v[240:241]
	v_add_co_u32_e32 v128, vcc, 0x1000, v128
	v_cvt_pk_bf16_f32 v130, v143, s0
	s_nop 0
	v_addc_co_u32_e32 v129, vcc, 0, v129, vcc
	global_store_short v[128:129], v130, off

; DEVI bf16_t f2bf(float a) { return (bf16_t)(pack2(a, 0.f) & 0xffff); }
; #define MFMA16(a, b, c) __builtin_amdgcn_mfma_f32_16x16x32_bf16((a), (b), (c), 0, 0, 0)
; DEVI void scan_item(const Params& p, int h, int sl, char* smem) {
;     ...
;       for (int m = 0; m < 2; ++m) {
;         const int mt = cw * 2 + m;
;         bf16x8 qkf[2];
; #pragma unroll
;         for (int s2 = 0; s2 < 2; ++s2) {
;           const char* a = qksm + (mt * 16 + l15) * 144 + s2 * 64 + quad * 8;
;           qkf[s2] = mk8(*(const u32x2*)a, *(const u32x2*)(a + 32));
;         }
;         const f32x4 ge4 = *(const f32x4*)(gsm + mt * 16 + quad * 4);
; #pragma unroll
;         for (int ct = 0; ct < NW; ++ct) {
;           f32x4 a2 = f32x4{0.f, 0.f, 0.f, 0.f};
; #pragma unroll
;           for (int s2 = 0; s2 < 2; ++s2) {
;             const bf16x8 vb = *(const bf16x8*)(vbx + ((ct * 2 + s2) * 64 + lane) * 16);
;             a2 = MFMA16(qkf[s2], vb, a2);
;           }
; #pragma unroll
;           for (int jj = 0; jj < 4; ++jj) {
;             const int t = t0 + mt * 16 + quad * 4 + jj;
;             const float o = ge4[jj] * acco[m][ct][jj] + a2[jj];
;             if (t >= 0) r1[(size_t)t * 3072 + 2048 + h * 128 + vb0 + ct * 16 + l15] = f2bf(o);
;           }
;         }
.LBB0_1217:
	s_or_b64 exec, exec, s[46:47]
	v_add_u32_e32 v0, v179, v187
	v_add_u32_e32 v0, v179, v0
	v_subrev_u32_e32 v0, 32, v0
	ds_read_b128 v[144:147], v0 offset:17408
	s_nop 1
	ds_read_b128 v[148:151], v0 offset:17472
	ds_read_b128 v[124:127], v185 offset:50240
	v_subrev_u32_e32 v0, 32, v233
	v_cmp_lt_i32_e64 s[0:1], -1, v0
	s_waitcnt lgkmcnt(2)
	v_mfma_f32_16x16x32_bf16 v[132:135], v[144:147], v[132:135], 0
	v_add_u32_e32 v0, s9, v202
	v_subrev_u32_e32 v152, 32, v0
	v_subrev_u32_e32 v3, 31, v0
	s_waitcnt lgkmcnt(1)
	v_mfma_f32_16x16x32_bf16 v[132:135], v[148:151], v[136:139], v[132:135]
	v_subrev_u32_e32 v2, 30, v0
	v_subrev_u32_e32 v0, 29, v0
	s_and_saveexec_b64 s[46:47], s[0:1]
	s_cbranch_execz .LBB0_1219
	v_readlane_b32 s24, v247, 26
	v_readlane_b32 s25, v247, 27
	s_movk_i32 s13, 0x1800
	s_lshl_b32 s62, s5, 1
	v_mov_b64_e32 v[136:137], s[24:25]
	v_mad_u64_u32 v[138:139], s[24:25], v152, s13, v[136:137]
	v_lshl_add_u64 v[138:139], v[138:139], 0, s[62:63]
	v_lshl_add_u64 v[138:139], v[138:139], 0, s[10:11]
	v_lshlrev_b32_e32 v154, 1, v156
	v_mov_b32_e32 v155, v1
	v_lshl_add_u64 v[138:139], v[138:139], 0, v[154:155]
	s_waitcnt lgkmcnt(0)
	v_fma_f32 v120, v120, v124, v132
	v_add_co_u32_e32 v138, vcc, s55, v138
	v_cvt_pk_bf16_f32 v120, v120, s0
	s_nop 0
	v_addc_co_u32_e32 v139, vcc, 0, v139, vcc
	global_store_short v[138:139], v120, off
	v_fma_f32 v120, v121, v125, v133
	v_cvt_pk_bf16_f32 v132, v120, s0
	v_mad_u64_u32 v[120:121], s[24:25], v3, s13, v[136:137]
	v_lshl_add_u64 v[120:121], v[120:121], 0, s[62:63]
	v_lshl_add_u64 v[120:121], v[120:121], 0, s[10:11]
	v_lshl_add_u64 v[120:121], v[120:121], 0, v[154:155]
	v_add_co_u32_e32 v120, vcc, s55, v120
	v_fmac_f32_e32 v135, v123, v127
	s_nop 0
	v_addc_co_u32_e32 v121, vcc, 0, v121, vcc
	global_store_short v[120:121], v132, off
	v_fma_f32 v120, v122, v126, v134
	v_cvt_pk_bf16_f32 v122, v120, s0
	v_mad_u64_u32 v[120:121], s[24:25], v2, s13, v[136:137]
	v_lshl_add_u64 v[120:121], v[120:121], 0, s[62:63]
	v_lshl_add_u64 v[120:121], v[120:121], 0, s[10:11]
	v_lshl_add_u64 v[120:121], v[120:121], 0, v[154:155]
	v_add_co_u32_e32 v120, vcc, s55, v120
	s_nop 1
	v_addc_co_u32_e32 v121, vcc, 0, v121, vcc
	global_store_short v[120:121], v122, off
	v_mad_u64_u32 v[120:121], s[24:25], v0, s13, v[136:137]
	v_lshl_add_u64 v[120:121], v[120:121], 0, s[62:63]
	v_lshl_add_u64 v[120:121], v[120:121], 0, s[10:11]
	v_lshl_add_u64 v[120:121], v[120:121], 0, v[154:155]
	v_add_co_u32_e32 v120, vcc, 0x1000, v120
	v_cvt_pk_bf16_f32 v122, v135, s0
	s_nop 0
	v_addc_co_u32_e32 v121, vcc, 0, v121, vcc
	global_store_short v[120:121], v122, off

; DEVI float bf2f(bf16_t b) { return __uint_as_float(((unsigned)b) << 16); }
; #define MFMA16(a, b, c) __builtin_amdgcn_mfma_f32_16x16x32_bf16((a), (b), (c), 0, 0, 0)
; DEVI void scan_item(const Params& p, int h, int sl, char* smem) {
;     ...
;       bf16x8 sb[4];
; #pragma unroll
;       for (int s = 0; s < 4; ++s) sb[s] = pack8(S[2 * s], S[2 * s + 1]);
;       f32x4 vnew[4];
; #pragma unroll
;       for (int mt = 0; mt < 4; ++mt) vnew[mt] = f32x4{0.f, 0.f, 0.f, 0.f};
; #pragma unroll
;       for (int s = 0; s < 4; ++s) {
; #pragma unroll
;         for (int mt = 0; mt < 4; ++mt) {
;           const char* aw = wsm + (mt * 16 + l15) * 272 + s * 64 + quad * 8;
;           bf16x8 wf = mk8(*(const u32x2*)aw, *(const u32x2*)(aw + 32));
;           vnew[mt] = MFMA16(wf, sb[s], vnew[mt]);
;         }
;       }
; #pragma unroll
;       for (int mt = 0; mt < 4; ++mt) {
; #pragma unroll
;         for (int jj = 0; jj < 4; ++jj) {
;           const int cidx = mt * 16 + quad * 4 + jj;
;           const float u = bf2f(*(const unsigned short*)(usm + cidx * USTR + (cw * 16 + l15) * 2));
;           vnew[mt][jj] = u - vnew[mt][jj];
;         }
;       }
; #pragma unroll
;       for (int s2 = 0; s2 < 2; ++s2)
;         *(bf16x8*)(vbx + ((cw * 2 + s2) * 64 + lane) * 16) = pack8(vnew[2 * s2], vnew[2 * s2 + 1]);
;       __syncthreads();
.LBB0_1222:
	v_add_u32_e32 v0, v179, v191
	v_add_u32_e32 v2, 0x1000, v0
	v_add_u32_e32 v3, 0x2000, v0
	v_add_u32_e32 v148, v179, v0
	v_subrev_u32_e32 v148, 32, v148
	ds_read_b128 v[132:135], v148
	ds_read_b128 v[136:139], v148 offset:4352
	ds_read_b128 v[140:143], v148 offset:8704
	ds_read_b128 v[144:147], v148 offset:13056
	s_waitcnt lgkmcnt(3)
	v_mfma_f32_16x16x32_bf16 v[132:135], v[132:135], v[128:131], 0
	s_waitcnt lgkmcnt(2)
	v_mfma_f32_16x16x32_bf16 v[136:139], v[136:139], v[128:131], 0
	s_waitcnt lgkmcnt(1)
	v_mfma_f32_16x16x32_bf16 v[140:143], v[140:143], v[128:131], 0
	s_waitcnt lgkmcnt(0)
	v_mfma_f32_16x16x32_bf16 v[128:131], v[144:147], v[128:131], 0
	ds_read_b128 v[144:147], v148 offset:64
	s_waitcnt lgkmcnt(0)
	v_mfma_f32_16x16x32_bf16 v[132:135], v[144:147], v[124:127], v[132:135]
	ds_read_b128 v[144:147], v148 offset:4416
	s_waitcnt lgkmcnt(0)
	v_mfma_f32_16x16x32_bf16 v[136:139], v[144:147], v[124:127], v[136:139]
	ds_read_b128 v[144:147], v148 offset:8768
	s_waitcnt lgkmcnt(0)
	v_mfma_f32_16x16x32_bf16 v[140:143], v[144:147], v[124:127], v[140:143]
	ds_read_b128 v[144:147], v148 offset:13120
	s_waitcnt lgkmcnt(0)
	v_mfma_f32_16x16x32_bf16 v[124:127], v[144:147], v[124:127], v[128:131]
	s_nop 2
	ds_read_b128 v[128:131], v148 offset:128
	s_waitcnt lgkmcnt(0)
	v_mfma_f32_16x16x32_bf16 v[128:131], v[128:131], v[120:123], v[132:135]
	s_nop 2
	ds_read_b128 v[132:135], v148 offset:4480
	s_waitcnt lgkmcnt(0)
	v_mfma_f32_16x16x32_bf16 v[132:135], v[132:135], v[120:123], v[136:139]
	s_nop 2
	ds_read_b128 v[136:139], v148 offset:8832
	s_waitcnt lgkmcnt(0)
	v_mfma_f32_16x16x32_bf16 v[136:139], v[136:139], v[120:123], v[140:143]
	s_nop 2
	ds_read_b128 v[140:143], v148 offset:13184
	s_waitcnt lgkmcnt(0)
	v_mfma_f32_16x16x32_bf16 v[120:123], v[140:143], v[120:123], v[124:127]
	s_nop 2
	ds_read_b128 v[124:127], v148 offset:192
	v_add_u32_e32 v0, v181, v182
	s_waitcnt lgkmcnt(0)
	v_mfma_f32_16x16x32_bf16 v[124:127], v[124:127], v[116:119], v[128:131]
	s_nop 2
	ds_read_b128 v[128:131], v148 offset:4544
	s_waitcnt lgkmcnt(0)
	v_mfma_f32_16x16x32_bf16 v[128:131], v[128:131], v[116:119], v[132:135]
	s_nop 2
	ds_read_b128 v[132:135], v148 offset:8896
	s_waitcnt lgkmcnt(0)
	v_mfma_f32_16x16x32_bf16 v[132:135], v[132:135], v[116:119], v[136:139]
	s_nop 2
	ds_read_b128 v[136:139], v148 offset:13248
	ds_read_u16 v2, v0 offset:45056
	ds_read_u16 v3, v0 offset:45136
	s_waitcnt lgkmcnt(1)
	v_lshlrev_b32_e32 v2, 16, v2
	s_waitcnt lgkmcnt(0)
	v_lshlrev_b32_e32 v3, 16, v3
	v_mfma_f32_16x16x32_bf16 v[116:119], v[136:139], v[116:119], v[120:123]
	v_add_f32_e64 v2, v2, -v124
	v_add_f32_e64 v3, v3, -v125
	s_nop 0
	ds_read_u16 v120, v0 offset:45216
	ds_read_u16 v121, v0 offset:45296
	ds_read_u16 v122, v0 offset:46336
	ds_read_u16 v123, v0 offset:46416
	ds_read_u16 v124, v0 offset:46496
	ds_read_u16 v125, v0 offset:46576
	s_waitcnt lgkmcnt(5)
	v_lshlrev_b32_e32 v120, 16, v120
	s_waitcnt lgkmcnt(4)
	v_lshlrev_b32_e32 v121, 16, v121
	s_waitcnt lgkmcnt(2)
	v_lshlrev_b32_e32 v123, 16, v123
	v_lshlrev_b32_e32 v122, 16, v122
	s_waitcnt lgkmcnt(0)
	v_lshlrev_b32_e32 v125, 16, v125
	v_lshlrev_b32_e32 v124, 16, v124
	v_pk_add_f32 v[120:121], v[120:121], v[126:127] neg_lo:[0,1] neg_hi:[0,1]
	v_pk_add_f32 v[122:123], v[122:123], v[128:129] neg_lo:[0,1] neg_hi:[0,1]
	v_pk_add_f32 v[124:125], v[124:125], v[130:131] neg_lo:[0,1] neg_hi:[0,1]
	ds_read_u16 v126, v0 offset:47616
	ds_read_u16 v127, v0 offset:47696
	ds_read_u16 v128, v0 offset:47776
	ds_read_u16 v129, v0 offset:47856
	ds_read_u16 v130, v0 offset:48896
	ds_read_u16 v131, v0 offset:48976
	s_waitcnt lgkmcnt(5)
	v_lshlrev_b32_e32 v126, 16, v126
	s_waitcnt lgkmcnt(4)
	v_lshlrev_b32_e32 v127, 16, v127
	s_waitcnt lgkmcnt(1)
	v_lshlrev_b32_e32 v130, 16, v130
	s_waitcnt lgkmcnt(0)
	v_lshlrev_b32_e32 v131, 16, v131
	v_pk_add_f32 v[130:131], v[130:131], v[116:117] neg_lo:[0,1] neg_hi:[0,1]
	ds_read_u16 v116, v0 offset:49056
	ds_read_u16 v0, v0 offset:49136
	v_lshlrev_b32_e32 v129, 16, v129
	v_lshlrev_b32_e32 v128, 16, v128
	v_pk_add_f32 v[126:127], v[126:127], v[132:133] neg_lo:[0,1] neg_hi:[0,1]
	s_waitcnt lgkmcnt(1)
	v_lshlrev_b32_e32 v116, 16, v116
	s_waitcnt lgkmcnt(0)
	v_lshlrev_b32_e32 v117, 16, v0
	v_pk_add_f32 v[128:129], v[128:129], v[134:135] neg_lo:[0,1] neg_hi:[0,1]
	v_pk_add_f32 v[132:133], v[116:117], v[118:119] neg_lo:[0,1] neg_hi:[0,1]
	v_cvt_pk_bf16_f32 v116, v2, v3
	v_cvt_pk_bf16_f32 v117, v120, v121
	v_cvt_pk_bf16_f32 v118, v122, v123
	v_cvt_pk_bf16_f32 v119, v124, v125
	v_add_u32_e32 v0, v178, v157
	ds_write_b128 v0, v[116:119] offset:59392
	v_cvt_pk_bf16_f32 v116, v126, v127
	v_cvt_pk_bf16_f32 v117, v128, v129
	v_cvt_pk_bf16_f32 v118, v130, v131
	v_cvt_pk_bf16_f32 v119, v132, v133
	ds_write_b128 v0, v[116:119] offset:60416
	s_waitcnt lgkmcnt(0)
	s_barrier
; #define MFMA16(a, b, c) __builtin_amdgcn_mfma_f32_16x16x32_bf16((a), (b), (c), 0, 0, 0)
; DEVI void scan_item(const Params& p, int h, int sl, char* smem) {
;     ...
;       const float eglast = gsm[128];
;       bf16x8 vb[2];
; #pragma unroll
;       for (int mt = 0; mt < 4; ++mt) {
;         const f32x4 gd4 = *(const f32x4*)(gsm + 64 + mt * 16 + quad * 4);
;         vnew[mt] = vnew[mt] * gd4;
;       }
; #pragma unroll
;       for (int s2 = 0; s2 < 2; ++s2) vb[s2] = pack8(vnew[2 * s2], vnew[2 * s2 + 1]);
; #pragma unroll
;       for (int r = 0; r < 8; ++r) S[r] = S[r] * eglast;
; #pragma unroll
;       for (int s2 = 0; s2 < 2; ++s2) {
; #pragma unroll
;         for (int r = 0; r < 8; ++r) {
;           const char* ap = ktsm + (r * 16 + l15) * 144 + s2 * 64 + quad * 8;
;           bf16x8 f = mk8(*(const u32x2*)ap, *(const u32x2*)(ap + 32));
;           S[r] = MFMA16(f, vb[s2], S[r]);
;         }
;       }
	ds_read_b32 v0, v218 offset:50688
	ds_read_b128 v[116:119], v200 offset:50432
	s_waitcnt lgkmcnt(1)
	v_pk_mul_f32 v[94:95], v[94:95], v[0:1] op_sel_hi:[1,0]
	s_waitcnt lgkmcnt(0)
	v_pk_mul_f32 v[134:135], v[120:121], v[118:119]
	v_pk_mul_f32 v[2:3], v[2:3], v[116:117]
	ds_read_b128 v[116:119], v200 offset:50496
	v_pk_mul_f32 v[92:93], v[92:93], v[0:1] op_sel_hi:[1,0]
	v_pk_mul_f32 v[90:91], v[90:91], v[0:1] op_sel_hi:[1,0]
	v_pk_mul_f32 v[88:89], v[88:89], v[0:1] op_sel_hi:[1,0]
	v_pk_mul_f32 v[98:99], v[98:99], v[0:1] op_sel_hi:[1,0]
	s_waitcnt lgkmcnt(0)
	v_pk_mul_f32 v[124:125], v[124:125], v[118:119]
	v_pk_mul_f32 v[122:123], v[122:123], v[116:117]
	ds_read_b128 v[116:119], v200 offset:50560
	v_pk_mul_f32 v[96:97], v[96:97], v[0:1] op_sel_hi:[1,0]
	v_pk_mul_f32 v[102:103], v[102:103], v[0:1] op_sel_hi:[1,0]
	v_pk_mul_f32 v[100:101], v[100:101], v[0:1] op_sel_hi:[1,0]
	v_pk_mul_f32 v[106:107], v[106:107], v[0:1] op_sel_hi:[1,0]
	s_waitcnt lgkmcnt(0)
	v_pk_mul_f32 v[128:129], v[128:129], v[118:119]
	v_pk_mul_f32 v[126:127], v[126:127], v[116:117]
	ds_read_b128 v[116:119], v200 offset:50624
	v_pk_mul_f32 v[104:105], v[104:105], v[0:1] op_sel_hi:[1,0]
	v_pk_mul_f32 v[110:111], v[110:111], v[0:1] op_sel_hi:[1,0]
	v_pk_mul_f32 v[108:109], v[108:109], v[0:1] op_sel_hi:[1,0]
	v_pk_mul_f32 v[114:115], v[114:115], v[0:1] op_sel_hi:[1,0]
	v_pk_mul_f32 v[112:113], v[112:113], v[0:1] op_sel_hi:[1,0]
	v_pk_mul_f32 v[86:87], v[86:87], v[0:1] op_sel_hi:[1,0]
	v_pk_mul_f32 v[84:85], v[84:85], v[0:1] op_sel_hi:[1,0]
	v_add_u32_e32 v0, v179, v232
	v_subrev_u32_e32 v0, 32, v0
	s_waitcnt lgkmcnt(0)
	v_pk_mul_f32 v[132:133], v[132:133], v[118:119]
	v_pk_mul_f32 v[118:119], v[130:131], v[116:117]
	v_cvt_pk_bf16_f32 v122, v122, v123
	v_cvt_pk_bf16_f32 v123, v124, v125
	v_cvt_pk_bf16_f32 v116, v126, v127
	ds_read_b128 v[124:127], v0 offset:26624
	v_cvt_pk_bf16_f32 v120, v2, v3
	v_cvt_pk_bf16_f32 v121, v134, v135
	v_add_u32_e32 v2, 0x7000, v232
	v_add_u32_e32 v3, 0x7800, v232
	s_waitcnt lgkmcnt(0)
	v_mfma_f32_16x16x32_bf16 v[92:95], v[124:127], v[120:123], v[92:95]
	ds_read_b128 v[124:127], v0 offset:28928
	v_cvt_pk_bf16_f32 v117, v128, v129
	v_add_u32_e32 v128, 0x8000, v232
	s_waitcnt lgkmcnt(0)
	v_mfma_f32_16x16x32_bf16 v[88:91], v[124:127], v[120:123], v[88:91]
	ds_read_b128 v[124:127], v0 offset:31232
	v_add_u32_e32 v129, 0x8800, v232
	v_add_u32_e32 v130, 0x9000, v232
	s_waitcnt lgkmcnt(0)
	v_mfma_f32_16x16x32_bf16 v[96:99], v[124:127], v[120:123], v[96:99]
	ds_read_b128 v[124:127], v0 offset:33536
	v_add_u32_e32 v131, 0x9800, v232
	v_cvt_pk_bf16_f32 v118, v118, v119
	s_waitcnt lgkmcnt(0)
	v_mfma_f32_16x16x32_bf16 v[100:103], v[124:127], v[120:123], v[100:103]
	ds_read_b128 v[124:127], v0 offset:35840
	v_cvt_pk_bf16_f32 v119, v132, v133
	v_add_u32_e32 v132, 0xa000, v232
	s_waitcnt lgkmcnt(0)
	v_mfma_f32_16x16x32_bf16 v[104:107], v[124:127], v[120:123], v[104:107]
	ds_read_b128 v[124:127], v0 offset:38144
	s_waitcnt lgkmcnt(0)
	v_mfma_f32_16x16x32_bf16 v[108:111], v[124:127], v[120:123], v[108:111]
	ds_read_b128 v[124:127], v0 offset:40448
	s_waitcnt lgkmcnt(0)
	v_mfma_f32_16x16x32_bf16 v[112:115], v[124:127], v[120:123], v[112:115]
	ds_read_b128 v[124:127], v0 offset:42752
	s_waitcnt lgkmcnt(0)
	v_mfma_f32_16x16x32_bf16 v[84:87], v[124:127], v[120:123], v[84:87]
	ds_read_b128 v[120:123], v0 offset:26688
	s_waitcnt lgkmcnt(0)
	v_mfma_f32_16x16x32_bf16 v[92:95], v[120:123], v[116:119], v[92:95]
	ds_read_b128 v[120:123], v0 offset:28992
	s_waitcnt lgkmcnt(0)
	v_mfma_f32_16x16x32_bf16 v[88:91], v[120:123], v[116:119], v[88:91]
	ds_read_b128 v[120:123], v0 offset:31296
	s_waitcnt lgkmcnt(0)
	v_mfma_f32_16x16x32_bf16 v[96:99], v[120:123], v[116:119], v[96:99]
	ds_read_b128 v[120:123], v0 offset:33600
	s_waitcnt lgkmcnt(0)
	v_mfma_f32_16x16x32_bf16 v[100:103], v[120:123], v[116:119], v[100:103]
	ds_read_b128 v[120:123], v0 offset:35904
	s_waitcnt lgkmcnt(0)
	v_mfma_f32_16x16x32_bf16 v[104:107], v[120:123], v[116:119], v[104:107]
	ds_read_b128 v[120:123], v0 offset:38208
	s_waitcnt lgkmcnt(0)
	v_mfma_f32_16x16x32_bf16 v[108:111], v[120:123], v[116:119], v[108:111]
	ds_read_b128 v[120:123], v0 offset:40512
	s_waitcnt lgkmcnt(0)
	v_mfma_f32_16x16x32_bf16 v[112:115], v[120:123], v[116:119], v[112:115]
	ds_read_b128 v[120:123], v0 offset:42816
	s_waitcnt lgkmcnt(0)
	v_mfma_f32_16x16x32_bf16 v[84:87], v[120:123], v[116:119], v[84:87]
	s_branch .LBB0_1182

; DEVI bf16_t f2bf(float a) { return (bf16_t)(pack2(a, 0.f) & 0xffff); }
; #define MFMA16(a, b, c) __builtin_amdgcn_mfma_f32_16x16x32_bf16((a), (b), (c), 0, 0, 0)
; DEVI void scan_item(const Params& p, int h, int sl, char* smem) {
;     ...
; #pragma unroll
;     for (int i = 0; i < 2; ++i) {
;       const int ch = tid + i * 256, row = ch >> 3, kc = ch & 7;
;       *(u32x4*)(qksm + row * 144 + kc * 16) = pqk[i];
;     }
; #pragma unroll
;     for (int i = 0; i < 4; ++i) {
;       const int ch = tid + i * 256, row = ch >> 3, kc = ch & 7;
;       *(u32x4*)(ktsm + row * 144 + kc * 16) = pkt[i];
;     }
;     ...
;       f32x4 acco[2][NW];
; #pragma unroll
;       for (int ct = 0; ct < NW; ++ct) {
;         bf16x8 sb[4];
; #pragma unroll
;         for (int s = 0; s < 4; ++s) sb[s] = *(const bf16x8*)(sbx + ((ct * 4 + s) * 64 + lane) * 16);
; #pragma unroll
;         for (int m = 0; m < 2; ++m) acco[m][ct] = f32x4{0.f, 0.f, 0.f, 0.f};
; #pragma unroll
;         for (int s = 0; s < 4; ++s)
; #pragma unroll
;           for (int m = 0; m < 2; ++m) acco[m][ct] = MFMA16(qfr[m][s], sb[s], acco[m][ct]);
;       }
;       if (n + 1 < NCH) qload(n + 1);
;       __syncthreads();
;       const int t0 = n * 64 - 48;
; #pragma unroll
;       for (int m = 0; m < 2; ++m) {
;         const int mt = cw * 2 + m;
;         bf16x8 qkf[2];
; #pragma unroll
;         for (int s2 = 0; s2 < 2; ++s2) {
;           const char* a = qksm + (mt * 16 + l15) * 144 + s2 * 64 + quad * 8;
;           qkf[s2] = mk8(*(const u32x2*)a, *(const u32x2*)(a + 32));
;         }
;         const f32x4 ge4 = *(const f32x4*)(gsm + mt * 16 + quad * 4);
; #pragma unroll
;         for (int ct = 0; ct < NW; ++ct) {
;           f32x4 a2 = f32x4{0.f, 0.f, 0.f, 0.f};
; #pragma unroll
;           for (int s2 = 0; s2 < 2; ++s2) {
;             const bf16x8 vb = *(const bf16x8*)(vbx + ((ct * 2 + s2) * 64 + lane) * 16);
;             a2 = MFMA16(qkf[s2], vb, a2);
;           }
; #pragma unroll
;           for (int jj = 0; jj < 4; ++jj) {
;             const int t = t0 + mt * 16 + quad * 4 + jj;
;             const float o = ge4[jj] * acco[m][ct][jj] + a2[jj];
;             if (t >= 0) r1[(size_t)t * 3072 + 2048 + h * 128 + vb0 + ct * 16 + l15] = f2bf(o);
;           }
;         }
.LBB0_1229:
	s_or_b64 exec, exec, s[0:1]
	s_waitcnt lgkmcnt(0)
	s_barrier
	ds_write_b128 v196, v[32:35] offset:17408
	ds_write_b128 v197, v[36:39] offset:17408
	ds_write_b128 v196, v[48:51] offset:26624
	ds_write_b128 v197, v[52:55] offset:26624
	ds_write_b128 v198, v[60:63] offset:26624
	ds_write_b128 v199, v[64:67] offset:26624
	s_and_saveexec_b64 s[0:1], s[36:37]
	s_xor_b64 s[16:17], exec, s[0:1]
	s_cbranch_execz .LBB0_1235
	v_add_u32_e32 v0, 32, v157
	ds_read_b128 v[2:5], v0 offset:51200
	ds_read_b128 v[24:27], v0 offset:52224
	s_movk_i32 s9, 0x3fd0
	s_movk_i32 s0, 0xc02f
	v_add3_u32 v51, v180, v184, s9
	s_waitcnt lgkmcnt(1)
	v_mfma_f32_16x16x32_bf16 v[6:9], v[28:31], v[2:5], 0
	v_cmp_lt_i32_e64 s[0:1], s0, v180
	v_or_b32_e32 v50, 1, v51
	v_mfma_f32_16x16x32_bf16 v[2:5], v[80:83], v[2:5], 0
	s_waitcnt lgkmcnt(0)
	v_mfma_f32_16x16x32_bf16 v[6:9], v[20:23], v[24:27], v[6:9]
	v_mfma_f32_16x16x32_bf16 v[2:5], v[72:75], v[24:27], v[2:5]
	ds_read_b128 v[24:27], v0 offset:53248
	s_waitcnt lgkmcnt(0)
	v_mfma_f32_16x16x32_bf16 v[6:9], v[12:15], v[24:27], v[6:9]
	v_mfma_f32_16x16x32_bf16 v[2:5], v[76:79], v[24:27], v[2:5]
	ds_read_b128 v[24:27], v0 offset:54272
	s_waitcnt lgkmcnt(0)
	v_mfma_f32_16x16x32_bf16 v[34:37], v[16:19], v[24:27], v[6:9]
	v_mfma_f32_16x16x32_bf16 v[6:9], v[56:59], v[24:27], v[2:5]
	s_nop 3
	ds_read_b128 v[2:5], v0 offset:55296
	s_waitcnt lgkmcnt(0)
	v_mfma_f32_16x16x32_bf16 v[24:27], v[28:31], v[2:5], 0
	ds_read_b128 v[28:31], v0 offset:56320
	s_waitcnt lgkmcnt(0)
	v_mfma_f32_16x16x32_bf16 v[20:23], v[20:23], v[28:31], v[24:27]
	s_nop 4
	ds_read_b128 v[24:27], v0 offset:57344
	ds_read_b128 v[46:49], v0 offset:58368
	s_waitcnt lgkmcnt(0)
	s_barrier
	v_mfma_f32_16x16x32_bf16 v[2:5], v[80:83], v[2:5], 0
	v_mfma_f32_16x16x32_bf16 v[10:13], v[12:15], v[24:27], v[20:23]
	v_add_u32_e32 v14, v179, v190
	v_add_u32_e32 v14, v179, v14
	v_subrev_u32_e32 v14, 32, v14
	ds_read_b128 v[38:41], v14 offset:17408
	v_mfma_f32_16x16x32_bf16 v[2:5], v[72:75], v[28:31], v[2:5]
	v_mfma_f32_16x16x32_bf16 v[2:5], v[76:79], v[24:27], v[2:5]
	v_mfma_f32_16x16x32_bf16 v[26:29], v[16:19], v[46:49], v[10:13]
	ds_read_b128 v[42:45], v14 offset:17472
	ds_read_b128 v[30:33], v189 offset:50176
	ds_read_b128 v[18:21], v0 offset:59392
	ds_read_b128 v[22:25], v0 offset:60416
	s_waitcnt lgkmcnt(1)
	v_mfma_f32_16x16x32_bf16 v[10:13], v[38:41], v[18:21], 0
	v_mfma_f32_16x16x32_bf16 v[2:5], v[56:59], v[46:49], v[2:5]
	v_or_b32_e32 v49, 2, v51
	v_or_b32_e32 v48, 3, v51
	v_lshlrev_b32_e32 v46, 1, v156
	s_waitcnt lgkmcnt(0)
	v_mfma_f32_16x16x32_bf16 v[10:13], v[42:45], v[22:25], v[10:13]
	s_and_saveexec_b64 s[36:37], s[0:1]
	s_cbranch_execz .LBB0_1232
	v_readlane_b32 s24, v247, 26
	v_readlane_b32 s25, v247, 27
	s_movk_i32 s9, 0x1800
	s_lshl_b32 s62, s5, 1
	v_mov_b64_e32 v[14:15], s[24:25]
	v_mad_u64_u32 v[16:17], s[24:25], v51, s9, v[14:15]
	v_lshl_add_u64 v[16:17], v[16:17], 0, s[62:63]
	v_lshl_add_u64 v[16:17], v[16:17], 0, s[10:11]
	v_mov_b32_e32 v47, v1
	v_lshl_add_u64 v[16:17], v[16:17], 0, v[46:47]
	v_fma_f32 v10, v34, v30, v10
	v_add_co_u32_e32 v16, vcc, s55, v16
	v_cvt_pk_bf16_f32 v10, v10, s0
	s_nop 0
	v_addc_co_u32_e32 v17, vcc, 0, v17, vcc
	global_store_short v[16:17], v10, off
	v_fma_f32 v10, v35, v31, v11
	v_cvt_pk_bf16_f32 v16, v10, s0
	v_mad_u64_u32 v[10:11], s[24:25], v50, s9, v[14:15]
	v_lshl_add_u64 v[10:11], v[10:11], 0, s[62:63]
	v_lshl_add_u64 v[10:11], v[10:11], 0, s[10:11]
	v_lshl_add_u64 v[10:11], v[10:11], 0, v[46:47]
	v_add_co_u32_e32 v10, vcc, s55, v10
	v_fmac_f32_e32 v13, v37, v33
	s_nop 0
	v_addc_co_u32_e32 v11, vcc, 0, v11, vcc
	global_store_short v[10:11], v16, off
	v_fma_f32 v10, v36, v32, v12
	v_cvt_pk_bf16_f32 v12, v10, s0
	v_mad_u64_u32 v[10:11], s[24:25], v49, s9, v[14:15]
	v_lshl_add_u64 v[10:11], v[10:11], 0, s[62:63]
	v_lshl_add_u64 v[10:11], v[10:11], 0, s[10:11]
	v_lshl_add_u64 v[10:11], v[10:11], 0, v[46:47]
	v_add_co_u32_e32 v10, vcc, s55, v10
	s_nop 1
	v_addc_co_u32_e32 v11, vcc, 0, v11, vcc
	global_store_short v[10:11], v12, off
	v_mad_u64_u32 v[10:11], s[24:25], v48, s9, v[14:15]
	v_lshl_add_u64 v[10:11], v[10:11], 0, s[62:63]
	v_lshl_add_u64 v[10:11], v[10:11], 0, s[10:11]
	v_lshl_add_u64 v[10:11], v[10:11], 0, v[46:47]
	v_add_co_u32_e32 v10, vcc, 0x1000, v10
	v_cvt_pk_bf16_f32 v12, v13, s0
	s_nop 0
	v_addc_co_u32_e32 v11, vcc, 0, v11, vcc
	global_store_short v[10:11], v12, off

; DEVI bf16_t f2bf(float a) { return (bf16_t)(pack2(a, 0.f) & 0xffff); }
; #define MFMA16(a, b, c) __builtin_amdgcn_mfma_f32_16x16x32_bf16((a), (b), (c), 0, 0, 0)
; DEVI void scan_item(const Params& p, int h, int sl, char* smem) {
;     ...
;       for (int m = 0; m < 2; ++m) {
;         const int mt = cw * 2 + m;
;         bf16x8 qkf[2];
; #pragma unroll
;         for (int s2 = 0; s2 < 2; ++s2) {
;           const char* a = qksm + (mt * 16 + l15) * 144 + s2 * 64 + quad * 8;
;           qkf[s2] = mk8(*(const u32x2*)a, *(const u32x2*)(a + 32));
;         }
;         const f32x4 ge4 = *(const f32x4*)(gsm + mt * 16 + quad * 4);
; #pragma unroll
;         for (int ct = 0; ct < NW; ++ct) {
;           f32x4 a2 = f32x4{0.f, 0.f, 0.f, 0.f};
; #pragma unroll
;           for (int s2 = 0; s2 < 2; ++s2) {
;             const bf16x8 vb = *(const bf16x8*)(vbx + ((ct * 2 + s2) * 64 + lane) * 16);
;             a2 = MFMA16(qkf[s2], vb, a2);
;           }
; #pragma unroll
;           for (int jj = 0; jj < 4; ++jj) {
;             const int t = t0 + mt * 16 + quad * 4 + jj;
;             const float o = ge4[jj] * acco[m][ct][jj] + a2[jj];
;             if (t >= 0) r1[(size_t)t * 3072 + 2048 + h * 128 + vb0 + ct * 16 + l15] = f2bf(o);
;           }
;         }
.LBB0_1234:
	s_or_b64 exec, exec, s[36:37]
	v_add_u32_e32 v0, v179, v187
	v_add_u32_e32 v0, v179, v0
	v_subrev_u32_e32 v0, 32, v0
	ds_read_b128 v[26:29], v0 offset:17408
	ds_read_b128 v[30:33], v0 offset:17472
	s_nop 0
	ds_read_b128 v[34:37], v185 offset:50240
	v_add_u32_e32 v0, v183, v184
	v_add_u32_e32 v38, 0x3fe0, v0
	s_waitcnt lgkmcnt(2)
	v_mfma_f32_16x16x32_bf16 v[18:21], v[26:29], v[18:21], 0
	s_movk_i32 s9, 0x1800
	s_lshl_b32 s62, s5, 1
	v_mov_b32_e32 v47, v1
	s_waitcnt lgkmcnt(1)
	v_mfma_f32_16x16x32_bf16 v[18:21], v[30:33], v[22:25], v[18:21]
	s_waitcnt lgkmcnt(0)
	s_nop 6
	v_fma_f32 v6, v6, v34, v18
	v_cvt_pk_bf16_f32 v6, v6, s0
	v_readlane_b32 s0, v247, 26
	v_readlane_b32 s1, v247, 27
	v_add_u32_e32 v18, 0x3fe1, v0
	v_fmac_f32_e32 v21, v9, v37
	v_mov_b64_e32 v[22:23], s[0:1]
	v_mad_u64_u32 v[24:25], s[0:1], v38, s9, v[22:23]
	v_lshl_add_u64 v[24:25], v[24:25], 0, s[62:63]
	v_lshl_add_u64 v[24:25], v[24:25], 0, s[10:11]
	v_lshl_add_u64 v[24:25], v[24:25], 0, v[46:47]
	v_add_co_u32_e32 v24, vcc, s55, v24
	s_nop 1
	v_addc_co_u32_e32 v25, vcc, 0, v25, vcc
	global_store_short v[24:25], v6, off
	v_fma_f32 v6, v7, v35, v19
	v_cvt_pk_bf16_f32 v19, v6, s0
	v_mad_u64_u32 v[6:7], s[0:1], v18, s9, v[22:23]
	v_lshl_add_u64 v[6:7], v[6:7], 0, s[62:63]
	v_lshl_add_u64 v[6:7], v[6:7], 0, s[10:11]
	v_lshl_add_u64 v[6:7], v[6:7], 0, v[46:47]
	v_add_co_u32_e32 v6, vcc, s55, v6
	s_nop 1
	v_addc_co_u32_e32 v7, vcc, 0, v7, vcc
	global_store_short v[6:7], v19, off
	v_add_u32_e32 v19, 0x3fe2, v0
	v_fma_f32 v6, v8, v36, v20
	v_cvt_pk_bf16_f32 v8, v6, s0
	v_mad_u64_u32 v[6:7], s[0:1], v19, s9, v[22:23]
	v_lshl_add_u64 v[6:7], v[6:7], 0, s[62:63]
	v_lshl_add_u64 v[6:7], v[6:7], 0, s[10:11]
	v_lshl_add_u64 v[6:7], v[6:7], 0, v[46:47]
	v_add_co_u32_e32 v6, vcc, s55, v6
	v_add_u32_e32 v0, 0x3fe3, v0
	s_nop 0
	v_addc_co_u32_e32 v7, vcc, 0, v7, vcc
	global_store_short v[6:7], v8, off
	v_cvt_pk_bf16_f32 v8, v21, s0
	v_mad_u64_u32 v[6:7], s[0:1], v0, s9, v[22:23]
	v_lshl_add_u64 v[6:7], v[6:7], 0, s[62:63]
	v_lshl_add_u64 v[6:7], v[6:7], 0, s[10:11]
	v_lshl_add_u64 v[6:7], v[6:7], 0, v[46:47]
	v_add_co_u32_e32 v6, vcc, s55, v6
	s_nop 1
	v_addc_co_u32_e32 v7, vcc, 0, v7, vcc
	global_store_short v[6:7], v8, off
	v_mfma_f32_16x16x32_bf16 v[6:9], v[26:29], v[14:17], 0
	v_mfma_f32_16x16x32_bf16 v[6:9], v[30:33], v[10:13], v[6:9]
	v_mov_b64_e32 v[10:11], s[6:7]
	s_nop 6
	v_fma_f32 v2, v2, v34, v6
	v_cvt_pk_bf16_f32 v2, v2, s0
	v_mad_u64_u32 v[12:13], s[0:1], v38, s9, v[10:11]
	v_lshl_add_u64 v[12:13], v[12:13], 0, v[46:47]
	v_add_co_u32_e32 v12, vcc, s55, v12
	v_fmac_f32_e32 v9, v5, v37
	s_nop 0
	v_addc_co_u32_e32 v13, vcc, 0, v13, vcc
	global_store_short v[12:13], v2, off offset:32
	v_fma_f32 v2, v3, v35, v7
	v_cvt_pk_bf16_f32 v6, v2, s0
	v_mad_u64_u32 v[2:3], s[0:1], v18, s9, v[10:11]
	v_lshl_add_u64 v[2:3], v[2:3], 0, v[46:47]
	v_add_co_u32_e32 v2, vcc, s55, v2
	s_nop 1
	v_addc_co_u32_e32 v3, vcc, 0, v3, vcc
	global_store_short v[2:3], v6, off offset:32
	v_fma_f32 v2, v4, v36, v8
	v_cvt_pk_bf16_f32 v4, v2, s0
	v_mad_u64_u32 v[2:3], s[0:1], v19, s9, v[10:11]
	v_lshl_add_u64 v[2:3], v[2:3], 0, v[46:47]
	v_add_co_u32_e32 v2, vcc, s55, v2
	s_nop 1
	v_addc_co_u32_e32 v3, vcc, 0, v3, vcc
	global_store_short v[2:3], v4, off offset:32
	v_cvt_pk_bf16_f32 v4, v9, s0
	v_mad_u64_u32 v[2:3], s[0:1], v0, s9, v[10:11]
	v_lshl_add_u64 v[2:3], v[2:3], 0, v[46:47]
	v_add_co_u32_e32 v2, vcc, 0x1000, v2
	s_nop 1
	v_addc_co_u32_e32 v3, vcc, 0, v3, vcc
	global_store_short v[2:3], v4, off offset:32
; DEVI float bf2f(bf16_t b) { return __uint_as_float(((unsigned)b) << 16); }
; #define MFMA16(a, b, c) __builtin_amdgcn_mfma_f32_16x16x32_bf16((a), (b), (c), 0, 0, 0)
; DEVI void scan_item(const Params& p, int h, int sl, char* smem) {
;     ...
;     if (is_state) {
;       bf16x8 sb[4];
; #pragma unroll
;       for (int s = 0; s < 4; ++s) sb[s] = pack8(S[2 * s], S[2 * s + 1]);
;       f32x4 vnew[4];
; #pragma unroll
;       for (int mt = 0; mt < 4; ++mt) vnew[mt] = f32x4{0.f, 0.f, 0.f, 0.f};
; #pragma unroll
;       for (int s = 0; s < 4; ++s) {
; #pragma unroll
;         for (int mt = 0; mt < 4; ++mt) {
;           const char* aw = wsm + (mt * 16 + l15) * 272 + s * 64 + quad * 8;
;           bf16x8 wf = mk8(*(const u32x2*)aw, *(const u32x2*)(aw + 32));
;           vnew[mt] = MFMA16(wf, sb[s], vnew[mt]);
;         }
;       }
; #pragma unroll
;       for (int mt = 0; mt < 4; ++mt) {
; #pragma unroll
;         for (int jj = 0; jj < 4; ++jj) {
;           const int cidx = mt * 16 + quad * 4 + jj;
;           const float u = bf2f(*(const unsigned short*)(usm + cidx * USTR + (cw * 16 + l15) * 2));
;           vnew[mt][jj] = u - vnew[mt][jj];
;         }
;       }
; #pragma unroll
;       for (int s2 = 0; s2 < 2; ++s2)
;         *(bf16x8*)(vbx + ((cw * 2 + s2) * 64 + lane) * 16) = pack8(vnew[2 * s2], vnew[2 * s2 + 1]);
;       __syncthreads();
.LBB0_1235:
	s_andn2_saveexec_b64 s[0:1], s[16:17]
	s_cbranch_execz .LBB0_1237
	v_add_u32_e32 v0, v179, v191
	v_add_u32_e32 v38, v179, v0
	v_subrev_u32_e32 v38, 32, v38
	ds_read_b128 v[10:13], v38
	ds_read_b128 v[32:35], v38 offset:64
	v_add_u32_e32 v36, 0x1000, v0
	ds_read_b128 v[14:17], v38 offset:4352
	v_add_u32_e32 v37, 0x2000, v0
	ds_read_b128 v[18:21], v38 offset:8704
	ds_read_b128 v[28:31], v38 offset:13056
	s_waitcnt lgkmcnt(4)
	v_mfma_f32_16x16x32_bf16 v[10:13], v[10:13], v[40:43], 0
	s_waitcnt lgkmcnt(3)
	v_mfma_f32_16x16x32_bf16 v[10:13], v[32:35], v[24:27], v[10:13]
	ds_read_b128 v[32:35], v38 offset:4416
	s_waitcnt lgkmcnt(3)
	v_mfma_f32_16x16x32_bf16 v[14:17], v[14:17], v[40:43], 0
	s_waitcnt lgkmcnt(2)
	v_mfma_f32_16x16x32_bf16 v[18:21], v[18:21], v[40:43], 0
	s_waitcnt lgkmcnt(0)
	v_mfma_f32_16x16x32_bf16 v[14:17], v[32:35], v[24:27], v[14:17]
	ds_read_b128 v[32:35], v38 offset:8768
	v_mfma_f32_16x16x32_bf16 v[28:31], v[28:31], v[40:43], 0
	s_waitcnt lgkmcnt(0)
	v_mfma_f32_16x16x32_bf16 v[18:21], v[32:35], v[24:27], v[18:21]
	ds_read_b128 v[32:35], v38 offset:13120
	s_waitcnt lgkmcnt(0)
	v_mfma_f32_16x16x32_bf16 v[22:25], v[32:35], v[24:27], v[28:31]
	s_nop 2
	ds_read_b128 v[26:29], v38 offset:128
	s_waitcnt lgkmcnt(0)
	v_mfma_f32_16x16x32_bf16 v[10:13], v[26:29], v[6:9], v[10:13]
	ds_read_b128 v[26:29], v38 offset:4480
	s_waitcnt lgkmcnt(0)
	v_mfma_f32_16x16x32_bf16 v[14:17], v[26:29], v[6:9], v[14:17]
	ds_read_b128 v[26:29], v38 offset:8832
	s_waitcnt lgkmcnt(0)
	v_mfma_f32_16x16x32_bf16 v[18:21], v[26:29], v[6:9], v[18:21]
	ds_read_b128 v[26:29], v38 offset:13184
	s_waitcnt lgkmcnt(0)
	v_mfma_f32_16x16x32_bf16 v[6:9], v[26:29], v[6:9], v[22:25]
	s_nop 2
	ds_read_b128 v[22:25], v38 offset:192
	v_add_u32_e32 v0, v181, v182
	s_waitcnt lgkmcnt(0)
	v_mfma_f32_16x16x32_bf16 v[10:13], v[22:25], v[2:5], v[10:13]
	ds_read_b128 v[22:25], v38 offset:4544
	s_waitcnt lgkmcnt(0)
	v_mfma_f32_16x16x32_bf16 v[14:17], v[22:25], v[2:5], v[14:17]
	ds_read_b128 v[22:25], v38 offset:8896
	s_waitcnt lgkmcnt(0)
	v_mfma_f32_16x16x32_bf16 v[18:21], v[22:25], v[2:5], v[18:21]
	ds_read_b128 v[22:25], v38 offset:13248
	s_waitcnt lgkmcnt(0)
	v_mfma_f32_16x16x32_bf16 v[2:5], v[22:25], v[2:5], v[6:9]
	s_nop 2
	ds_read_u16 v6, v0 offset:45056
	ds_read_u16 v7, v0 offset:45136
	ds_read_u16 v8, v0 offset:45216
	ds_read_u16 v9, v0 offset:45296
	s_waitcnt lgkmcnt(3)
	v_lshlrev_b32_e32 v6, 16, v6
	s_waitcnt lgkmcnt(2)
	v_lshlrev_b32_e32 v7, 16, v7
	v_pk_add_f32 v[6:7], v[6:7], v[10:11] neg_lo:[0,1] neg_hi:[0,1]
	ds_read_u16 v10, v0 offset:46336
	ds_read_u16 v11, v0 offset:46416
	s_waitcnt lgkmcnt(2)
	v_lshlrev_b32_e32 v9, 16, v9
	v_lshlrev_b32_e32 v8, 16, v8
	v_pk_add_f32 v[8:9], v[8:9], v[12:13] neg_lo:[0,1] neg_hi:[0,1]
	s_waitcnt lgkmcnt(1)
	v_lshlrev_b32_e32 v10, 16, v10
	s_waitcnt lgkmcnt(0)
	v_lshlrev_b32_e32 v11, 16, v11
	v_pk_add_f32 v[10:11], v[10:11], v[14:15] neg_lo:[0,1] neg_hi:[0,1]
	ds_read_u16 v12, v0 offset:46496
	ds_read_u16 v13, v0 offset:46576
	ds_read_u16 v14, v0 offset:47616
	ds_read_u16 v15, v0 offset:47696
	s_waitcnt lgkmcnt(3)
	v_lshlrev_b32_e32 v12, 16, v12
	s_waitcnt lgkmcnt(2)
	v_lshlrev_b32_e32 v13, 16, v13
	s_waitcnt lgkmcnt(0)
	v_lshlrev_b32_e32 v15, 16, v15
	v_lshlrev_b32_e32 v14, 16, v14
	v_pk_add_f32 v[12:13], v[12:13], v[16:17] neg_lo:[0,1] neg_hi:[0,1]
	v_pk_add_f32 v[14:15], v[14:15], v[18:19] neg_lo:[0,1] neg_hi:[0,1]
	ds_read_u16 v16, v0 offset:47776
	ds_read_u16 v17, v0 offset:47856
	ds_read_u16 v18, v0 offset:48896
	ds_read_u16 v19, v0 offset:48976
	s_waitcnt lgkmcnt(3)
	v_lshlrev_b32_e32 v16, 16, v16
	s_waitcnt lgkmcnt(1)
	v_lshlrev_b32_e32 v18, 16, v18
	s_waitcnt lgkmcnt(0)
	v_lshlrev_b32_e32 v19, 16, v19
	v_pk_add_f32 v[18:19], v[18:19], v[2:3] neg_lo:[0,1] neg_hi:[0,1]
	ds_read_u16 v2, v0 offset:49056
	ds_read_u16 v0, v0 offset:49136
	v_lshlrev_b32_e32 v17, 16, v17
	v_pk_add_f32 v[16:17], v[16:17], v[20:21] neg_lo:[0,1] neg_hi:[0,1]
	s_waitcnt lgkmcnt(1)
	v_lshlrev_b32_e32 v2, 16, v2
	s_waitcnt lgkmcnt(0)
	v_lshlrev_b32_e32 v3, 16, v0
	v_pk_add_f32 v[20:21], v[2:3], v[4:5] neg_lo:[0,1] neg_hi:[0,1]
	v_cvt_pk_bf16_f32 v2, v6, v7
	v_cvt_pk_bf16_f32 v3, v8, v9
	v_cvt_pk_bf16_f32 v4, v10, v11
	v_cvt_pk_bf16_f32 v5, v12, v13
	v_add_u32_e32 v0, v178, v157
	ds_write_b128 v0, v[2:5] offset:59392
	v_cvt_pk_bf16_f32 v2, v14, v15
	v_cvt_pk_bf16_f32 v3, v16, v17
	v_cvt_pk_bf16_f32 v4, v18, v19
	v_cvt_pk_bf16_f32 v5, v20, v21
	ds_write_b128 v0, v[2:5] offset:60416
	s_waitcnt lgkmcnt(0)
	s_barrier

; DEVI bf16_t f2bf(float a) { return (bf16_t)(pack2(a, 0.f) & 0xffff); }
; DEVI void prep_item(const Params& p, int j, int n, int h, char* smem) {
;     ...
;     bf16_t* qkout = r0 + R0_QK + (size_t)(n * 8 + h) * 4096;
; #pragma unroll
;     for (int nt = 0; nt < 4; ++nt) {
;       const int jx = nt * 16 + l15;
;       const float gj = sgc[jx];
; #pragma unroll
;       for (int jj = 0; jj < 4; ++jj) {
;         const int i = wave * 16 + quad * 4 + jj;
;         const float dec = __expf(fminf(sgc[i] - gj, 0.f));
;         am[i * 68 + jx] = (jx < i) ? sbeta[i] * akk[nt][jj] * dec : 0.f;
;         qkout[i * 64 + jx] = f2bf((jx <= i) ? aqk[nt][jj] * dec : 0.f);
;       }
;     }
.LBB0_1263:
	s_or_b64 exec, exec, s[0:1]
	s_movk_i32 s0, 0x110
	v_and_b32_e32 v86, 12, v0
	v_and_b32_e32 v87, 3, v0
	v_lshl_or_b32 v86, v86, 1, v87
	v_mov_b32_e32 v87, 0
	v_mul_f32_e32 v26, v26, v47
	v_lshl_add_u32 v30, v0, 2, 32
	v_mul_lo_u32 v45, v35, s0
	v_cmp_le_i32_e32 vcc, v0, v35
	v_cvt_pk_bf16_f32 v26, v26, s0
	v_add_u32_e32 v45, v30, v45
	v_cndmask_b32_e32 v30, 0, v26, vcc
	v_lshlrev_b32_e32 v26, 6, v35
	v_lshlrev_b64 v[38:39], 13, v[36:37]
	ds_write_b32 v45, v48 offset:52224
	v_or_b32_e32 v48, v26, v86
	v_lshl_add_u64 v[38:39], s[36:37], 0, v[38:39]
	v_ashrrev_i32_e32 v49, 31, v48
	v_lshl_add_u64 v[48:49], v[48:49], 1, v[38:39]
	v_or_b32_e32 v47, 1, v35
	global_store_short v[48:49], v30, off
	v_lshl_add_u32 v48, v47, 2, 32
	v_add_u32_e32 v49, 0x11100, v48
	ds_read_b32 v30, v49
	v_mov_b32_e32 v50, 0
	s_waitcnt lgkmcnt(0)
	v_sub_f32_e32 v30, v30, v56
	v_min_f32_e32 v30, 0, v30
	v_mul_f32_e32 v30, 0x3fb8aa3b, v30
	v_exp_f32_e32 v30, v30
	s_and_saveexec_b64 s[0:1], vcc
	s_cbranch_execz .LBB0_1265
	v_add_u32_e32 v50, 0x11000, v48
	ds_read_b32 v50, v50
	s_waitcnt lgkmcnt(0)
	v_mul_f32_e32 v31, v31, v50
	v_mul_f32_e32 v50, v30, v31
.LBB0_1265:
	s_or_b64 exec, exec, s[0:1]
	v_mul_f32_e32 v27, v27, v30
	v_lshlrev_b32_e32 v30, 6, v47
	ds_write_b32 v45, v50 offset:52496
	v_or_b32_e32 v50, v30, v86
	v_cvt_pk_bf16_f32 v27, v27, s0
	v_cmp_le_i32_e32 vcc, v0, v47
	v_ashrrev_i32_e32 v51, 31, v50
	v_lshl_add_u64 v[50:51], v[50:51], 1, v[38:39]
	v_cndmask_b32_e32 v27, 0, v27, vcc
	global_store_short v[50:51], v27, off
	v_or_b32_e32 v50, 2, v35
	v_lshl_add_u32 v51, v50, 2, 32
	v_add_u32_e32 v52, 0x11100, v51
	ds_read_b32 v27, v52
	v_cmp_lt_i32_e32 vcc, v0, v50
	s_waitcnt lgkmcnt(0)
	v_sub_f32_e32 v27, v27, v56
	v_min_f32_e32 v27, 0, v27
	v_mul_f32_e32 v27, 0x3fb8aa3b, v27
	v_exp_f32_e32 v27, v27
	s_and_saveexec_b64 s[0:1], vcc
	s_cbranch_execz .LBB0_1267
	v_add_u32_e32 v31, 0x11000, v51
	ds_read_b32 v31, v31
	s_waitcnt lgkmcnt(0)
	v_mul_f32_e32 v31, v32, v31
	v_mul_f32_e32 v53, v27, v31
.LBB0_1267:
	s_or_b64 exec, exec, s[0:1]
	v_mul_f32_e32 v27, v28, v27
	v_lshlrev_b32_e32 v28, 6, v50
	v_or_b32_e32 v54, v28, v86
	v_cvt_pk_bf16_f32 v27, v27, s0
	v_cmp_le_i32_e32 vcc, v0, v50
	v_ashrrev_i32_e32 v55, 31, v54
	ds_write_b32 v45, v53 offset:52768
	v_cndmask_b32_e32 v27, 0, v27, vcc
	v_lshl_add_u64 v[54:55], v[54:55], 1, v[38:39]
	v_or_b32_e32 v53, 3, v35
	global_store_short v[54:55], v27, off
	v_lshl_add_u32 v54, v53, 2, 32
	v_add_u32_e32 v55, 0x11100, v54
	ds_read_b32 v27, v55
	v_cmp_lt_i32_e32 vcc, v0, v53
	v_mov_b32_e32 v32, 0
	s_waitcnt lgkmcnt(0)
	v_sub_f32_e32 v31, v27, v56
	v_min_f32_e32 v31, 0, v31
	v_mul_f32_e32 v31, 0x3fb8aa3b, v31
	v_exp_f32_e32 v31, v31
	v_mov_b32_e32 v27, 0
	s_and_saveexec_b64 s[0:1], vcc
	s_cbranch_execz .LBB0_1269
	v_add_u32_e32 v32, 0x11000, v54
	ds_read_b32 v32, v32
	s_waitcnt lgkmcnt(0)
	v_mul_f32_e32 v32, v33, v32
	v_mul_f32_e32 v32, v31, v32
.LBB0_1269:
	s_or_b64 exec, exec, s[0:1]
	ds_write_b32 v45, v32 offset:53040
	v_lshlrev_b32_e32 v32, 6, v53
	v_mul_f32_e32 v29, v29, v31
	v_or_b32_e32 v56, v32, v86
	v_cvt_pk_bf16_f32 v29, v29, s0
	v_cmp_le_i32_e32 vcc, v0, v53
	v_ashrrev_i32_e32 v57, 31, v56
	v_or_b32_e32 v33, 16, v0
	v_cndmask_b32_e32 v29, 0, v29, vcc
	v_lshl_add_u64 v[56:57], v[56:57], 1, v[38:39]
	global_store_short v[56:57], v29, off
	v_lshl_add_u32 v29, v33, 2, 32
	v_add_u32_e32 v29, 0x11100, v29
	ds_read_b32 v56, v29
	ds_read_b32 v29, v44
	v_cmp_lt_i32_e32 vcc, v33, v35
	s_waitcnt lgkmcnt(0)
	v_sub_f32_e32 v29, v29, v56
	v_min_f32_e32 v29, 0, v29
	v_mul_f32_e32 v29, 0x3fb8aa3b, v29
	v_exp_f32_e32 v29, v29
	s_and_saveexec_b64 s[0:1], vcc
	s_cbranch_execz .LBB0_1271
	v_add_u32_e32 v27, 0x11000, v46
	ds_read_b32 v27, v27
	s_waitcnt lgkmcnt(0)
	v_mul_f32_e32 v22, v22, v27
	v_mul_f32_e32 v27, v29, v22
.LBB0_1271:
	s_or_b64 exec, exec, s[0:1]
	ds_write_b32 v45, v27 offset:52288
	v_mul_f32_e32 v18, v18, v29
	v_ashrrev_i32_e32 v27, 31, v26
	v_cmp_le_i32_e32 vcc, v33, v35
	v_cvt_pk_bf16_f32 v18, v18, s0
	v_lshl_add_u64 v[26:27], v[26:27], 0, v[86:87]
	v_cndmask_b32_e32 v18, 0, v18, vcc
	v_lshl_add_u64 v[26:27], v[26:27], 1, v[38:39]
	global_store_short v[26:27], v18, off offset:8
	ds_read_b32 v18, v49
	v_mov_b32_e32 v22, 0
	v_mov_b32_e32 v29, 0
	s_waitcnt lgkmcnt(0)
	v_sub_f32_e32 v18, v18, v56
	v_min_f32_e32 v18, 0, v18
	v_mul_f32_e32 v18, 0x3fb8aa3b, v18
	v_exp_f32_e32 v18, v18
	s_and_saveexec_b64 s[0:1], vcc
	s_cbranch_execz .LBB0_1273
	v_add_u32_e32 v29, 0x11000, v48
	ds_read_b32 v29, v29
	s_waitcnt lgkmcnt(0)
	v_mul_f32_e32 v23, v23, v29
	v_mul_f32_e32 v29, v18, v23
.LBB0_1273:
	s_or_b64 exec, exec, s[0:1]
	v_mul_f32_e32 v18, v19, v18
	v_cvt_pk_bf16_f32 v18, v18, s0
	v_cmp_le_i32_e32 vcc, v33, v47
	v_ashrrev_i32_e32 v31, 31, v30
	ds_write_b32 v45, v29 offset:52560
	v_cndmask_b32_e32 v23, 0, v18, vcc
	v_lshl_add_u64 v[18:19], v[30:31], 0, v[86:87]
	v_lshl_add_u64 v[18:19], v[18:19], 1, v[38:39]
	global_store_short v[18:19], v23, off offset:8
	ds_read_b32 v23, v52
	v_cmp_lt_i32_e32 vcc, v33, v50
	s_waitcnt lgkmcnt(0)
	v_sub_f32_e32 v23, v23, v56
	v_min_f32_e32 v23, 0, v23
	v_mul_f32_e32 v23, 0x3fb8aa3b, v23
	v_exp_f32_e32 v23, v23
	s_and_saveexec_b64 s[0:1], vcc
	s_cbranch_execz .LBB0_1275
	v_add_u32_e32 v22, 0x11000, v51
	ds_read_b32 v22, v22
	s_waitcnt lgkmcnt(0)
	v_mul_f32_e32 v22, v24, v22
	v_mul_f32_e32 v22, v23, v22
.LBB0_1275:
	s_or_b64 exec, exec, s[0:1]
	v_mul_f32_e32 v20, v20, v23
	v_ashrrev_i32_e32 v29, 31, v28
	ds_write_b32 v45, v22 offset:52832
	v_cvt_pk_bf16_f32 v20, v20, s0
	v_cmp_le_i32_e32 vcc, v33, v50
	v_lshl_add_u64 v[22:23], v[28:29], 0, v[86:87]
	v_lshl_add_u64 v[22:23], v[22:23], 1, v[38:39]
	v_cndmask_b32_e32 v20, 0, v20, vcc
	global_store_short v[22:23], v20, off offset:8
	ds_read_b32 v20, v55
	v_mov_b32_e32 v28, 0
	v_cmp_lt_i32_e32 vcc, v33, v53
	v_mov_b32_e32 v29, 0
	s_waitcnt lgkmcnt(0)
	v_sub_f32_e32 v20, v20, v56
	v_min_f32_e32 v20, 0, v20
	v_mul_f32_e32 v20, 0x3fb8aa3b, v20
	v_exp_f32_e32 v20, v20
	s_and_saveexec_b64 s[0:1], vcc
	s_cbranch_execz .LBB0_1277
	v_add_u32_e32 v24, 0x11000, v54
	ds_read_b32 v24, v24
	s_waitcnt lgkmcnt(0)
	v_mul_f32_e32 v24, v25, v24
	v_mul_f32_e32 v29, v20, v24
.LBB0_1277:
	s_or_b64 exec, exec, s[0:1]
	v_mul_f32_e32 v20, v21, v20
	v_cvt_pk_bf16_f32 v20, v20, s0
	v_cmp_le_i32_e32 vcc, v33, v53
	v_ashrrev_i32_e32 v33, 31, v32
	v_or_b32_e32 v24, 32, v0
	v_cndmask_b32_e32 v25, 0, v20, vcc
	v_lshl_add_u64 v[20:21], v[32:33], 0, v[86:87]
	v_lshl_add_u64 v[20:21], v[20:21], 1, v[38:39]
	global_store_short v[20:21], v25, off offset:8
	v_lshl_add_u32 v25, v24, 2, 32
	ds_write_b32 v45, v29 offset:53104
	v_add_u32_e32 v25, 0x11100, v25
	ds_read_b32 v25, v25
	ds_read_b32 v29, v44
	v_cmp_lt_i32_e32 vcc, v24, v35
	s_waitcnt lgkmcnt(0)
	v_sub_f32_e32 v29, v29, v25
	v_min_f32_e32 v29, 0, v29
	v_mul_f32_e32 v29, 0x3fb8aa3b, v29
	v_exp_f32_e32 v29, v29
	s_and_saveexec_b64 s[0:1], vcc
	s_cbranch_execz .LBB0_1279
	v_add_u32_e32 v28, 0x11000, v46
	ds_read_b32 v28, v28
	s_waitcnt lgkmcnt(0)
	v_mul_f32_e32 v14, v14, v28
	v_mul_f32_e32 v28, v29, v14

; DEVI bf16_t f2bf(float a) { return (bf16_t)(pack2(a, 0.f) & 0xffff); }
; DEVI float bf2f(bf16_t b) { return __uint_as_float(((unsigned)b) << 16); }
; DEVI void prep_item(const Params& p, int j, int n, int h, char* smem) {
;     ...
; #pragma unroll
;     for (int nt = 0; nt < 4; ++nt) {
;       const int jx = nt * 16 + l15;
;       const float gj = sgc[jx];
; #pragma unroll
;       for (int jj = 0; jj < 4; ++jj) {
;         const int i = wave * 16 + quad * 4 + jj;
;         const float dec = __expf(fminf(sgc[i] - gj, 0.f));
;         am[i * 68 + jx] = (jx < i) ? sbeta[i] * akk[nt][jj] * dec : 0.f;
;         qkout[i * 64 + jx] = f2bf((jx <= i) ? aqk[nt][jj] * dec : 0.f);
;       }
;     }
;   }
;   __syncthreads();
;   {
;     bf16_t* kt = r0 + R0_KT + (size_t)(n * 8 + h) * 8192;
; #pragma unroll
;     for (int i = 0; i < 4; ++i) {
;       const int unit = tid + i * 256, d = unit >> 3, i0 = (unit & 7) * 8;
;       unsigned e[8];
; #pragma unroll
;       for (int q = 0; q < 8; ++q) e[q] = *(const unsigned short*)(ks + (i0 + q) * 272 + d * 2);
;       u32x4 o = {e[0] | (e[1] << 16), e[2] | (e[3] << 16), e[4] | (e[5] << 16), e[6] | (e[7] << 16)};
;       *(u32x4*)(kt + d * 64 + i0) = o;
;     }
;   }
;   {
;     const int c = tid;
;     const bool isu = c < 128;
;     const char* src = isu ? (vs + c * 2) : (ks + (c - 128) * 2);
;     float x[64];
; #pragma unroll
;     for (int i = 0; i < 64; ++i) x[i] = 0.f;
;     int zero;
;     asm volatile("v_mov_b32 %0, 0" : "=v"(zero));
; #pragma unroll
;     for (int i = 0; i < 64; ++i) {
;       const float* amz = am + zero;
;       const float* sbz = sbeta + zero;
;       const float eg = __expf(sbz[64 + i]);
;       float acc = bf2f(*(const unsigned short*)(src + i * 272)) * sbz[i] * (isu ? 1.0f : eg);
.LBB0_1287:
	s_or_b64 exec, exec, s[0:1]
	ds_write_b32 v45, v11 offset:52416
	ds_read_b32 v6, v49
	v_mul_f32_e32 v2, v2, v12
	v_cvt_pk_bf16_f32 v2, v2, s0
	v_cmp_le_i32_e32 vcc, v0, v35
	v_mov_b32_e32 v11, 0
	s_waitcnt lgkmcnt(0)
	v_sub_f32_e32 v6, v6, v10
	v_min_f32_e32 v6, 0, v6
	v_mul_f32_e32 v6, 0x3fb8aa3b, v6
	v_exp_f32_e32 v6, v6
	v_cndmask_b32_e32 v2, 0, v2, vcc
	global_store_short v[26:27], v2, off offset:72
	v_mov_b32_e32 v2, 0
	s_and_saveexec_b64 s[0:1], vcc
	s_cbranch_execz .LBB0_1289
	v_add_u32_e32 v11, 0x11000, v48
	ds_read_b32 v11, v11
	s_waitcnt lgkmcnt(0)
	v_mul_f32_e32 v7, v7, v11
	v_mul_f32_e32 v11, v6, v7
.LBB0_1289:
	s_or_b64 exec, exec, s[0:1]
	ds_write_b32 v45, v11 offset:52688
	ds_read_b32 v7, v52
	v_mul_f32_e32 v3, v3, v6
	v_cvt_pk_bf16_f32 v6, v3, s0
	v_cmp_le_i32_e32 vcc, v0, v47
	s_waitcnt lgkmcnt(0)
	v_sub_f32_e32 v3, v7, v10
	v_min_f32_e32 v3, 0, v3
	v_mul_f32_e32 v3, 0x3fb8aa3b, v3
	v_exp_f32_e32 v3, v3
	v_cndmask_b32_e32 v6, 0, v6, vcc
	v_cmp_lt_i32_e32 vcc, v0, v50
	global_store_short v[18:19], v6, off offset:72
	s_and_saveexec_b64 s[0:1], vcc
	s_cbranch_execz .LBB0_1291
	v_add_u32_e32 v2, 0x11000, v51
	ds_read_b32 v2, v2
	s_waitcnt lgkmcnt(0)
	v_mul_f32_e32 v2, v8, v2
	v_mul_f32_e32 v2, v3, v2
.LBB0_1291:
	s_or_b64 exec, exec, s[0:1]
	ds_write_b32 v45, v2 offset:52960
	ds_read_b32 v2, v55
	v_mul_f32_e32 v3, v4, v3
	v_cvt_pk_bf16_f32 v3, v3, s0
	v_cmp_le_i32_e32 vcc, v0, v50
	s_waitcnt lgkmcnt(0)
	v_sub_f32_e32 v2, v2, v10
	v_min_f32_e32 v2, 0, v2
	v_mul_f32_e32 v2, 0x3fb8aa3b, v2
	v_exp_f32_e32 v2, v2
	v_cndmask_b32_e32 v3, 0, v3, vcc
	global_store_short v[22:23], v3, off offset:72
	v_mov_b32_e32 v3, 0
	v_cmp_lt_i32_e32 vcc, v0, v53
	s_and_saveexec_b64 s[0:1], vcc
	s_cbranch_execz .LBB0_1293
	v_add_u32_e32 v3, 0x11000, v54
	ds_read_b32 v3, v3
	s_waitcnt lgkmcnt(0)
	v_mul_f32_e32 v3, v9, v3
	v_mul_f32_e32 v3, v2, v3
.LBB0_1293:
	s_or_b64 exec, exec, s[0:1]
	v_mul_f32_e32 v2, v5, v2
	v_cvt_pk_bf16_f32 v2, v2, s0
	v_cmp_le_i32_e32 vcc, v0, v53
	v_and_b32_e32 v4, 56, v41
	v_ashrrev_i32_e32 v8, 3, v34
	v_cndmask_b32_e32 v0, 0, v2, vcc
	global_store_short v[20:21], v0, off offset:72
	v_lshlrev_b32_e32 v0, 1, v4
	v_and_b32_e32 v85, 24, v4
	v_and_b32_e32 v10, 32, v4
	v_lshrrev_b32_e32 v85, 1, v85
	v_or_b32_e32 v10, v10, v85
	v_mul_u32_u24_e32 v10, 0x110, v10
	v_lshlrev_b32_e32 v4, 1, v8
	v_add3_u32 v4, 32, v4, v10
	ds_write_b32 v45, v3 offset:53232
	s_waitcnt lgkmcnt(0)
	s_barrier
	v_lshlrev_b64 v[2:3], 14, v[36:37]
	ds_read_u16 v5, v4 offset:17408
	ds_read_u16 v9, v4 offset:17680
	ds_read_u16 v11, v4 offset:17952
	ds_read_u16 v12, v4 offset:18224
	ds_read_u16 v13, v4 offset:21760
	ds_read_u16 v14, v4 offset:22032
	ds_read_u16 v15, v4 offset:22304
	ds_read_u16 v16, v4 offset:22576
	v_lshl_add_u64 v[2:3], s[30:31], 0, v[2:3]
	v_lshl_add_u64 v[6:7], v[2:3], 0, v[0:1]
	v_ashrrev_i32_e32 v0, 3, v40
	s_waitcnt lgkmcnt(4)
	v_lshl_or_b32 v3, v12, 16, v11
	v_lshlrev_b32_e32 v11, 1, v0
	v_add3_u32 v11, 32, v11, v10
	v_lshl_or_b32 v2, v9, 16, v5
	s_waitcnt lgkmcnt(2)
	v_lshl_or_b32 v4, v14, 16, v13
	s_waitcnt lgkmcnt(0)
	v_lshl_or_b32 v5, v16, 16, v15
	ds_read_u16 v12, v11 offset:17408
	ds_read_u16 v13, v11 offset:17680
	ds_read_u16 v14, v11 offset:17952
	ds_read_u16 v15, v11 offset:18224
	ds_read_u16 v16, v11 offset:21760
	ds_read_u16 v17, v11 offset:22032
	ds_read_u16 v18, v11 offset:22304
	ds_read_u16 v11, v11 offset:22576
	v_lshlrev_b32_e32 v8, 6, v8
	v_ashrrev_i32_e32 v9, 31, v8
	v_lshl_add_u64 v[8:9], v[8:9], 1, v[6:7]
	global_store_dwordx4 v[8:9], v[2:5], off
	v_lshlrev_b32_e32 v8, 6, v0
	v_ashrrev_i32_e32 v0, 3, v42
	s_waitcnt lgkmcnt(0)
	v_lshl_or_b32 v5, v11, 16, v18
	v_lshlrev_b32_e32 v11, 1, v0
	v_add3_u32 v11, 32, v11, v10
	v_lshl_or_b32 v2, v13, 16, v12
	v_lshl_or_b32 v3, v15, 16, v14
	v_lshl_or_b32 v4, v17, 16, v16
	ds_read_u16 v12, v11 offset:17408
	ds_read_u16 v13, v11 offset:17680
	ds_read_u16 v14, v11 offset:17952
	ds_read_u16 v15, v11 offset:18224
	ds_read_u16 v16, v11 offset:21760
	ds_read_u16 v17, v11 offset:22032
	ds_read_u16 v18, v11 offset:22304
	ds_read_u16 v11, v11 offset:22576
	v_ashrrev_i32_e32 v9, 31, v8
	v_lshl_add_u64 v[8:9], v[8:9], 1, v[6:7]
	global_store_dwordx4 v[8:9], v[2:5], off
	v_lshlrev_b32_e32 v8, 6, v0
	v_ashrrev_i32_e32 v0, 3, v43
	s_waitcnt lgkmcnt(0)
	v_lshl_or_b32 v5, v11, 16, v18
	v_lshlrev_b32_e32 v11, 1, v0
	v_add3_u32 v10, 32, v11, v10
	v_lshl_or_b32 v2, v13, 16, v12
	v_lshl_or_b32 v3, v15, 16, v14
	v_lshl_or_b32 v4, v17, 16, v16
	ds_read_u16 v11, v10 offset:17408
	ds_read_u16 v12, v10 offset:17680
	ds_read_u16 v13, v10 offset:17952
	ds_read_u16 v14, v10 offset:18224
	ds_read_u16 v15, v10 offset:21760
	ds_read_u16 v16, v10 offset:22032
	ds_read_u16 v17, v10 offset:22304
	ds_read_u16 v10, v10 offset:22576
	v_ashrrev_i32_e32 v9, 31, v8
	v_lshl_add_u64 v[8:9], v[8:9], 1, v[6:7]
	global_store_dwordx4 v[8:9], v[2:5], off
	v_lshlrev_b32_e32 v8, 6, v0
	v_ashrrev_i32_e32 v9, 31, v8
	s_waitcnt lgkmcnt(6)
	v_lshl_or_b32 v2, v12, 16, v11
	s_waitcnt lgkmcnt(4)
	v_lshl_or_b32 v3, v14, 16, v13
	s_waitcnt lgkmcnt(2)
	v_lshl_or_b32 v4, v16, 16, v15
	s_waitcnt lgkmcnt(0)
	v_lshl_or_b32 v5, v10, 16, v17
	v_lshl_add_u64 v[6:7], v[8:9], 1, v[6:7]
	s_add_i32 s0, 32, 0x11000
	global_store_dwordx4 v[6:7], v[2:5], off
	v_mov_b32 v0, 0
	v_cmp_gt_i32_e32 vcc, s49, v34
	s_lshl_b32 s62, s7, 1
	v_lshl_add_u32 v3, v0, 2, s0
	ds_read2st64_b32 v[4:5], v3 offset1:1
	v_lshl_add_u32 v2, v34, 1, 32
	v_add_u32_e32 v3, 0x4300, v2
	v_add_u32_e32 v2, 0x8800, v2
	v_cndmask_b32_e32 v2, v3, v2, vcc
	s_waitcnt lgkmcnt(0)
	v_mul_f32_e32 v3, 0x3fb8aa3b, v5
	ds_read_u16 v5, v2
	v_exp_f32_e32 v3, v3
	s_cmp_lt_i32 s44, 1
	s_waitcnt lgkmcnt(0)
; DEVI float bf2f(bf16_t b) { return __uint_as_float(((unsigned)b) << 16); }
; DEVI void prep_item(const Params& p, int j, int n, int h, char* smem) {
;     ...
;     for (int i = 0; i < 64; ++i) {
;       const float* amz = am + zero;
;       const float* sbz = sbeta + zero;
;       const float eg = __expf(sbz[64 + i]);
;       float acc = bf2f(*(const unsigned short*)(src + i * 272)) * sbz[i] * (isu ? 1.0f : eg);
; #pragma unroll
;       for (int j4 = 0; j4 < (i + 3) / 4; ++j4) {
;         const f32x4 a = *(const f32x4*)(amz + i * 68 + j4 * 4);
;         acc -= a[0] * x[j4 * 4 + 0];
;         acc -= a[1] * x[j4 * 4 + 1];
;         acc -= a[2] * x[j4 * 4 + 2];
;         acc -= a[3] * x[j4 * 4 + 3];
;       }
;       asm volatile("" : "+v"(zero), "+v"(acc));
;       x[i] = acc;
;     }
	v_lshlrev_b32_e32 v5, 16, v5
	v_cndmask_b32_e64 v3, v3, 1.0, vcc
	v_mul_f32_e32 v4, v4, v5
	v_mul_f32_e32 v4, v3, v4
	s_nop 0
	v_lshlrev_b32_e32 v3, 2, v0
	v_add_u32_e32 v5, s0, v3
	ds_read2_b32 v[10:11], v5 offset0:1 offset1:65
	v_add_u32_e32 v3, 32, v3
	ds_read_b128 v[6:9], v3 offset:52496
	s_waitcnt lgkmcnt(1)
	v_mul_f32_e32 v5, 0x3fb8aa3b, v11
	ds_read_u16 v11, v2 offset:272
	v_exp_f32_e32 v5, v5
	s_waitcnt lgkmcnt(1)
	v_mul_f32_e32 v6, v4, v6
	v_cndmask_b32_e64 v3, v5, 1.0, vcc
	s_waitcnt lgkmcnt(0)
	v_lshlrev_b32_e32 v5, 16, v11
	v_mul_f32_e32 v5, v10, v5
	v_fma_f32 v5, v3, v5, -v6
	v_fmac_f32_e32 v5, 0x80000000, v7
	v_fmac_f32_e32 v5, 0x80000000, v8
	v_fmac_f32_e32 v5, 0x80000000, v9
	ds_read_u16 v12, v2 offset:544
	v_lshlrev_b32_e32 v3, 2, v0
	v_add_u32_e32 v6, s0, v3
	ds_read2_b32 v[10:11], v6 offset0:2 offset1:66
	v_add_u32_e32 v3, 32, v3
	s_waitcnt lgkmcnt(0)
	v_mul_f32_e32 v6, 0x3fb8aa3b, v11
	v_exp_f32_e32 v11, v6
	ds_read_b128 v[6:9], v3 offset:52768
	v_cndmask_b32_e64 v3, v11, 1.0, vcc
	v_lshlrev_b32_e32 v11, 16, v12
	v_mul_f32_e32 v10, v10, v11
	s_waitcnt lgkmcnt(0)
	v_mul_f32_e32 v6, v4, v6
	v_fma_f32 v3, v3, v10, -v6
	v_fma_f32 v6, -v5, v7, v3
	v_fmac_f32_e32 v6, 0x80000000, v8
	v_fmac_f32_e32 v6, 0x80000000, v9
	s_nop 0
	v_lshlrev_b32_e32 v3, 2, v0
	v_add_u32_e32 v7, s0, v3
	ds_read2_b32 v[12:13], v7 offset0:3 offset1:67
	v_add_u32_e32 v3, 32, v3
	ds_read_b128 v[8:11], v3 offset:53040
	s_waitcnt lgkmcnt(1)
	v_mul_f32_e32 v7, 0x3fb8aa3b, v13
	ds_read_u16 v13, v2 offset:816
	v_exp_f32_e32 v7, v7
	s_waitcnt lgkmcnt(1)
	v_mul_f32_e32 v8, v4, v8
	v_cndmask_b32_e64 v3, v7, 1.0, vcc
	s_waitcnt lgkmcnt(0)
	v_lshlrev_b32_e32 v7, 16, v13
	v_mul_f32_e32 v7, v12, v7
	v_fma_f32 v3, v3, v7, -v8
	v_fma_f32 v3, -v5, v9, v3
	v_fma_f32 v7, -v6, v10, v3
	v_fmac_f32_e32 v7, 0x80000000, v11
	ds_read_u16 v14, v2 offset:1088
	v_lshlrev_b32_e32 v3, 2, v0
	v_add_u32_e32 v8, s0, v3
	ds_read2_b32 v[12:13], v8 offset0:4 offset1:68
	v_add_u32_e32 v3, 32, v3
	s_waitcnt lgkmcnt(0)
	v_mul_f32_e32 v8, 0x3fb8aa3b, v13
	v_exp_f32_e32 v13, v8
	ds_read_b128 v[8:11], v3 offset:53312
	v_cndmask_b32_e64 v3, v13, 1.0, vcc
	v_lshlrev_b32_e32 v13, 16, v14
	v_mul_f32_e32 v12, v12, v13
	s_waitcnt lgkmcnt(0)
	v_mul_f32_e32 v8, v4, v8
	v_fma_f32 v3, v3, v12, -v8
	v_fma_f32 v3, -v5, v9, v3
	v_fma_f32 v3, -v6, v10, v3
	v_fma_f32 v8, -v7, v11, v3
	s_nop 0
	v_lshlrev_b32_e32 v3, 2, v0
	v_add_u32_e32 v9, s0, v3
	ds_read2_b32 v[14:15], v9 offset0:5 offset1:69
	v_add_u32_e32 v3, 32, v3
	ds_read_b128 v[10:13], v3 offset:53584
	s_waitcnt lgkmcnt(1)
	v_mul_f32_e32 v9, 0x3fb8aa3b, v15
	ds_read_u16 v15, v2 offset:1360
	v_exp_f32_e32 v9, v9
	s_waitcnt lgkmcnt(0)
	v_lshlrev_b32_e32 v15, 16, v15
	v_cndmask_b32_e64 v9, v9, 1.0, vcc
	v_mul_f32_e32 v18, v14, v15
	ds_read_b128 v[14:17], v3 offset:53600
	v_mul_f32_e32 v3, v4, v10
	v_fma_f32 v3, v9, v18, -v3
	v_fma_f32 v3, -v5, v11, v3
	v_fma_f32 v3, -v6, v12, v3
	v_fma_f32 v3, -v7, v13, v3
	s_waitcnt lgkmcnt(0)
	v_fma_f32 v9, -v8, v14, v3
	v_fmac_f32_e32 v9, 0x80000000, v15
	v_fmac_f32_e32 v9, 0x80000000, v16
	v_fmac_f32_e32 v9, 0x80000000, v17
	ds_read_u16 v16, v2 offset:1632
	v_lshlrev_b32_e32 v3, 2, v0
	v_add_u32_e32 v10, s0, v3
	ds_read2_b32 v[14:15], v10 offset0:6 offset1:70
	v_add_u32_e32 v3, 32, v3
	s_waitcnt lgkmcnt(0)
	v_mul_f32_e32 v10, 0x3fb8aa3b, v15
	v_exp_f32_e32 v15, v10
	ds_read_b128 v[10:13], v3 offset:53856
	v_cndmask_b32_e64 v18, v15, 1.0, vcc
	v_lshlrev_b32_e32 v15, 16, v16
	v_mul_f32_e32 v19, v14, v15
	ds_read_b128 v[14:17], v3 offset:53872
	s_waitcnt lgkmcnt(1)
	v_mul_f32_e32 v3, v4, v10
	v_fma_f32 v3, v18, v19, -v3
	v_fma_f32 v3, -v5, v11, v3
	v_fma_f32 v3, -v6, v12, v3
	v_fma_f32 v3, -v7, v13, v3
	s_waitcnt lgkmcnt(0)
	v_fma_f32 v3, -v8, v14, v3
	v_fma_f32 v10, -v9, v15, v3
	v_fmac_f32_e32 v10, 0x80000000, v16
	v_fmac_f32_e32 v10, 0x80000000, v17
	s_nop 0
	v_lshlrev_b32_e32 v3, 2, v0
	v_add_u32_e32 v11, s0, v3
	ds_read2_b32 v[16:17], v11 offset0:7 offset1:71
	v_add_u32_e32 v3, 32, v3
	ds_read_b128 v[12:15], v3 offset:54128
	s_waitcnt lgkmcnt(1)
	v_mul_f32_e32 v11, 0x3fb8aa3b, v17
	ds_read_u16 v17, v2 offset:1904
	v_exp_f32_e32 v11, v11
	s_waitcnt lgkmcnt(0)
	v_lshlrev_b32_e32 v17, 16, v17
	v_cndmask_b32_e64 v11, v11, 1.0, vcc
	v_mul_f32_e32 v20, v16, v17
	ds_read_b128 v[16:19], v3 offset:54144
	v_mul_f32_e32 v3, v4, v12
	v_fma_f32 v3, v11, v20, -v3
	v_fma_f32 v3, -v5, v13, v3
	v_fma_f32 v3, -v6, v14, v3
	v_fma_f32 v3, -v7, v15, v3
	s_waitcnt lgkmcnt(0)
	v_fma_f32 v3, -v8, v16, v3
	v_fma_f32 v3, -v9, v17, v3
	v_fma_f32 v11, -v10, v18, v3
	v_fmac_f32_e32 v11, 0x80000000, v19
	ds_read_u16 v18, v2 offset:2176
	v_lshlrev_b32_e32 v3, 2, v0
	v_add_u32_e32 v12, s0, v3
	ds_read2_b32 v[16:17], v12 offset0:8 offset1:72
	v_add_u32_e32 v3, 32, v3
	s_waitcnt lgkmcnt(0)
	v_mul_f32_e32 v12, 0x3fb8aa3b, v17
	v_exp_f32_e32 v17, v12
	ds_read_b128 v[12:15], v3 offset:54400
	v_cndmask_b32_e64 v20, v17, 1.0, vcc
	v_lshlrev_b32_e32 v17, 16, v18
	v_mul_f32_e32 v21, v16, v17
	ds_read_b128 v[16:19], v3 offset:54416
	s_waitcnt lgkmcnt(1)
	v_mul_f32_e32 v3, v4, v12
	v_fma_f32 v3, v20, v21, -v3
	v_fma_f32 v3, -v5, v13, v3
	v_fma_f32 v3, -v6, v14, v3
	v_fma_f32 v3, -v7, v15, v3
	s_waitcnt lgkmcnt(0)
	v_fma_f32 v3, -v8, v16, v3
	v_fma_f32 v3, -v9, v17, v3
	v_fma_f32 v3, -v10, v18, v3
	v_fma_f32 v12, -v11, v19, v3
	s_nop 0
	v_lshlrev_b32_e32 v3, 2, v0
	v_add_u32_e32 v13, s0, v3
	ds_read2_b32 v[18:19], v13 offset0:9 offset1:73
	v_add_u32_e32 v3, 32, v3
	ds_read_b128 v[14:17], v3 offset:54672
	s_waitcnt lgkmcnt(1)
	v_mul_f32_e32 v13, 0x3fb8aa3b, v19
	ds_read_u16 v19, v2 offset:2448
	v_exp_f32_e32 v13, v13
	s_waitcnt lgkmcnt(0)
; DEVI float bf2f(bf16_t b) { return __uint_as_float(((unsigned)b) << 16); }
; DEVI void prep_item(const Params& p, int j, int n, int h, char* smem) {
;     ...
;     for (int i = 0; i < 64; ++i) {
;       const float* amz = am + zero;
;       const float* sbz = sbeta + zero;
;       const float eg = __expf(sbz[64 + i]);
;       float acc = bf2f(*(const unsigned short*)(src + i * 272)) * sbz[i] * (isu ? 1.0f : eg);
; #pragma unroll
;       for (int j4 = 0; j4 < (i + 3) / 4; ++j4) {
;         const f32x4 a = *(const f32x4*)(amz + i * 68 + j4 * 4);
;         acc -= a[0] * x[j4 * 4 + 0];
;         acc -= a[1] * x[j4 * 4 + 1];
;         acc -= a[2] * x[j4 * 4 + 2];
;         acc -= a[3] * x[j4 * 4 + 3];
;       }
;       asm volatile("" : "+v"(zero), "+v"(acc));
;       x[i] = acc;
;     }
	v_lshlrev_b32_e32 v19, 16, v19
	v_cndmask_b32_e64 v13, v13, 1.0, vcc
	v_mul_f32_e32 v26, v18, v19
	ds_read_b128 v[18:21], v3 offset:54688
	ds_read_b128 v[22:25], v3 offset:54704
	v_mul_f32_e32 v3, v4, v14
	v_fma_f32 v3, v13, v26, -v3
	v_fma_f32 v3, -v5, v15, v3
	v_fma_f32 v3, -v6, v16, v3
	v_fma_f32 v3, -v7, v17, v3
	s_waitcnt lgkmcnt(1)
	v_fma_f32 v3, -v8, v18, v3
	v_fma_f32 v3, -v9, v19, v3
	v_fma_f32 v3, -v10, v20, v3
	v_fma_f32 v3, -v11, v21, v3
	s_waitcnt lgkmcnt(0)
	v_fma_f32 v13, -v12, v22, v3
	v_fmac_f32_e32 v13, 0x80000000, v23
	v_fmac_f32_e32 v13, 0x80000000, v24
	v_fmac_f32_e32 v13, 0x80000000, v25
	s_nop 0
	v_lshlrev_b32_e32 v3, 2, v0
	v_add_u32_e32 v14, s0, v3
	ds_read2_b32 v[18:19], v14 offset0:10 offset1:74
	v_add_u32_e32 v3, 32, v3
	s_waitcnt lgkmcnt(0)
	v_mul_f32_e32 v14, 0x3fb8aa3b, v19
	v_exp_f32_e32 v14, v14
	ds_read_u16 v19, v2 offset:2720
	v_cndmask_b32_e64 v26, v14, 1.0, vcc
	ds_read_b128 v[14:17], v3 offset:54944
	s_waitcnt lgkmcnt(1)
	v_lshlrev_b32_e32 v19, 16, v19
	v_mul_f32_e32 v27, v18, v19
	ds_read_b128 v[18:21], v3 offset:54960
	ds_read_b128 v[22:25], v3 offset:54976
	s_waitcnt lgkmcnt(2)
	v_mul_f32_e32 v3, v4, v14
	v_fma_f32 v3, v26, v27, -v3
	v_fma_f32 v3, -v5, v15, v3
	v_fma_f32 v3, -v6, v16, v3
	v_fma_f32 v3, -v7, v17, v3
	s_waitcnt lgkmcnt(1)
	v_fma_f32 v3, -v8, v18, v3
	v_fma_f32 v3, -v9, v19, v3
	v_fma_f32 v3, -v10, v20, v3
	v_fma_f32 v3, -v11, v21, v3
	s_waitcnt lgkmcnt(0)
	v_fma_f32 v3, -v12, v22, v3
	v_fma_f32 v14, -v13, v23, v3
	v_fmac_f32_e32 v14, 0x80000000, v24
	v_fmac_f32_e32 v14, 0x80000000, v25
	s_nop 0
	v_lshlrev_b32_e32 v3, 2, v0
	v_add_u32_e32 v15, s0, v3
	ds_read2_b32 v[20:21], v15 offset0:11 offset1:75
	v_add_u32_e32 v3, 32, v3
	ds_read_b128 v[16:19], v3 offset:55216
	s_waitcnt lgkmcnt(1)
	v_mul_f32_e32 v15, 0x3fb8aa3b, v21
	ds_read_u16 v21, v2 offset:2992
	v_exp_f32_e32 v15, v15
	s_waitcnt lgkmcnt(0)
	v_lshlrev_b32_e32 v21, 16, v21
	v_cndmask_b32_e64 v15, v15, 1.0, vcc
	v_mul_f32_e32 v28, v20, v21
	ds_read_b128 v[20:23], v3 offset:55232
	ds_read_b128 v[24:27], v3 offset:55248
	v_mul_f32_e32 v3, v4, v16
	v_fma_f32 v3, v15, v28, -v3
	v_fma_f32 v3, -v5, v17, v3
	v_fma_f32 v3, -v6, v18, v3
	v_fma_f32 v3, -v7, v19, v3
	s_waitcnt lgkmcnt(1)
	v_fma_f32 v3, -v8, v20, v3
	v_fma_f32 v3, -v9, v21, v3
	v_fma_f32 v3, -v10, v22, v3
	v_fma_f32 v3, -v11, v23, v3
	s_waitcnt lgkmcnt(0)
	v_fma_f32 v3, -v12, v24, v3
	v_fma_f32 v3, -v13, v25, v3
	v_fma_f32 v15, -v14, v26, v3
	v_fmac_f32_e32 v15, 0x80000000, v27
	s_nop 0
	v_lshlrev_b32_e32 v3, 2, v0
	v_add_u32_e32 v16, s0, v3
	ds_read2_b32 v[20:21], v16 offset0:12 offset1:76
	v_add_u32_e32 v3, 32, v3
	s_waitcnt lgkmcnt(0)
	v_mul_f32_e32 v16, 0x3fb8aa3b, v21
	v_exp_f32_e32 v16, v16
	ds_read_u16 v21, v2 offset:3264
	v_cndmask_b32_e64 v28, v16, 1.0, vcc
	ds_read_b128 v[16:19], v3 offset:55488
	s_waitcnt lgkmcnt(1)
	v_lshlrev_b32_e32 v21, 16, v21
	v_mul_f32_e32 v29, v20, v21
	ds_read_b128 v[20:23], v3 offset:55504
	ds_read_b128 v[24:27], v3 offset:55520
	s_waitcnt lgkmcnt(2)
	v_mul_f32_e32 v3, v4, v16
	v_fma_f32 v3, v28, v29, -v3
	v_fma_f32 v3, -v5, v17, v3
	v_fma_f32 v3, -v6, v18, v3
	v_fma_f32 v3, -v7, v19, v3
	s_waitcnt lgkmcnt(1)
	v_fma_f32 v3, -v8, v20, v3
	v_fma_f32 v3, -v9, v21, v3
	v_fma_f32 v3, -v10, v22, v3
	v_fma_f32 v3, -v11, v23, v3
	s_waitcnt lgkmcnt(0)
	v_fma_f32 v3, -v12, v24, v3
	v_fma_f32 v3, -v13, v25, v3
	v_fma_f32 v3, -v14, v26, v3
	v_fma_f32 v16, -v15, v27, v3
	ds_read_u16 v18, v2 offset:3536
	v_lshlrev_b32_e32 v3, 2, v0
	v_add_u32_e32 v17, s0, v3
	ds_read2_b32 v[22:23], v17 offset0:13 offset1:77
	v_add_u32_e32 v3, 32, v3
	s_waitcnt lgkmcnt(0)
	v_mul_f32_e32 v17, 0x3fb8aa3b, v23
	v_lshlrev_b32_e32 v23, 16, v18
	ds_read_b128 v[18:21], v3 offset:55760
	v_exp_f32_e32 v17, v17
	v_mul_f32_e32 v35, v22, v23
	ds_read_b128 v[22:25], v3 offset:55776
	ds_read_b128 v[26:29], v3 offset:55792
	ds_read_b128 v[30:33], v3 offset:55808
	v_cndmask_b32_e64 v17, v17, 1.0, vcc
	s_waitcnt lgkmcnt(3)
	v_mul_f32_e32 v3, v4, v18
	v_fma_f32 v3, v17, v35, -v3
	v_fma_f32 v3, -v5, v19, v3
	v_fma_f32 v3, -v6, v20, v3
	v_fma_f32 v3, -v7, v21, v3
	s_waitcnt lgkmcnt(2)
	v_fma_f32 v3, -v8, v22, v3
	v_fma_f32 v3, -v9, v23, v3
	v_fma_f32 v3, -v10, v24, v3
	v_fma_f32 v3, -v11, v25, v3
	s_waitcnt lgkmcnt(1)
	v_fma_f32 v3, -v12, v26, v3
	v_fma_f32 v3, -v13, v27, v3
	v_fma_f32 v3, -v14, v28, v3
	v_fma_f32 v3, -v15, v29, v3
	s_waitcnt lgkmcnt(0)
	v_fma_f32 v17, -v16, v30, v3
	v_fmac_f32_e32 v17, 0x80000000, v31
	v_fmac_f32_e32 v17, 0x80000000, v32
	v_fmac_f32_e32 v17, 0x80000000, v33
	ds_read_u16 v19, v2 offset:3808
	v_lshlrev_b32_e32 v3, 2, v0
	v_add_u32_e32 v18, s0, v3
	ds_read2_b32 v[22:23], v18 offset0:14 offset1:78
	v_add_u32_e32 v3, 32, v3
	s_waitcnt lgkmcnt(0)
	v_mul_f32_e32 v18, 0x3fb8aa3b, v23
	v_exp_f32_e32 v18, v18
	v_lshlrev_b32_e32 v23, 16, v19
	v_mul_f32_e32 v36, v22, v23
	v_cndmask_b32_e64 v35, v18, 1.0, vcc
	ds_read_b128 v[18:21], v3 offset:56032
	ds_read_b128 v[22:25], v3 offset:56048
	ds_read_b128 v[26:29], v3 offset:56064
	ds_read_b128 v[30:33], v3 offset:56080
	s_waitcnt lgkmcnt(3)
	v_mul_f32_e32 v3, v4, v18
	v_fma_f32 v3, v35, v36, -v3
	v_fma_f32 v3, -v5, v19, v3
	v_fma_f32 v3, -v6, v20, v3
	v_fma_f32 v3, -v7, v21, v3
	s_waitcnt lgkmcnt(2)
	v_fma_f32 v3, -v8, v22, v3
	v_fma_f32 v3, -v9, v23, v3
	v_fma_f32 v3, -v10, v24, v3
	v_fma_f32 v3, -v11, v25, v3
	s_waitcnt lgkmcnt(1)
	v_fma_f32 v3, -v12, v26, v3
	v_fma_f32 v3, -v13, v27, v3
	v_fma_f32 v3, -v14, v28, v3
	v_fma_f32 v3, -v15, v29, v3
	s_waitcnt lgkmcnt(0)
; DEVI float bf2f(bf16_t b) { return __uint_as_float(((unsigned)b) << 16); }
; DEVI void prep_item(const Params& p, int j, int n, int h, char* smem) {
;     ...
;     for (int i = 0; i < 64; ++i) {
;       const float* amz = am + zero;
;       const float* sbz = sbeta + zero;
;       const float eg = __expf(sbz[64 + i]);
;       float acc = bf2f(*(const unsigned short*)(src + i * 272)) * sbz[i] * (isu ? 1.0f : eg);
; #pragma unroll
;       for (int j4 = 0; j4 < (i + 3) / 4; ++j4) {
;         const f32x4 a = *(const f32x4*)(amz + i * 68 + j4 * 4);
;         acc -= a[0] * x[j4 * 4 + 0];
;         acc -= a[1] * x[j4 * 4 + 1];
;         acc -= a[2] * x[j4 * 4 + 2];
;         acc -= a[3] * x[j4 * 4 + 3];
;       }
;       asm volatile("" : "+v"(zero), "+v"(acc));
;       x[i] = acc;
;     }
	v_fma_f32 v3, -v16, v30, v3
	v_fma_f32 v18, -v17, v31, v3
	v_fmac_f32_e32 v18, 0x80000000, v32
	v_fmac_f32_e32 v18, 0x80000000, v33
	ds_read_u16 v20, v2 offset:4080
	v_lshlrev_b32_e32 v3, 2, v0
	v_add_u32_e32 v19, s0, v3
	ds_read2_b32 v[24:25], v19 offset0:15 offset1:79
	v_add_u32_e32 v3, 32, v3
	s_waitcnt lgkmcnt(0)
	v_mul_f32_e32 v19, 0x3fb8aa3b, v25
	v_lshlrev_b32_e32 v25, 16, v20
	ds_read_b128 v[20:23], v3 offset:56304
	v_exp_f32_e32 v19, v19
	v_mul_f32_e32 v32, v24, v25
	ds_read_b128 v[24:27], v3 offset:56320
	ds_read_b128 v[28:31], v3 offset:56336
	ds_read_b128 v[36:39], v3 offset:56352
	v_cndmask_b32_e64 v19, v19, 1.0, vcc
	s_waitcnt lgkmcnt(3)
	v_mul_f32_e32 v3, v4, v20
	v_fma_f32 v3, v19, v32, -v3
	v_fma_f32 v3, -v5, v21, v3
	v_fma_f32 v3, -v6, v22, v3
	v_fma_f32 v3, -v7, v23, v3
	s_waitcnt lgkmcnt(2)
	v_fma_f32 v3, -v8, v24, v3
	v_fma_f32 v3, -v9, v25, v3
	v_fma_f32 v3, -v10, v26, v3
	v_fma_f32 v3, -v11, v27, v3
	s_waitcnt lgkmcnt(1)
	v_fma_f32 v3, -v12, v28, v3
	v_fma_f32 v3, -v13, v29, v3
	v_fma_f32 v3, -v14, v30, v3
	v_fma_f32 v3, -v15, v31, v3
	s_waitcnt lgkmcnt(0)
	v_fma_f32 v3, -v16, v36, v3
	v_fma_f32 v3, -v17, v37, v3
	v_fma_f32 v19, -v18, v38, v3
	v_fmac_f32_e32 v19, 0x80000000, v39
	ds_read_u16 v21, v2 offset:4352
	v_lshlrev_b32_e32 v3, 2, v0
	v_add_u32_e32 v20, s0, v3
	ds_read2_b32 v[24:25], v20 offset0:16 offset1:80
	v_add_u32_e32 v3, 32, v3
	s_waitcnt lgkmcnt(0)
	v_mul_f32_e32 v20, 0x3fb8aa3b, v25
	v_exp_f32_e32 v20, v20
	v_lshlrev_b32_e32 v25, 16, v21
	v_mul_f32_e32 v33, v24, v25
	v_cndmask_b32_e64 v32, v20, 1.0, vcc
	ds_read_b128 v[20:23], v3 offset:56576
	ds_read_b128 v[24:27], v3 offset:56592
	ds_read_b128 v[28:31], v3 offset:56608
	ds_read_b128 v[36:39], v3 offset:56624
	s_waitcnt lgkmcnt(3)
	v_mul_f32_e32 v3, v4, v20
	v_fma_f32 v3, v32, v33, -v3
	v_fma_f32 v3, -v5, v21, v3
	v_fma_f32 v3, -v6, v22, v3
	v_fma_f32 v3, -v7, v23, v3
	s_waitcnt lgkmcnt(2)
	v_fma_f32 v3, -v8, v24, v3
	v_fma_f32 v3, -v9, v25, v3
	v_fma_f32 v3, -v10, v26, v3
	v_fma_f32 v3, -v11, v27, v3
	s_waitcnt lgkmcnt(1)
	v_fma_f32 v3, -v12, v28, v3
	v_fma_f32 v3, -v13, v29, v3
	v_fma_f32 v3, -v14, v30, v3
	v_fma_f32 v3, -v15, v31, v3
	s_waitcnt lgkmcnt(0)
	v_fma_f32 v3, -v16, v36, v3
	v_fma_f32 v3, -v17, v37, v3
	v_fma_f32 v3, -v18, v38, v3
	v_fma_f32 v20, -v19, v39, v3
	ds_read_u16 v22, v2 offset:4624
	v_lshlrev_b32_e32 v3, 2, v0
	v_add_u32_e32 v21, s0, v3
	ds_read2_b32 v[26:27], v21 offset0:17 offset1:81
	v_add_u32_e32 v3, 32, v3
	s_waitcnt lgkmcnt(0)
	v_mul_f32_e32 v21, 0x3fb8aa3b, v27
	v_lshlrev_b32_e32 v27, 16, v22
	ds_read_b128 v[22:25], v3 offset:56848
	v_exp_f32_e32 v21, v21
	v_mul_f32_e32 v35, v26, v27
	ds_read_b128 v[26:29], v3 offset:56864
	ds_read_b128 v[30:33], v3 offset:56880
	ds_read_b128 v[36:39], v3 offset:56896
	v_cndmask_b32_e64 v21, v21, 1.0, vcc
	s_waitcnt lgkmcnt(3)
	v_mul_f32_e32 v22, v4, v22
	v_fma_f32 v21, v21, v35, -v22
	v_fma_f32 v21, -v5, v23, v21
	v_fma_f32 v21, -v6, v24, v21
	v_fma_f32 v21, -v7, v25, v21
	s_waitcnt lgkmcnt(2)
	v_fma_f32 v21, -v8, v26, v21
	v_fma_f32 v21, -v9, v27, v21
	v_fma_f32 v21, -v10, v28, v21
	v_fma_f32 v21, -v11, v29, v21
	s_waitcnt lgkmcnt(1)
	v_fma_f32 v21, -v12, v30, v21
	v_fma_f32 v21, -v13, v31, v21
	v_fma_f32 v21, -v14, v32, v21
	v_fma_f32 v21, -v15, v33, v21
	ds_read_b128 v[22:25], v3 offset:56912
	s_waitcnt lgkmcnt(1)
	v_fma_f32 v3, -v16, v36, v21
	v_fma_f32 v3, -v17, v37, v3
	v_fma_f32 v3, -v18, v38, v3
	v_fma_f32 v3, -v19, v39, v3
	s_waitcnt lgkmcnt(0)
	v_fma_f32 v21, -v20, v22, v3
	v_fmac_f32_e32 v21, 0x80000000, v23
	v_fmac_f32_e32 v21, 0x80000000, v24
	v_fmac_f32_e32 v21, 0x80000000, v25
	ds_read_u16 v23, v2 offset:4896
	v_lshlrev_b32_e32 v3, 2, v0
	v_add_u32_e32 v22, s0, v3
	ds_read2_b32 v[26:27], v22 offset0:18 offset1:82
	v_add_u32_e32 v3, 32, v3
	s_waitcnt lgkmcnt(0)
	v_mul_f32_e32 v22, 0x3fb8aa3b, v27
	v_exp_f32_e32 v22, v22
	v_lshlrev_b32_e32 v27, 16, v23
	v_mul_f32_e32 v40, v26, v27
	v_cndmask_b32_e64 v35, v22, 1.0, vcc
	ds_read_b128 v[22:25], v3 offset:57120
	ds_read_b128 v[26:29], v3 offset:57136
	ds_read_b128 v[30:33], v3 offset:57152
	ds_read_b128 v[36:39], v3 offset:57168
	s_waitcnt lgkmcnt(3)
	v_mul_f32_e32 v22, v4, v22
	v_fma_f32 v22, v35, v40, -v22
	v_fma_f32 v22, -v5, v23, v22
	v_fma_f32 v22, -v6, v24, v22
	v_fma_f32 v22, -v7, v25, v22
	s_waitcnt lgkmcnt(2)
	v_fma_f32 v22, -v8, v26, v22
	v_fma_f32 v22, -v9, v27, v22
	v_fma_f32 v22, -v10, v28, v22
	v_fma_f32 v22, -v11, v29, v22
	s_waitcnt lgkmcnt(1)
	v_fma_f32 v22, -v12, v30, v22
	v_fma_f32 v22, -v13, v31, v22
	v_fma_f32 v22, -v14, v32, v22
	v_fma_f32 v26, -v15, v33, v22
	ds_read_b128 v[22:25], v3 offset:57184
	s_waitcnt lgkmcnt(1)
	v_fma_f32 v3, -v16, v36, v26
	v_fma_f32 v3, -v17, v37, v3
	v_fma_f32 v3, -v18, v38, v3
	v_fma_f32 v3, -v19, v39, v3
	s_waitcnt lgkmcnt(0)
	v_fma_f32 v3, -v20, v22, v3
	v_fma_f32 v22, -v21, v23, v3
	v_fmac_f32_e32 v22, 0x80000000, v24
	v_fmac_f32_e32 v22, 0x80000000, v25
	ds_read_u16 v24, v2 offset:5168
	v_lshlrev_b32_e32 v3, 2, v0
	v_add_u32_e32 v23, s0, v3
	ds_read2_b32 v[28:29], v23 offset0:19 offset1:83
	v_add_u32_e32 v3, 32, v3
	s_waitcnt lgkmcnt(0)
	v_mul_f32_e32 v23, 0x3fb8aa3b, v29
	v_lshlrev_b32_e32 v29, 16, v24
	ds_read_b128 v[24:27], v3 offset:57392
	v_exp_f32_e32 v23, v23
	v_mul_f32_e32 v32, v28, v29
	ds_read_b128 v[28:31], v3 offset:57408
	ds_read_b128 v[36:39], v3 offset:57424
	ds_read_b128 v[40:43], v3 offset:57440
	v_cndmask_b32_e64 v23, v23, 1.0, vcc
	s_waitcnt lgkmcnt(3)
	v_mul_f32_e32 v24, v4, v24
	v_fma_f32 v23, v23, v32, -v24
	v_fma_f32 v23, -v5, v25, v23
	v_fma_f32 v23, -v6, v26, v23
	v_fma_f32 v23, -v7, v27, v23
	s_waitcnt lgkmcnt(2)
; DEVI float bf2f(bf16_t b) { return __uint_as_float(((unsigned)b) << 16); }
; DEVI void prep_item(const Params& p, int j, int n, int h, char* smem) {
;     ...
;     for (int i = 0; i < 64; ++i) {
;       const float* amz = am + zero;
;       const float* sbz = sbeta + zero;
;       const float eg = __expf(sbz[64 + i]);
;       float acc = bf2f(*(const unsigned short*)(src + i * 272)) * sbz[i] * (isu ? 1.0f : eg);
; #pragma unroll
;       for (int j4 = 0; j4 < (i + 3) / 4; ++j4) {
;         const f32x4 a = *(const f32x4*)(amz + i * 68 + j4 * 4);
;         acc -= a[0] * x[j4 * 4 + 0];
;         acc -= a[1] * x[j4 * 4 + 1];
;         acc -= a[2] * x[j4 * 4 + 2];
;         acc -= a[3] * x[j4 * 4 + 3];
;       }
;       asm volatile("" : "+v"(zero), "+v"(acc));
;       x[i] = acc;
;     }
	v_fma_f32 v23, -v8, v28, v23
	v_fma_f32 v23, -v9, v29, v23
	v_fma_f32 v23, -v10, v30, v23
	v_fma_f32 v23, -v11, v31, v23
	s_waitcnt lgkmcnt(1)
	v_fma_f32 v23, -v12, v36, v23
	v_fma_f32 v23, -v13, v37, v23
	v_fma_f32 v23, -v14, v38, v23
	v_fma_f32 v23, -v15, v39, v23
	ds_read_b128 v[24:27], v3 offset:57456
	s_waitcnt lgkmcnt(1)
	v_fma_f32 v3, -v16, v40, v23
	v_fma_f32 v3, -v17, v41, v3
	v_fma_f32 v3, -v18, v42, v3
	v_fma_f32 v3, -v19, v43, v3
	s_waitcnt lgkmcnt(0)
	v_fma_f32 v3, -v20, v24, v3
	v_fma_f32 v3, -v21, v25, v3
	v_fma_f32 v23, -v22, v26, v3
	v_fmac_f32_e32 v23, 0x80000000, v27
	ds_read_u16 v25, v2 offset:5440
	v_lshlrev_b32_e32 v3, 2, v0
	v_add_u32_e32 v24, s0, v3
	ds_read2_b32 v[28:29], v24 offset0:20 offset1:84
	v_add_u32_e32 v3, 32, v3
	s_waitcnt lgkmcnt(0)
	v_mul_f32_e32 v24, 0x3fb8aa3b, v29
	v_exp_f32_e32 v24, v24
	v_lshlrev_b32_e32 v29, 16, v25
	v_mul_f32_e32 v33, v28, v29
	v_cndmask_b32_e64 v32, v24, 1.0, vcc
	ds_read_b128 v[24:27], v3 offset:57664
	ds_read_b128 v[28:31], v3 offset:57680
	ds_read_b128 v[36:39], v3 offset:57696
	ds_read_b128 v[40:43], v3 offset:57712
	s_waitcnt lgkmcnt(3)
	v_mul_f32_e32 v24, v4, v24
	v_fma_f32 v24, v32, v33, -v24
	v_fma_f32 v24, -v5, v25, v24
	v_fma_f32 v24, -v6, v26, v24
	v_fma_f32 v24, -v7, v27, v24
	s_waitcnt lgkmcnt(2)
	v_fma_f32 v24, -v8, v28, v24
	v_fma_f32 v24, -v9, v29, v24
	v_fma_f32 v24, -v10, v30, v24
	v_fma_f32 v24, -v11, v31, v24
	s_waitcnt lgkmcnt(1)
	v_fma_f32 v24, -v12, v36, v24
	v_fma_f32 v24, -v13, v37, v24
	v_fma_f32 v24, -v14, v38, v24
	v_fma_f32 v28, -v15, v39, v24
	ds_read_b128 v[24:27], v3 offset:57728
	s_waitcnt lgkmcnt(1)
	v_fma_f32 v3, -v16, v40, v28
	v_fma_f32 v3, -v17, v41, v3
	v_fma_f32 v3, -v18, v42, v3
	v_fma_f32 v3, -v19, v43, v3
	s_waitcnt lgkmcnt(0)
	v_fma_f32 v3, -v20, v24, v3
	v_fma_f32 v3, -v21, v25, v3
	v_fma_f32 v3, -v22, v26, v3
	v_fma_f32 v24, -v23, v27, v3
	ds_read_u16 v26, v2 offset:5712
	v_lshlrev_b32_e32 v3, 2, v0
	v_add_u32_e32 v25, s0, v3
	ds_read2_b32 v[30:31], v25 offset0:21 offset1:85
	v_add_u32_e32 v3, 32, v3
	s_waitcnt lgkmcnt(0)
	v_mul_f32_e32 v25, 0x3fb8aa3b, v31
	v_lshlrev_b32_e32 v31, 16, v26
	ds_read_b128 v[26:29], v3 offset:57936
	v_exp_f32_e32 v25, v25
	v_mul_f32_e32 v35, v30, v31
	ds_read_b128 v[30:33], v3 offset:57952
	ds_read_b128 v[36:39], v3 offset:57968
	ds_read_b128 v[40:43], v3 offset:57984
	v_cndmask_b32_e64 v25, v25, 1.0, vcc
	s_waitcnt lgkmcnt(3)
	v_mul_f32_e32 v26, v4, v26
	v_fma_f32 v25, v25, v35, -v26
	v_fma_f32 v25, -v5, v27, v25
	v_fma_f32 v25, -v6, v28, v25
	v_fma_f32 v25, -v7, v29, v25
	s_waitcnt lgkmcnt(2)
	v_fma_f32 v25, -v8, v30, v25
	v_fma_f32 v25, -v9, v31, v25
	v_fma_f32 v25, -v10, v32, v25
	v_fma_f32 v25, -v11, v33, v25
	s_waitcnt lgkmcnt(1)
	v_fma_f32 v25, -v12, v36, v25
	v_fma_f32 v25, -v13, v37, v25
	v_fma_f32 v25, -v14, v38, v25
	v_fma_f32 v25, -v15, v39, v25
	ds_read_b128 v[26:29], v3 offset:58000
	s_waitcnt lgkmcnt(1)
	v_fma_f32 v25, -v16, v40, v25
	v_fma_f32 v25, -v17, v41, v25
	v_fma_f32 v25, -v18, v42, v25
	v_fma_f32 v25, -v19, v43, v25
	ds_read_b128 v[30:33], v3 offset:58016
	s_waitcnt lgkmcnt(1)
	v_fma_f32 v3, -v20, v26, v25
	v_fma_f32 v3, -v21, v27, v3
	v_fma_f32 v3, -v22, v28, v3
	v_fma_f32 v3, -v23, v29, v3
	s_waitcnt lgkmcnt(0)
	v_fma_f32 v25, -v24, v30, v3
	v_fmac_f32_e32 v25, 0x80000000, v31
	v_fmac_f32_e32 v25, 0x80000000, v32
	v_fmac_f32_e32 v25, 0x80000000, v33
	ds_read_u16 v27, v2 offset:5984
	v_lshlrev_b32_e32 v3, 2, v0
	v_add_u32_e32 v26, s0, v3
	ds_read2_b32 v[30:31], v26 offset0:22 offset1:86
	v_add_u32_e32 v3, 32, v3
	s_waitcnt lgkmcnt(0)
	v_mul_f32_e32 v26, 0x3fb8aa3b, v31
	v_exp_f32_e32 v26, v26
	v_lshlrev_b32_e32 v31, 16, v27
	v_mul_f32_e32 v44, v30, v31
	v_cndmask_b32_e64 v35, v26, 1.0, vcc
	ds_read_b128 v[26:29], v3 offset:58208
	ds_read_b128 v[30:33], v3 offset:58224
	ds_read_b128 v[36:39], v3 offset:58240
	ds_read_b128 v[40:43], v3 offset:58256
	s_waitcnt lgkmcnt(3)
	v_mul_f32_e32 v26, v4, v26
	v_fma_f32 v26, v35, v44, -v26
	v_fma_f32 v26, -v5, v27, v26
	v_fma_f32 v26, -v6, v28, v26
	v_fma_f32 v26, -v7, v29, v26
	s_waitcnt lgkmcnt(2)
	v_fma_f32 v26, -v8, v30, v26
	v_fma_f32 v26, -v9, v31, v26
	v_fma_f32 v26, -v10, v32, v26
	v_fma_f32 v26, -v11, v33, v26
	s_waitcnt lgkmcnt(1)
	v_fma_f32 v26, -v12, v36, v26
	v_fma_f32 v26, -v13, v37, v26
	v_fma_f32 v26, -v14, v38, v26
	v_fma_f32 v26, -v15, v39, v26
	s_waitcnt lgkmcnt(0)
	v_fma_f32 v30, -v16, v40, v26
	ds_read_b128 v[26:29], v3 offset:58272
	v_fma_f32 v30, -v17, v41, v30
	v_fma_f32 v30, -v18, v42, v30
	v_fma_f32 v35, -v19, v43, v30
	ds_read_b128 v[30:33], v3 offset:58288
	s_waitcnt lgkmcnt(1)
	v_fma_f32 v3, -v20, v26, v35
	v_fma_f32 v3, -v21, v27, v3
	v_fma_f32 v3, -v22, v28, v3
	v_fma_f32 v3, -v23, v29, v3
	s_waitcnt lgkmcnt(0)
	v_fma_f32 v3, -v24, v30, v3
	v_fma_f32 v26, -v25, v31, v3
	v_fmac_f32_e32 v26, 0x80000000, v32
	v_fmac_f32_e32 v26, 0x80000000, v33
	ds_read_u16 v28, v2 offset:6256
	v_lshlrev_b32_e32 v3, 2, v0
	v_add_u32_e32 v27, s0, v3
	ds_read2_b32 v[32:33], v27 offset0:23 offset1:87
	v_add_u32_e32 v3, 32, v3
	s_waitcnt lgkmcnt(0)
	v_mul_f32_e32 v27, 0x3fb8aa3b, v33
	v_lshlrev_b32_e32 v33, 16, v28
	ds_read_b128 v[28:31], v3 offset:58480
	v_exp_f32_e32 v27, v27
	v_mul_f32_e32 v32, v32, v33
	ds_read_b128 v[36:39], v3 offset:58496
	ds_read_b128 v[40:43], v3 offset:58512
	ds_read_b128 v[44:47], v3 offset:58528
	v_cndmask_b32_e64 v27, v27, 1.0, vcc
	s_waitcnt lgkmcnt(3)
	v_mul_f32_e32 v28, v4, v28
	v_fma_f32 v27, v27, v32, -v28
	v_fma_f32 v27, -v5, v29, v27
	v_fma_f32 v27, -v6, v30, v27
	v_fma_f32 v27, -v7, v31, v27
	s_waitcnt lgkmcnt(2)
	v_fma_f32 v27, -v8, v36, v27
	v_fma_f32 v27, -v9, v37, v27
	v_fma_f32 v27, -v10, v38, v27
	v_fma_f32 v27, -v11, v39, v27
	s_waitcnt lgkmcnt(1)
; DEVI float bf2f(bf16_t b) { return __uint_as_float(((unsigned)b) << 16); }
; DEVI void prep_item(const Params& p, int j, int n, int h, char* smem) {
;     ...
;     for (int i = 0; i < 64; ++i) {
;       const float* amz = am + zero;
;       const float* sbz = sbeta + zero;
;       const float eg = __expf(sbz[64 + i]);
;       float acc = bf2f(*(const unsigned short*)(src + i * 272)) * sbz[i] * (isu ? 1.0f : eg);
; #pragma unroll
;       for (int j4 = 0; j4 < (i + 3) / 4; ++j4) {
;         const f32x4 a = *(const f32x4*)(amz + i * 68 + j4 * 4);
;         acc -= a[0] * x[j4 * 4 + 0];
;         acc -= a[1] * x[j4 * 4 + 1];
;         acc -= a[2] * x[j4 * 4 + 2];
;         acc -= a[3] * x[j4 * 4 + 3];
;       }
;       asm volatile("" : "+v"(zero), "+v"(acc));
;       x[i] = acc;
;     }
	v_fma_f32 v27, -v12, v40, v27
	v_fma_f32 v27, -v13, v41, v27
	v_fma_f32 v27, -v14, v42, v27
	v_fma_f32 v27, -v15, v43, v27
	ds_read_b128 v[28:31], v3 offset:58544
	s_waitcnt lgkmcnt(1)
	v_fma_f32 v27, -v16, v44, v27
	v_fma_f32 v27, -v17, v45, v27
	v_fma_f32 v27, -v18, v46, v27
	v_fma_f32 v27, -v19, v47, v27
	ds_read_b128 v[36:39], v3 offset:58560
	s_waitcnt lgkmcnt(1)
	v_fma_f32 v3, -v20, v28, v27
	v_fma_f32 v3, -v21, v29, v3
	v_fma_f32 v3, -v22, v30, v3
	v_fma_f32 v3, -v23, v31, v3
	s_waitcnt lgkmcnt(0)
	v_fma_f32 v3, -v24, v36, v3
	v_fma_f32 v3, -v25, v37, v3
	v_fma_f32 v27, -v26, v38, v3
	v_fmac_f32_e32 v27, 0x80000000, v39
	ds_read_u16 v29, v2 offset:6528
	v_lshlrev_b32_e32 v3, 2, v0
	v_add_u32_e32 v28, s0, v3
	ds_read2_b32 v[32:33], v28 offset0:24 offset1:88
	v_add_u32_e32 v3, 32, v3
	s_waitcnt lgkmcnt(1)
	v_lshlrev_b32_e32 v35, 16, v29
	s_waitcnt lgkmcnt(0)
	v_mul_f32_e32 v28, 0x3fb8aa3b, v33
	v_exp_f32_e32 v28, v28
	v_mul_f32_e32 v32, v32, v35
	v_cndmask_b32_e64 v33, v28, 1.0, vcc
	ds_read_b128 v[28:31], v3 offset:58752
	ds_read_b128 v[36:39], v3 offset:58768
	ds_read_b128 v[40:43], v3 offset:58784
	ds_read_b128 v[44:47], v3 offset:58800
	s_waitcnt lgkmcnt(3)
	v_mul_f32_e32 v28, v4, v28
	v_fma_f32 v28, v33, v32, -v28
	v_fma_f32 v28, -v5, v29, v28
	v_fma_f32 v28, -v6, v30, v28
	v_fma_f32 v28, -v7, v31, v28
	s_waitcnt lgkmcnt(2)
	v_fma_f32 v28, -v8, v36, v28
	v_fma_f32 v28, -v9, v37, v28
	v_fma_f32 v28, -v10, v38, v28
	v_fma_f32 v28, -v11, v39, v28
	s_waitcnt lgkmcnt(1)
	v_fma_f32 v28, -v12, v40, v28
	v_fma_f32 v28, -v13, v41, v28
	v_fma_f32 v28, -v14, v42, v28
	v_fma_f32 v28, -v15, v43, v28
	s_waitcnt lgkmcnt(0)
	v_fma_f32 v32, -v16, v44, v28
	ds_read_b128 v[28:31], v3 offset:58816
	v_fma_f32 v32, -v17, v45, v32
	v_fma_f32 v32, -v18, v46, v32
	v_fma_f32 v32, -v19, v47, v32
	ds_read_b128 v[36:39], v3 offset:58832
	s_waitcnt lgkmcnt(1)
	v_fma_f32 v3, -v20, v28, v32
	v_fma_f32 v3, -v21, v29, v3
	v_fma_f32 v3, -v22, v30, v3
	v_fma_f32 v3, -v23, v31, v3
	s_waitcnt lgkmcnt(0)
	v_fma_f32 v3, -v24, v36, v3
	v_fma_f32 v3, -v25, v37, v3
	v_fma_f32 v3, -v26, v38, v3
	v_fma_f32 v28, -v27, v39, v3
	ds_read_u16 v30, v2 offset:6800
	v_lshlrev_b32_e32 v3, 2, v0
	v_add_u32_e32 v29, s0, v3
	ds_read2_b32 v[36:37], v29 offset0:25 offset1:89
	v_add_u32_e32 v3, 32, v3
	s_waitcnt lgkmcnt(1)
	v_lshlrev_b32_e32 v35, 16, v30
	ds_read_b128 v[30:33], v3 offset:59024
	s_waitcnt lgkmcnt(1)
	v_mul_f32_e32 v29, 0x3fb8aa3b, v37
	v_exp_f32_e32 v29, v29
	v_mul_f32_e32 v35, v36, v35
	s_waitcnt lgkmcnt(0)
	v_mul_f32_e32 v30, v4, v30
	ds_read_b128 v[36:39], v3 offset:59040
	ds_read_b128 v[40:43], v3 offset:59056
	ds_read_b128 v[44:47], v3 offset:59072
	v_cndmask_b32_e64 v29, v29, 1.0, vcc
	v_fma_f32 v29, v29, v35, -v30
	v_fma_f32 v29, -v5, v31, v29
	v_fma_f32 v29, -v6, v32, v29
	v_fma_f32 v29, -v7, v33, v29
	s_waitcnt lgkmcnt(2)
	v_fma_f32 v29, -v8, v36, v29
	v_fma_f32 v29, -v9, v37, v29
	v_fma_f32 v29, -v10, v38, v29
	v_fma_f32 v29, -v11, v39, v29
	s_waitcnt lgkmcnt(1)
	v_fma_f32 v29, -v12, v40, v29
	v_fma_f32 v29, -v13, v41, v29
	v_fma_f32 v29, -v14, v42, v29
	v_fma_f32 v29, -v15, v43, v29
	ds_read_b128 v[30:33], v3 offset:59088
	s_waitcnt lgkmcnt(1)
	v_fma_f32 v29, -v16, v44, v29
	v_fma_f32 v29, -v17, v45, v29
	v_fma_f32 v29, -v18, v46, v29
	v_fma_f32 v29, -v19, v47, v29
	ds_read_b128 v[36:39], v3 offset:59104
	s_waitcnt lgkmcnt(1)
	v_fma_f32 v29, -v20, v30, v29
	v_fma_f32 v29, -v21, v31, v29
	v_fma_f32 v29, -v22, v32, v29
	v_fma_f32 v29, -v23, v33, v29
	ds_read_b128 v[30:33], v3 offset:59120
	s_waitcnt lgkmcnt(1)
	v_fma_f32 v3, -v24, v36, v29
	v_fma_f32 v3, -v25, v37, v3
	v_fma_f32 v3, -v26, v38, v3
	v_fma_f32 v3, -v27, v39, v3
	s_waitcnt lgkmcnt(0)
	v_fma_f32 v29, -v28, v30, v3
	v_fmac_f32_e32 v29, 0x80000000, v31
	v_fmac_f32_e32 v29, 0x80000000, v32
	v_fmac_f32_e32 v29, 0x80000000, v33
	ds_read_u16 v31, v2 offset:7072
	v_lshlrev_b32_e32 v3, 2, v0
	v_add_u32_e32 v30, s0, v3
	ds_read2_b32 v[36:37], v30 offset0:26 offset1:90
	v_add_u32_e32 v3, 32, v3
	s_waitcnt lgkmcnt(0)
	v_mul_f32_e32 v30, 0x3fb8aa3b, v37
	v_exp_f32_e32 v30, v30
	v_lshlrev_b32_e32 v37, 16, v31
	v_mul_f32_e32 v48, v36, v37
	v_cndmask_b32_e64 v35, v30, 1.0, vcc
	ds_read_b128 v[30:33], v3 offset:59296
	ds_read_b128 v[36:39], v3 offset:59312
	ds_read_b128 v[40:43], v3 offset:59328
	ds_read_b128 v[44:47], v3 offset:59344
	s_waitcnt lgkmcnt(3)
	v_mul_f32_e32 v30, v4, v30
	v_fma_f32 v30, v35, v48, -v30
	v_fma_f32 v30, -v5, v31, v30
	v_fma_f32 v30, -v6, v32, v30
	v_fma_f32 v30, -v7, v33, v30
	s_waitcnt lgkmcnt(2)
	v_fma_f32 v30, -v8, v36, v30
	v_fma_f32 v30, -v9, v37, v30
	v_fma_f32 v30, -v10, v38, v30
	v_fma_f32 v30, -v11, v39, v30
	s_waitcnt lgkmcnt(1)
	v_fma_f32 v30, -v12, v40, v30
	v_fma_f32 v30, -v13, v41, v30
	v_fma_f32 v30, -v14, v42, v30
	v_fma_f32 v30, -v15, v43, v30
	s_waitcnt lgkmcnt(0)
	v_fma_f32 v35, -v16, v44, v30
	ds_read_b128 v[30:33], v3 offset:59360
	v_fma_f32 v35, -v17, v45, v35
	v_fma_f32 v35, -v18, v46, v35
	v_fma_f32 v35, -v19, v47, v35
	ds_read_b128 v[36:39], v3 offset:59376
	s_waitcnt lgkmcnt(1)
	v_fma_f32 v30, -v20, v30, v35
	v_fma_f32 v30, -v21, v31, v30
	v_fma_f32 v30, -v22, v32, v30
	v_fma_f32 v35, -v23, v33, v30
	ds_read_b128 v[30:33], v3 offset:59392
	s_waitcnt lgkmcnt(1)
	v_fma_f32 v3, -v24, v36, v35
	v_fma_f32 v3, -v25, v37, v3
	v_fma_f32 v3, -v26, v38, v3
	v_fma_f32 v3, -v27, v39, v3
	s_waitcnt lgkmcnt(0)
	v_fma_f32 v3, -v28, v30, v3
	v_fma_f32 v30, -v29, v31, v3
	v_fmac_f32_e32 v30, 0x80000000, v32
	v_fmac_f32_e32 v30, 0x80000000, v33
	s_nop 0
	v_lshlrev_b32_e32 v3, 2, v0
	v_add_u32_e32 v31, s0, v3
	ds_read2_b32 v[32:33], v31 offset0:27 offset1:91
	v_add_u32_e32 v3, 32, v3
	ds_read_b128 v[36:39], v3 offset:59568
	s_waitcnt lgkmcnt(1)
; DEVI float bf2f(bf16_t b) { return __uint_as_float(((unsigned)b) << 16); }
; DEVI void prep_item(const Params& p, int j, int n, int h, char* smem) {
;     ...
;     for (int i = 0; i < 64; ++i) {
;       const float* amz = am + zero;
;       const float* sbz = sbeta + zero;
;       const float eg = __expf(sbz[64 + i]);
;       float acc = bf2f(*(const unsigned short*)(src + i * 272)) * sbz[i] * (isu ? 1.0f : eg);
; #pragma unroll
;       for (int j4 = 0; j4 < (i + 3) / 4; ++j4) {
;         const f32x4 a = *(const f32x4*)(amz + i * 68 + j4 * 4);
;         acc -= a[0] * x[j4 * 4 + 0];
;         acc -= a[1] * x[j4 * 4 + 1];
;         acc -= a[2] * x[j4 * 4 + 2];
;         acc -= a[3] * x[j4 * 4 + 3];
;       }
;       asm volatile("" : "+v"(zero), "+v"(acc));
;       x[i] = acc;
;     }
	v_mul_f32_e32 v31, 0x3fb8aa3b, v33
	ds_read_u16 v33, v2 offset:7344
	v_exp_f32_e32 v31, v31
	ds_read_b128 v[40:43], v3 offset:59584
	ds_read_b128 v[44:47], v3 offset:59600
	ds_read_b128 v[48:51], v3 offset:59616
	s_waitcnt lgkmcnt(3)
	v_lshlrev_b32_e32 v33, 16, v33
	v_cndmask_b32_e64 v31, v31, 1.0, vcc
	v_mul_f32_e32 v32, v32, v33
	v_mul_f32_e32 v33, v4, v36
	v_fma_f32 v31, v31, v32, -v33
	v_fma_f32 v31, -v5, v37, v31
	v_fma_f32 v31, -v6, v38, v31
	v_fma_f32 v31, -v7, v39, v31
	s_waitcnt lgkmcnt(2)
	v_fma_f32 v31, -v8, v40, v31
	v_fma_f32 v31, -v9, v41, v31
	v_fma_f32 v31, -v10, v42, v31
	v_fma_f32 v31, -v11, v43, v31
	s_waitcnt lgkmcnt(1)
	v_fma_f32 v31, -v12, v44, v31
	v_fma_f32 v31, -v13, v45, v31
	v_fma_f32 v31, -v14, v46, v31
	v_fma_f32 v31, -v15, v47, v31
	ds_read_b128 v[36:39], v3 offset:59632
	s_waitcnt lgkmcnt(1)
	v_fma_f32 v31, -v16, v48, v31
	v_fma_f32 v31, -v17, v49, v31
	v_fma_f32 v31, -v18, v50, v31
	v_fma_f32 v31, -v19, v51, v31
	ds_read_b128 v[40:43], v3 offset:59648
	s_waitcnt lgkmcnt(1)
	v_fma_f32 v31, -v20, v36, v31
	v_fma_f32 v31, -v21, v37, v31
	v_fma_f32 v31, -v22, v38, v31
	v_fma_f32 v31, -v23, v39, v31
	ds_read_b128 v[36:39], v3 offset:59664
	s_waitcnt lgkmcnt(1)
	v_fma_f32 v3, -v24, v40, v31
	v_fma_f32 v3, -v25, v41, v3
	v_fma_f32 v3, -v26, v42, v3
	v_fma_f32 v3, -v27, v43, v3
	s_waitcnt lgkmcnt(0)
	v_fma_f32 v3, -v28, v36, v3
	v_fma_f32 v3, -v29, v37, v3
	v_fma_f32 v31, -v30, v38, v3
	v_fmac_f32_e32 v31, 0x80000000, v39
	ds_read_u16 v35, v2 offset:7616
	v_lshlrev_b32_e32 v3, 2, v0
	v_add_u32_e32 v32, s0, v3
	ds_read2_b32 v[32:33], v32 offset0:28 offset1:92
	v_add_u32_e32 v3, 32, v3
	ds_read_b128 v[36:39], v3 offset:59840
	s_waitcnt lgkmcnt(2)
	v_lshlrev_b32_e32 v35, 16, v35
	ds_read_b128 v[40:43], v3 offset:59856
	ds_read_b128 v[44:47], v3 offset:59872
	ds_read_b128 v[48:51], v3 offset:59888
	s_waitcnt lgkmcnt(4)
	v_mul_f32_e32 v33, 0x3fb8aa3b, v33
	v_exp_f32_e32 v33, v33
	v_mul_f32_e32 v32, v32, v35
	s_waitcnt lgkmcnt(3)
	v_mul_f32_e32 v35, v4, v36
	v_cndmask_b32_e64 v33, v33, 1.0, vcc
	v_fma_f32 v32, v33, v32, -v35
	v_fma_f32 v32, -v5, v37, v32
	v_fma_f32 v32, -v6, v38, v32
	v_fma_f32 v32, -v7, v39, v32
	s_waitcnt lgkmcnt(2)
	v_fma_f32 v32, -v8, v40, v32
	v_fma_f32 v32, -v9, v41, v32
	v_fma_f32 v32, -v10, v42, v32
	v_fma_f32 v32, -v11, v43, v32
	s_waitcnt lgkmcnt(1)
	v_fma_f32 v32, -v12, v44, v32
	v_fma_f32 v32, -v13, v45, v32
	v_fma_f32 v32, -v14, v46, v32
	v_fma_f32 v32, -v15, v47, v32
	ds_read_b128 v[36:39], v3 offset:59904
	s_waitcnt lgkmcnt(1)
	v_fma_f32 v32, -v16, v48, v32
	v_fma_f32 v32, -v17, v49, v32
	v_fma_f32 v32, -v18, v50, v32
	v_fma_f32 v32, -v19, v51, v32
	ds_read_b128 v[40:43], v3 offset:59920
	s_waitcnt lgkmcnt(1)
	v_fma_f32 v32, -v20, v36, v32
	v_fma_f32 v32, -v21, v37, v32
	v_fma_f32 v32, -v22, v38, v32
	v_fma_f32 v32, -v23, v39, v32
	ds_read_b128 v[36:39], v3 offset:59936
	s_waitcnt lgkmcnt(1)
	v_fma_f32 v3, -v24, v40, v32
	v_fma_f32 v3, -v25, v41, v3
	v_fma_f32 v3, -v26, v42, v3
	v_fma_f32 v3, -v27, v43, v3
	s_waitcnt lgkmcnt(0)
	v_fma_f32 v3, -v28, v36, v3
	v_fma_f32 v3, -v29, v37, v3
	v_fma_f32 v3, -v30, v38, v3
	v_fma_f32 v32, -v31, v39, v3
	ds_read_u16 v35, v2 offset:7888
	v_lshlrev_b32_e32 v3, 2, v0
	v_add_u32_e32 v33, s0, v3
	ds_read2_b32 v[40:41], v33 offset0:29 offset1:93
	v_add_u32_e32 v3, 32, v3
	ds_read_b128 v[36:39], v3 offset:60112
	s_waitcnt lgkmcnt(2)
	v_lshlrev_b32_e32 v35, 16, v35
	s_waitcnt lgkmcnt(1)
	v_mul_f32_e32 v33, 0x3fb8aa3b, v41
	v_exp_f32_e32 v33, v33
	v_mul_f32_e32 v35, v40, v35
	s_waitcnt lgkmcnt(0)
	v_mul_f32_e32 v36, v4, v36
	ds_read_b128 v[40:43], v3 offset:60128
	ds_read_b128 v[44:47], v3 offset:60144
	ds_read_b128 v[48:51], v3 offset:60160
	v_cndmask_b32_e64 v33, v33, 1.0, vcc
	v_fma_f32 v33, v33, v35, -v36
	v_fma_f32 v33, -v5, v37, v33
	v_fma_f32 v33, -v6, v38, v33
	v_fma_f32 v33, -v7, v39, v33
	s_waitcnt lgkmcnt(2)
	v_fma_f32 v33, -v8, v40, v33
	v_fma_f32 v33, -v9, v41, v33
	v_fma_f32 v33, -v10, v42, v33
	v_fma_f32 v33, -v11, v43, v33
	s_waitcnt lgkmcnt(1)
	v_fma_f32 v33, -v12, v44, v33
	v_fma_f32 v33, -v13, v45, v33
	v_fma_f32 v33, -v14, v46, v33
	v_fma_f32 v33, -v15, v47, v33
	ds_read_b128 v[36:39], v3 offset:60176
	s_waitcnt lgkmcnt(1)
	v_fma_f32 v33, -v16, v48, v33
	v_fma_f32 v33, -v17, v49, v33
	v_fma_f32 v33, -v18, v50, v33
	v_fma_f32 v33, -v19, v51, v33
	ds_read_b128 v[40:43], v3 offset:60192
	s_waitcnt lgkmcnt(1)
	v_fma_f32 v33, -v20, v36, v33
	v_fma_f32 v33, -v21, v37, v33
	v_fma_f32 v33, -v22, v38, v33
	v_fma_f32 v33, -v23, v39, v33
	ds_read_b128 v[36:39], v3 offset:60208
	s_waitcnt lgkmcnt(1)
	v_fma_f32 v33, -v24, v40, v33
	v_fma_f32 v33, -v25, v41, v33
	v_fma_f32 v33, -v26, v42, v33
	v_fma_f32 v33, -v27, v43, v33
	ds_read_b128 v[40:43], v3 offset:60224
	s_waitcnt lgkmcnt(1)
	v_fma_f32 v3, -v28, v36, v33
	v_fma_f32 v3, -v29, v37, v3
	v_fma_f32 v3, -v30, v38, v3
	v_fma_f32 v3, -v31, v39, v3
	s_waitcnt lgkmcnt(0)
	v_fma_f32 v33, -v32, v40, v3
	v_fmac_f32_e32 v33, 0x80000000, v41
	v_fmac_f32_e32 v33, 0x80000000, v42
	v_fmac_f32_e32 v33, 0x80000000, v43
	ds_read_u16 v36, v2 offset:8160
	v_lshlrev_b32_e32 v3, 2, v0
	v_add_u32_e32 v35, s0, v3
	ds_read2_b32 v[40:41], v35 offset0:30 offset1:94
	v_add_u32_e32 v3, 32, v3
	s_waitcnt lgkmcnt(0)
	v_mul_f32_e32 v35, 0x3fb8aa3b, v41
	v_lshlrev_b32_e32 v41, 16, v36
	ds_read_b128 v[36:39], v3 offset:60384
	v_exp_f32_e32 v35, v35
	v_mul_f32_e32 v52, v40, v41
	ds_read_b128 v[40:43], v3 offset:60400
	ds_read_b128 v[44:47], v3 offset:60416
	ds_read_b128 v[48:51], v3 offset:60432
	v_cndmask_b32_e64 v35, v35, 1.0, vcc
	s_waitcnt lgkmcnt(3)
; DEVI float bf2f(bf16_t b) { return __uint_as_float(((unsigned)b) << 16); }
; DEVI void prep_item(const Params& p, int j, int n, int h, char* smem) {
;     ...
;     for (int i = 0; i < 64; ++i) {
;       const float* amz = am + zero;
;       const float* sbz = sbeta + zero;
;       const float eg = __expf(sbz[64 + i]);
;       float acc = bf2f(*(const unsigned short*)(src + i * 272)) * sbz[i] * (isu ? 1.0f : eg);
; #pragma unroll
;       for (int j4 = 0; j4 < (i + 3) / 4; ++j4) {
;         const f32x4 a = *(const f32x4*)(amz + i * 68 + j4 * 4);
;         acc -= a[0] * x[j4 * 4 + 0];
;         acc -= a[1] * x[j4 * 4 + 1];
;         acc -= a[2] * x[j4 * 4 + 2];
;         acc -= a[3] * x[j4 * 4 + 3];
;       }
;       asm volatile("" : "+v"(zero), "+v"(acc));
;       x[i] = acc;
;     }
	v_mul_f32_e32 v36, v4, v36
	v_fma_f32 v35, v35, v52, -v36
	v_fma_f32 v35, -v5, v37, v35
	v_fma_f32 v35, -v6, v38, v35
	v_fma_f32 v35, -v7, v39, v35
	s_waitcnt lgkmcnt(2)
	v_fma_f32 v35, -v8, v40, v35
	v_fma_f32 v35, -v9, v41, v35
	v_fma_f32 v35, -v10, v42, v35
	v_fma_f32 v35, -v11, v43, v35
	s_waitcnt lgkmcnt(1)
	v_fma_f32 v35, -v12, v44, v35
	v_fma_f32 v35, -v13, v45, v35
	v_fma_f32 v35, -v14, v46, v35
	v_fma_f32 v35, -v15, v47, v35
	ds_read_b128 v[36:39], v3 offset:60448
	s_waitcnt lgkmcnt(1)
	v_fma_f32 v35, -v16, v48, v35
	v_fma_f32 v35, -v17, v49, v35
	v_fma_f32 v35, -v18, v50, v35
	v_fma_f32 v35, -v19, v51, v35
	ds_read_b128 v[40:43], v3 offset:60464
	s_waitcnt lgkmcnt(1)
	v_fma_f32 v35, -v20, v36, v35
	v_fma_f32 v35, -v21, v37, v35
	v_fma_f32 v35, -v22, v38, v35
	v_fma_f32 v35, -v23, v39, v35
	ds_read_b128 v[36:39], v3 offset:60480
	s_waitcnt lgkmcnt(1)
	v_fma_f32 v35, -v24, v40, v35
	v_fma_f32 v35, -v25, v41, v35
	v_fma_f32 v35, -v26, v42, v35
	v_fma_f32 v35, -v27, v43, v35
	ds_read_b128 v[40:43], v3 offset:60496
	s_waitcnt lgkmcnt(1)
	v_fma_f32 v3, -v28, v36, v35
	v_fma_f32 v3, -v29, v37, v3
	v_fma_f32 v3, -v30, v38, v3
	v_fma_f32 v3, -v31, v39, v3
	s_waitcnt lgkmcnt(0)
	v_fma_f32 v3, -v32, v40, v3
	v_fma_f32 v35, -v33, v41, v3
	v_fmac_f32_e32 v35, 0x80000000, v42
	v_fmac_f32_e32 v35, 0x80000000, v43
	ds_read_u16 v37, v2 offset:8432
	v_lshlrev_b32_e32 v3, 2, v0
	v_add_u32_e32 v36, s0, v3
	ds_read2_b32 v[40:41], v36 offset0:31 offset1:95
	v_add_u32_e32 v3, 32, v3
	s_waitcnt lgkmcnt(0)
	v_mul_f32_e32 v36, 0x3fb8aa3b, v41
	v_exp_f32_e32 v36, v36
	v_lshlrev_b32_e32 v41, 16, v37
	v_mul_f32_e32 v53, v40, v41
	v_cndmask_b32_e64 v52, v36, 1.0, vcc
	ds_read_b128 v[36:39], v3 offset:60656
	ds_read_b128 v[40:43], v3 offset:60672
	ds_read_b128 v[44:47], v3 offset:60688
	ds_read_b128 v[48:51], v3 offset:60704
	s_waitcnt lgkmcnt(3)
	v_mul_f32_e32 v36, v4, v36
	v_fma_f32 v36, v52, v53, -v36
	v_fma_f32 v36, -v5, v37, v36
	v_fma_f32 v36, -v6, v38, v36
	v_fma_f32 v36, -v7, v39, v36
	s_waitcnt lgkmcnt(2)
	v_fma_f32 v36, -v8, v40, v36
	v_fma_f32 v36, -v9, v41, v36
	v_fma_f32 v36, -v10, v42, v36
	v_fma_f32 v36, -v11, v43, v36
	s_waitcnt lgkmcnt(1)
	v_fma_f32 v36, -v12, v44, v36
	v_fma_f32 v36, -v13, v45, v36
	v_fma_f32 v36, -v14, v46, v36
	v_fma_f32 v36, -v15, v47, v36
	s_waitcnt lgkmcnt(0)
	v_fma_f32 v40, -v16, v48, v36
	ds_read_b128 v[36:39], v3 offset:60720
	v_fma_f32 v40, -v17, v49, v40
	v_fma_f32 v40, -v18, v50, v40
	v_fma_f32 v44, -v19, v51, v40
	ds_read_b128 v[40:43], v3 offset:60736
	s_waitcnt lgkmcnt(1)
	v_fma_f32 v36, -v20, v36, v44
	v_fma_f32 v36, -v21, v37, v36
	v_fma_f32 v36, -v22, v38, v36
	v_fma_f32 v36, -v23, v39, v36
	s_waitcnt lgkmcnt(0)
	v_fma_f32 v40, -v24, v40, v36
	ds_read_b128 v[36:39], v3 offset:60752
	v_fma_f32 v40, -v25, v41, v40
	v_fma_f32 v40, -v26, v42, v40
	v_fma_f32 v44, -v27, v43, v40
	ds_read_b128 v[40:43], v3 offset:60768
	s_waitcnt lgkmcnt(1)
	v_fma_f32 v3, -v28, v36, v44
	v_fma_f32 v3, -v29, v37, v3
	v_fma_f32 v3, -v30, v38, v3
	v_fma_f32 v3, -v31, v39, v3
	s_waitcnt lgkmcnt(0)
	v_fma_f32 v3, -v32, v40, v3
	v_fma_f32 v3, -v33, v41, v3
	v_fma_f32 v36, -v35, v42, v3
	v_fmac_f32_e32 v36, 0x80000000, v43
	ds_read_u16 v38, v2 offset:8704
	v_lshlrev_b32_e32 v3, 2, v0
	v_add_u32_e32 v37, s0, v3
	ds_read2_b32 v[42:43], v37 offset0:32 offset1:96
	v_add_u32_e32 v3, 32, v3
	s_waitcnt lgkmcnt(0)
	v_mul_f32_e32 v37, 0x3fb8aa3b, v43
	v_lshlrev_b32_e32 v43, 16, v38
	ds_read_b128 v[38:41], v3 offset:60928
	v_exp_f32_e32 v37, v37
	v_mul_f32_e32 v54, v42, v43
	ds_read_b128 v[42:45], v3 offset:60944
	ds_read_b128 v[46:49], v3 offset:60960
	ds_read_b128 v[50:53], v3 offset:60976
	v_cndmask_b32_e64 v37, v37, 1.0, vcc
	s_waitcnt lgkmcnt(3)
	v_mul_f32_e32 v38, v4, v38
	v_fma_f32 v37, v37, v54, -v38
	v_fma_f32 v37, -v5, v39, v37
	v_fma_f32 v37, -v6, v40, v37
	v_fma_f32 v37, -v7, v41, v37
	s_waitcnt lgkmcnt(2)
	v_fma_f32 v37, -v8, v42, v37
	v_fma_f32 v37, -v9, v43, v37
	v_fma_f32 v37, -v10, v44, v37
	v_fma_f32 v37, -v11, v45, v37
	s_waitcnt lgkmcnt(1)
	v_fma_f32 v37, -v12, v46, v37
	v_fma_f32 v37, -v13, v47, v37
	v_fma_f32 v37, -v14, v48, v37
	v_fma_f32 v37, -v15, v49, v37
	ds_read_b128 v[38:41], v3 offset:60992
	s_waitcnt lgkmcnt(1)
	v_fma_f32 v37, -v16, v50, v37
	v_fma_f32 v37, -v17, v51, v37
	v_fma_f32 v37, -v18, v52, v37
	v_fma_f32 v37, -v19, v53, v37
	ds_read_b128 v[42:45], v3 offset:61008
	s_waitcnt lgkmcnt(1)
	v_fma_f32 v37, -v20, v38, v37
	v_fma_f32 v37, -v21, v39, v37
	v_fma_f32 v37, -v22, v40, v37
	v_fma_f32 v37, -v23, v41, v37
	ds_read_b128 v[38:41], v3 offset:61024
	s_waitcnt lgkmcnt(1)
	v_fma_f32 v37, -v24, v42, v37
	v_fma_f32 v37, -v25, v43, v37
	v_fma_f32 v37, -v26, v44, v37
	v_fma_f32 v37, -v27, v45, v37
	ds_read_b128 v[42:45], v3 offset:61040
	s_waitcnt lgkmcnt(1)
	v_fma_f32 v3, -v28, v38, v37
	v_fma_f32 v3, -v29, v39, v3
	v_fma_f32 v3, -v30, v40, v3
	v_fma_f32 v3, -v31, v41, v3
	s_waitcnt lgkmcnt(0)
	v_fma_f32 v3, -v32, v42, v3
	v_fma_f32 v3, -v33, v43, v3
	v_fma_f32 v3, -v35, v44, v3
	v_fma_f32 v37, -v36, v45, v3
	ds_read_u16 v39, v2 offset:8976
	v_lshlrev_b32_e32 v3, 2, v0
	v_add_u32_e32 v38, s0, v3
	ds_read2_b32 v[42:43], v38 offset0:33 offset1:97
	v_add_u32_e32 v3, 32, v3
	s_waitcnt lgkmcnt(0)
	v_mul_f32_e32 v38, 0x3fb8aa3b, v43
	v_exp_f32_e32 v38, v38
	v_lshlrev_b32_e32 v43, 16, v39
	v_mul_f32_e32 v55, v42, v43
	v_cndmask_b32_e64 v54, v38, 1.0, vcc
	ds_read_b128 v[38:41], v3 offset:61200
	ds_read_b128 v[42:45], v3 offset:61216
	ds_read_b128 v[46:49], v3 offset:61232
	ds_read_b128 v[50:53], v3 offset:61248
	s_waitcnt lgkmcnt(3)
	v_mul_f32_e32 v38, v4, v38
	v_fma_f32 v38, v54, v55, -v38
	v_fma_f32 v38, -v5, v39, v38
	v_fma_f32 v38, -v6, v40, v38
	v_fma_f32 v38, -v7, v41, v38
	s_waitcnt lgkmcnt(2)
; DEVI float bf2f(bf16_t b) { return __uint_as_float(((unsigned)b) << 16); }
; DEVI void prep_item(const Params& p, int j, int n, int h, char* smem) {
;     ...
;     for (int i = 0; i < 64; ++i) {
;       const float* amz = am + zero;
;       const float* sbz = sbeta + zero;
;       const float eg = __expf(sbz[64 + i]);
;       float acc = bf2f(*(const unsigned short*)(src + i * 272)) * sbz[i] * (isu ? 1.0f : eg);
; #pragma unroll
;       for (int j4 = 0; j4 < (i + 3) / 4; ++j4) {
;         const f32x4 a = *(const f32x4*)(amz + i * 68 + j4 * 4);
;         acc -= a[0] * x[j4 * 4 + 0];
;         acc -= a[1] * x[j4 * 4 + 1];
;         acc -= a[2] * x[j4 * 4 + 2];
;         acc -= a[3] * x[j4 * 4 + 3];
;       }
;       asm volatile("" : "+v"(zero), "+v"(acc));
;       x[i] = acc;
;     }
	v_fma_f32 v38, -v8, v42, v38
	v_fma_f32 v38, -v9, v43, v38
	v_fma_f32 v38, -v10, v44, v38
	v_fma_f32 v38, -v11, v45, v38
	s_waitcnt lgkmcnt(1)
	v_fma_f32 v38, -v12, v46, v38
	v_fma_f32 v38, -v13, v47, v38
	v_fma_f32 v38, -v14, v48, v38
	v_fma_f32 v38, -v15, v49, v38
	s_waitcnt lgkmcnt(0)
	v_fma_f32 v42, -v16, v50, v38
	ds_read_b128 v[38:41], v3 offset:61264
	v_fma_f32 v42, -v17, v51, v42
	v_fma_f32 v42, -v18, v52, v42
	v_fma_f32 v46, -v19, v53, v42
	ds_read_b128 v[42:45], v3 offset:61280
	s_waitcnt lgkmcnt(1)
	v_fma_f32 v38, -v20, v38, v46
	v_fma_f32 v38, -v21, v39, v38
	v_fma_f32 v38, -v22, v40, v38
	v_fma_f32 v38, -v23, v41, v38
	s_waitcnt lgkmcnt(0)
	v_fma_f32 v42, -v24, v42, v38
	ds_read_b128 v[38:41], v3 offset:61296
	v_fma_f32 v42, -v25, v43, v42
	v_fma_f32 v42, -v26, v44, v42
	v_fma_f32 v46, -v27, v45, v42
	ds_read_b128 v[42:45], v3 offset:61312
	s_waitcnt lgkmcnt(1)
	v_fma_f32 v38, -v28, v38, v46
	v_fma_f32 v38, -v29, v39, v38
	v_fma_f32 v38, -v30, v40, v38
	v_fma_f32 v46, -v31, v41, v38
	ds_read_b128 v[38:41], v3 offset:61328
	s_waitcnt lgkmcnt(1)
	v_fma_f32 v3, -v32, v42, v46
	v_fma_f32 v3, -v33, v43, v3
	v_fma_f32 v3, -v35, v44, v3
	v_fma_f32 v3, -v36, v45, v3
	s_waitcnt lgkmcnt(0)
	v_fma_f32 v38, -v37, v38, v3
	v_fmac_f32_e32 v38, 0x80000000, v39
	v_fmac_f32_e32 v38, 0x80000000, v40
	v_fmac_f32_e32 v38, 0x80000000, v41
	ds_read_u16 v40, v2 offset:9248
	v_lshlrev_b32_e32 v3, 2, v0
	v_add_u32_e32 v39, s0, v3
	ds_read2_b32 v[44:45], v39 offset0:34 offset1:98
	v_add_u32_e32 v3, 32, v3
	s_waitcnt lgkmcnt(0)
	v_mul_f32_e32 v39, 0x3fb8aa3b, v45
	v_lshlrev_b32_e32 v45, 16, v40
	ds_read_b128 v[40:43], v3 offset:61472
	v_exp_f32_e32 v39, v39
	v_mul_f32_e32 v56, v44, v45
	ds_read_b128 v[44:47], v3 offset:61488
	ds_read_b128 v[48:51], v3 offset:61504
	ds_read_b128 v[52:55], v3 offset:61520
	v_cndmask_b32_e64 v39, v39, 1.0, vcc
	s_waitcnt lgkmcnt(3)
	v_mul_f32_e32 v40, v4, v40
	v_fma_f32 v39, v39, v56, -v40
	v_fma_f32 v39, -v5, v41, v39
	v_fma_f32 v39, -v6, v42, v39
	v_fma_f32 v39, -v7, v43, v39
	s_waitcnt lgkmcnt(2)
	v_fma_f32 v39, -v8, v44, v39
	v_fma_f32 v39, -v9, v45, v39
	v_fma_f32 v39, -v10, v46, v39
	v_fma_f32 v39, -v11, v47, v39
	s_waitcnt lgkmcnt(1)
	v_fma_f32 v39, -v12, v48, v39
	v_fma_f32 v39, -v13, v49, v39
	v_fma_f32 v39, -v14, v50, v39
	v_fma_f32 v39, -v15, v51, v39
	ds_read_b128 v[40:43], v3 offset:61536
	s_waitcnt lgkmcnt(1)
	v_fma_f32 v39, -v16, v52, v39
	v_fma_f32 v39, -v17, v53, v39
	v_fma_f32 v39, -v18, v54, v39
	v_fma_f32 v39, -v19, v55, v39
	ds_read_b128 v[44:47], v3 offset:61552
	s_waitcnt lgkmcnt(1)
	v_fma_f32 v39, -v20, v40, v39
	v_fma_f32 v39, -v21, v41, v39
	v_fma_f32 v39, -v22, v42, v39
	v_fma_f32 v39, -v23, v43, v39
	ds_read_b128 v[40:43], v3 offset:61568
	s_waitcnt lgkmcnt(1)
	v_fma_f32 v39, -v24, v44, v39
	v_fma_f32 v39, -v25, v45, v39
	v_fma_f32 v39, -v26, v46, v39
	v_fma_f32 v39, -v27, v47, v39
	ds_read_b128 v[44:47], v3 offset:61584
	s_waitcnt lgkmcnt(1)
	v_fma_f32 v39, -v28, v40, v39
	v_fma_f32 v39, -v29, v41, v39
	v_fma_f32 v39, -v30, v42, v39
	v_fma_f32 v39, -v31, v43, v39
	ds_read_b128 v[40:43], v3 offset:61600
	s_waitcnt lgkmcnt(1)
	v_fma_f32 v3, -v32, v44, v39
	v_fma_f32 v3, -v33, v45, v3
	v_fma_f32 v3, -v35, v46, v3
	v_fma_f32 v3, -v36, v47, v3
	s_waitcnt lgkmcnt(0)
	v_fma_f32 v3, -v37, v40, v3
	v_fma_f32 v39, -v38, v41, v3
	v_fmac_f32_e32 v39, 0x80000000, v42
	v_fmac_f32_e32 v39, 0x80000000, v43
	ds_read_u16 v41, v2 offset:9520
	v_lshlrev_b32_e32 v3, 2, v0
	v_add_u32_e32 v40, s0, v3
	ds_read2_b32 v[44:45], v40 offset0:35 offset1:99
	v_add_u32_e32 v3, 32, v3
	s_waitcnt lgkmcnt(0)
	v_mul_f32_e32 v40, 0x3fb8aa3b, v45
	v_exp_f32_e32 v40, v40
	v_lshlrev_b32_e32 v45, 16, v41
	v_mul_f32_e32 v57, v44, v45
	v_cndmask_b32_e64 v56, v40, 1.0, vcc
	ds_read_b128 v[40:43], v3 offset:61744
	ds_read_b128 v[44:47], v3 offset:61760
	ds_read_b128 v[48:51], v3 offset:61776
	ds_read_b128 v[52:55], v3 offset:61792
	s_waitcnt lgkmcnt(3)
	v_mul_f32_e32 v40, v4, v40
	v_fma_f32 v40, v56, v57, -v40
	v_fma_f32 v40, -v5, v41, v40
	v_fma_f32 v40, -v6, v42, v40
	v_fma_f32 v40, -v7, v43, v40
	s_waitcnt lgkmcnt(2)
	v_fma_f32 v40, -v8, v44, v40
	v_fma_f32 v40, -v9, v45, v40
	v_fma_f32 v40, -v10, v46, v40
	v_fma_f32 v40, -v11, v47, v40
	s_waitcnt lgkmcnt(1)
	v_fma_f32 v40, -v12, v48, v40
	v_fma_f32 v40, -v13, v49, v40
	v_fma_f32 v40, -v14, v50, v40
	v_fma_f32 v40, -v15, v51, v40
	s_waitcnt lgkmcnt(0)
	v_fma_f32 v44, -v16, v52, v40
	ds_read_b128 v[40:43], v3 offset:61808
	v_fma_f32 v44, -v17, v53, v44
	v_fma_f32 v44, -v18, v54, v44
	v_fma_f32 v48, -v19, v55, v44
	ds_read_b128 v[44:47], v3 offset:61824
	s_waitcnt lgkmcnt(1)
	v_fma_f32 v40, -v20, v40, v48
	v_fma_f32 v40, -v21, v41, v40
	v_fma_f32 v40, -v22, v42, v40
	v_fma_f32 v40, -v23, v43, v40
	s_waitcnt lgkmcnt(0)
	v_fma_f32 v44, -v24, v44, v40
	ds_read_b128 v[40:43], v3 offset:61840
	v_fma_f32 v44, -v25, v45, v44
	v_fma_f32 v44, -v26, v46, v44
	v_fma_f32 v48, -v27, v47, v44
	ds_read_b128 v[44:47], v3 offset:61856
	s_waitcnt lgkmcnt(1)
	v_fma_f32 v40, -v28, v40, v48
	v_fma_f32 v40, -v29, v41, v40
	v_fma_f32 v40, -v30, v42, v40
	v_fma_f32 v48, -v31, v43, v40
	ds_read_b128 v[40:43], v3 offset:61872
	s_waitcnt lgkmcnt(1)
	v_fma_f32 v3, -v32, v44, v48
	v_fma_f32 v3, -v33, v45, v3
	v_fma_f32 v3, -v35, v46, v3
	v_fma_f32 v3, -v36, v47, v3
	s_waitcnt lgkmcnt(0)
	v_fma_f32 v3, -v37, v40, v3
	v_fma_f32 v3, -v38, v41, v3
	v_fma_f32 v40, -v39, v42, v3
	v_fmac_f32_e32 v40, 0x80000000, v43
	ds_read_u16 v42, v2 offset:9792
	v_lshlrev_b32_e32 v3, 2, v0
	v_add_u32_e32 v41, s0, v3
	ds_read2_b32 v[46:47], v41 offset0:36 offset1:100
	v_add_u32_e32 v3, 32, v3
	s_waitcnt lgkmcnt(0)
; DEVI float bf2f(bf16_t b) { return __uint_as_float(((unsigned)b) << 16); }
; DEVI void prep_item(const Params& p, int j, int n, int h, char* smem) {
;     ...
;     for (int i = 0; i < 64; ++i) {
;       const float* amz = am + zero;
;       const float* sbz = sbeta + zero;
;       const float eg = __expf(sbz[64 + i]);
;       float acc = bf2f(*(const unsigned short*)(src + i * 272)) * sbz[i] * (isu ? 1.0f : eg);
; #pragma unroll
;       for (int j4 = 0; j4 < (i + 3) / 4; ++j4) {
;         const f32x4 a = *(const f32x4*)(amz + i * 68 + j4 * 4);
;         acc -= a[0] * x[j4 * 4 + 0];
;         acc -= a[1] * x[j4 * 4 + 1];
;         acc -= a[2] * x[j4 * 4 + 2];
;         acc -= a[3] * x[j4 * 4 + 3];
;       }
;       asm volatile("" : "+v"(zero), "+v"(acc));
;       x[i] = acc;
;     }
	v_mul_f32_e32 v41, 0x3fb8aa3b, v47
	v_lshlrev_b32_e32 v47, 16, v42
	ds_read_b128 v[42:45], v3 offset:62016
	v_exp_f32_e32 v41, v41
	v_mul_f32_e32 v58, v46, v47
	ds_read_b128 v[46:49], v3 offset:62032
	ds_read_b128 v[50:53], v3 offset:62048
	ds_read_b128 v[54:57], v3 offset:62064
	v_cndmask_b32_e64 v41, v41, 1.0, vcc
	s_waitcnt lgkmcnt(3)
	v_mul_f32_e32 v42, v4, v42
	v_fma_f32 v41, v41, v58, -v42
	v_fma_f32 v41, -v5, v43, v41
	v_fma_f32 v41, -v6, v44, v41
	v_fma_f32 v41, -v7, v45, v41
	s_waitcnt lgkmcnt(2)
	v_fma_f32 v41, -v8, v46, v41
	v_fma_f32 v41, -v9, v47, v41
	v_fma_f32 v41, -v10, v48, v41
	v_fma_f32 v41, -v11, v49, v41
	s_waitcnt lgkmcnt(1)
	v_fma_f32 v41, -v12, v50, v41
	v_fma_f32 v41, -v13, v51, v41
	v_fma_f32 v41, -v14, v52, v41
	v_fma_f32 v41, -v15, v53, v41
	ds_read_b128 v[42:45], v3 offset:62080
	s_waitcnt lgkmcnt(1)
	v_fma_f32 v41, -v16, v54, v41
	v_fma_f32 v41, -v17, v55, v41
	v_fma_f32 v41, -v18, v56, v41
	v_fma_f32 v41, -v19, v57, v41
	ds_read_b128 v[46:49], v3 offset:62096
	s_waitcnt lgkmcnt(1)
	v_fma_f32 v41, -v20, v42, v41
	v_fma_f32 v41, -v21, v43, v41
	v_fma_f32 v41, -v22, v44, v41
	v_fma_f32 v41, -v23, v45, v41
	ds_read_b128 v[42:45], v3 offset:62112
	s_waitcnt lgkmcnt(1)
	v_fma_f32 v41, -v24, v46, v41
	v_fma_f32 v41, -v25, v47, v41
	v_fma_f32 v41, -v26, v48, v41
	v_fma_f32 v41, -v27, v49, v41
	ds_read_b128 v[46:49], v3 offset:62128
	s_waitcnt lgkmcnt(1)
	v_fma_f32 v41, -v28, v42, v41
	v_fma_f32 v41, -v29, v43, v41
	v_fma_f32 v41, -v30, v44, v41
	v_fma_f32 v41, -v31, v45, v41
	ds_read_b128 v[42:45], v3 offset:62144
	s_waitcnt lgkmcnt(1)
	v_fma_f32 v3, -v32, v46, v41
	v_fma_f32 v3, -v33, v47, v3
	v_fma_f32 v3, -v35, v48, v3
	v_fma_f32 v3, -v36, v49, v3
	s_waitcnt lgkmcnt(0)
	v_fma_f32 v3, -v37, v42, v3
	v_fma_f32 v3, -v38, v43, v3
	v_fma_f32 v3, -v39, v44, v3
	v_fma_f32 v41, -v40, v45, v3
	ds_read_u16 v43, v2 offset:10064
	v_lshlrev_b32_e32 v3, 2, v0
	v_add_u32_e32 v42, s0, v3
	ds_read2_b32 v[46:47], v42 offset0:37 offset1:101
	v_add_u32_e32 v3, 32, v3
	s_waitcnt lgkmcnt(0)
	v_mul_f32_e32 v42, 0x3fb8aa3b, v47
	v_exp_f32_e32 v42, v42
	v_lshlrev_b32_e32 v47, 16, v43
	v_mul_f32_e32 v59, v46, v47
	v_cndmask_b32_e64 v58, v42, 1.0, vcc
	ds_read_b128 v[42:45], v3 offset:62288
	ds_read_b128 v[46:49], v3 offset:62304
	ds_read_b128 v[50:53], v3 offset:62320
	ds_read_b128 v[54:57], v3 offset:62336
	s_waitcnt lgkmcnt(3)
	v_mul_f32_e32 v42, v4, v42
	v_fma_f32 v42, v58, v59, -v42
	v_fma_f32 v42, -v5, v43, v42
	v_fma_f32 v42, -v6, v44, v42
	v_fma_f32 v42, -v7, v45, v42
	s_waitcnt lgkmcnt(2)
	v_fma_f32 v42, -v8, v46, v42
	v_fma_f32 v42, -v9, v47, v42
	v_fma_f32 v42, -v10, v48, v42
	v_fma_f32 v42, -v11, v49, v42
	s_waitcnt lgkmcnt(1)
	v_fma_f32 v42, -v12, v50, v42
	v_fma_f32 v42, -v13, v51, v42
	v_fma_f32 v42, -v14, v52, v42
	v_fma_f32 v42, -v15, v53, v42
	s_waitcnt lgkmcnt(0)
	v_fma_f32 v46, -v16, v54, v42
	ds_read_b128 v[42:45], v3 offset:62352
	v_fma_f32 v46, -v17, v55, v46
	v_fma_f32 v46, -v18, v56, v46
	v_fma_f32 v50, -v19, v57, v46
	ds_read_b128 v[46:49], v3 offset:62368
	s_waitcnt lgkmcnt(1)
	v_fma_f32 v42, -v20, v42, v50
	v_fma_f32 v42, -v21, v43, v42
	v_fma_f32 v42, -v22, v44, v42
	v_fma_f32 v42, -v23, v45, v42
	s_waitcnt lgkmcnt(0)
	v_fma_f32 v46, -v24, v46, v42
	ds_read_b128 v[42:45], v3 offset:62384
	v_fma_f32 v46, -v25, v47, v46
	v_fma_f32 v46, -v26, v48, v46
	v_fma_f32 v50, -v27, v49, v46
	ds_read_b128 v[46:49], v3 offset:62400
	s_waitcnt lgkmcnt(1)
	v_fma_f32 v42, -v28, v42, v50
	v_fma_f32 v42, -v29, v43, v42
	v_fma_f32 v42, -v30, v44, v42
	v_fma_f32 v42, -v31, v45, v42
	s_waitcnt lgkmcnt(0)
	v_fma_f32 v46, -v32, v46, v42
	ds_read_b128 v[42:45], v3 offset:62416
	v_fma_f32 v46, -v33, v47, v46
	v_fma_f32 v46, -v35, v48, v46
	v_fma_f32 v50, -v36, v49, v46
	ds_read_b128 v[46:49], v3 offset:62432
	s_waitcnt lgkmcnt(1)
	v_fma_f32 v3, -v37, v42, v50
	v_fma_f32 v3, -v38, v43, v3
	v_fma_f32 v3, -v39, v44, v3
	v_fma_f32 v3, -v40, v45, v3
	s_waitcnt lgkmcnt(0)
	v_fma_f32 v42, -v41, v46, v3
	v_fmac_f32_e32 v42, 0x80000000, v47
	v_fmac_f32_e32 v42, 0x80000000, v48
	v_fmac_f32_e32 v42, 0x80000000, v49
	ds_read_u16 v44, v2 offset:10336
	v_lshlrev_b32_e32 v3, 2, v0
	v_add_u32_e32 v43, s0, v3
	ds_read2_b32 v[48:49], v43 offset0:38 offset1:102
	v_add_u32_e32 v3, 32, v3
	s_waitcnt lgkmcnt(0)
	v_mul_f32_e32 v43, 0x3fb8aa3b, v49
	v_lshlrev_b32_e32 v49, 16, v44
	ds_read_b128 v[44:47], v3 offset:62560
	v_exp_f32_e32 v43, v43
	v_mul_f32_e32 v60, v48, v49
	ds_read_b128 v[48:51], v3 offset:62576
	ds_read_b128 v[52:55], v3 offset:62592
	ds_read_b128 v[56:59], v3 offset:62608
	v_cndmask_b32_e64 v43, v43, 1.0, vcc
	s_waitcnt lgkmcnt(3)
	v_mul_f32_e32 v44, v4, v44
	v_fma_f32 v43, v43, v60, -v44
	v_fma_f32 v43, -v5, v45, v43
	v_fma_f32 v43, -v6, v46, v43
	v_fma_f32 v43, -v7, v47, v43
	s_waitcnt lgkmcnt(2)
	v_fma_f32 v43, -v8, v48, v43
	v_fma_f32 v43, -v9, v49, v43
	v_fma_f32 v43, -v10, v50, v43
	v_fma_f32 v43, -v11, v51, v43
	s_waitcnt lgkmcnt(1)
	v_fma_f32 v43, -v12, v52, v43
	v_fma_f32 v43, -v13, v53, v43
	v_fma_f32 v43, -v14, v54, v43
	v_fma_f32 v43, -v15, v55, v43
	ds_read_b128 v[44:47], v3 offset:62624
	s_waitcnt lgkmcnt(1)
	v_fma_f32 v43, -v16, v56, v43
	v_fma_f32 v43, -v17, v57, v43
	v_fma_f32 v43, -v18, v58, v43
	v_fma_f32 v43, -v19, v59, v43
	ds_read_b128 v[48:51], v3 offset:62640
	s_waitcnt lgkmcnt(1)
	v_fma_f32 v43, -v20, v44, v43
	v_fma_f32 v43, -v21, v45, v43
	v_fma_f32 v43, -v22, v46, v43
	v_fma_f32 v43, -v23, v47, v43
	ds_read_b128 v[44:47], v3 offset:62656
	s_waitcnt lgkmcnt(1)
	v_fma_f32 v43, -v24, v48, v43
	v_fma_f32 v43, -v25, v49, v43
	v_fma_f32 v43, -v26, v50, v43
	v_fma_f32 v43, -v27, v51, v43
	ds_read_b128 v[48:51], v3 offset:62672
	s_waitcnt lgkmcnt(1)
; DEVI float bf2f(bf16_t b) { return __uint_as_float(((unsigned)b) << 16); }
; DEVI void prep_item(const Params& p, int j, int n, int h, char* smem) {
;     ...
;     for (int i = 0; i < 64; ++i) {
;       const float* amz = am + zero;
;       const float* sbz = sbeta + zero;
;       const float eg = __expf(sbz[64 + i]);
;       float acc = bf2f(*(const unsigned short*)(src + i * 272)) * sbz[i] * (isu ? 1.0f : eg);
; #pragma unroll
;       for (int j4 = 0; j4 < (i + 3) / 4; ++j4) {
;         const f32x4 a = *(const f32x4*)(amz + i * 68 + j4 * 4);
;         acc -= a[0] * x[j4 * 4 + 0];
;         acc -= a[1] * x[j4 * 4 + 1];
;         acc -= a[2] * x[j4 * 4 + 2];
;         acc -= a[3] * x[j4 * 4 + 3];
;       }
;       asm volatile("" : "+v"(zero), "+v"(acc));
;       x[i] = acc;
;     }
	v_fma_f32 v43, -v28, v44, v43
	v_fma_f32 v43, -v29, v45, v43
	v_fma_f32 v43, -v30, v46, v43
	v_fma_f32 v43, -v31, v47, v43
	ds_read_b128 v[44:47], v3 offset:62688
	s_waitcnt lgkmcnt(1)
	v_fma_f32 v43, -v32, v48, v43
	v_fma_f32 v43, -v33, v49, v43
	v_fma_f32 v43, -v35, v50, v43
	v_fma_f32 v43, -v36, v51, v43
	ds_read_b128 v[48:51], v3 offset:62704
	s_waitcnt lgkmcnt(1)
	v_fma_f32 v3, -v37, v44, v43
	v_fma_f32 v3, -v38, v45, v3
	v_fma_f32 v3, -v39, v46, v3
	v_fma_f32 v3, -v40, v47, v3
	s_waitcnt lgkmcnt(0)
	v_fma_f32 v3, -v41, v48, v3
	v_fma_f32 v43, -v42, v49, v3
	v_fmac_f32_e32 v43, 0x80000000, v50
	v_fmac_f32_e32 v43, 0x80000000, v51
	ds_read_u16 v45, v2 offset:10608
	v_lshlrev_b32_e32 v3, 2, v0
	v_add_u32_e32 v44, s0, v3
	ds_read2_b32 v[48:49], v44 offset0:39 offset1:103
	v_add_u32_e32 v3, 32, v3
	s_waitcnt lgkmcnt(0)
	v_mul_f32_e32 v44, 0x3fb8aa3b, v49
	v_exp_f32_e32 v44, v44
	v_lshlrev_b32_e32 v49, 16, v45
	v_mul_f32_e32 v61, v48, v49
	v_cndmask_b32_e64 v60, v44, 1.0, vcc
	ds_read_b128 v[44:47], v3 offset:62832
	ds_read_b128 v[48:51], v3 offset:62848
	ds_read_b128 v[52:55], v3 offset:62864
	ds_read_b128 v[56:59], v3 offset:62880
	s_waitcnt lgkmcnt(3)
	v_mul_f32_e32 v44, v4, v44
	v_fma_f32 v44, v60, v61, -v44
	v_fma_f32 v44, -v5, v45, v44
	v_fma_f32 v44, -v6, v46, v44
	v_fma_f32 v44, -v7, v47, v44
	s_waitcnt lgkmcnt(2)
	v_fma_f32 v44, -v8, v48, v44
	v_fma_f32 v44, -v9, v49, v44
	v_fma_f32 v44, -v10, v50, v44
	v_fma_f32 v44, -v11, v51, v44
	s_waitcnt lgkmcnt(1)
	v_fma_f32 v44, -v12, v52, v44
	v_fma_f32 v44, -v13, v53, v44
	v_fma_f32 v44, -v14, v54, v44
	v_fma_f32 v44, -v15, v55, v44
	s_waitcnt lgkmcnt(0)
	v_fma_f32 v48, -v16, v56, v44
	ds_read_b128 v[44:47], v3 offset:62896
	v_fma_f32 v48, -v17, v57, v48
	v_fma_f32 v48, -v18, v58, v48
	v_fma_f32 v52, -v19, v59, v48
	ds_read_b128 v[48:51], v3 offset:62912
	s_waitcnt lgkmcnt(1)
	v_fma_f32 v44, -v20, v44, v52
	v_fma_f32 v44, -v21, v45, v44
	v_fma_f32 v44, -v22, v46, v44
	v_fma_f32 v44, -v23, v47, v44
	s_waitcnt lgkmcnt(0)
	v_fma_f32 v48, -v24, v48, v44
	ds_read_b128 v[44:47], v3 offset:62928
	v_fma_f32 v48, -v25, v49, v48
	v_fma_f32 v48, -v26, v50, v48
	v_fma_f32 v52, -v27, v51, v48
	ds_read_b128 v[48:51], v3 offset:62944
	s_waitcnt lgkmcnt(1)
	v_fma_f32 v44, -v28, v44, v52
	v_fma_f32 v44, -v29, v45, v44
	v_fma_f32 v44, -v30, v46, v44
	v_fma_f32 v44, -v31, v47, v44
	s_waitcnt lgkmcnt(0)
	v_fma_f32 v48, -v32, v48, v44
	ds_read_b128 v[44:47], v3 offset:62960
	v_fma_f32 v48, -v33, v49, v48
	v_fma_f32 v48, -v35, v50, v48
	v_fma_f32 v52, -v36, v51, v48
	ds_read_b128 v[48:51], v3 offset:62976
	s_waitcnt lgkmcnt(1)
	v_fma_f32 v3, -v37, v44, v52
	v_fma_f32 v3, -v38, v45, v3
	v_fma_f32 v3, -v39, v46, v3
	v_fma_f32 v3, -v40, v47, v3
	s_waitcnt lgkmcnt(0)
	v_fma_f32 v3, -v41, v48, v3
	v_fma_f32 v3, -v42, v49, v3
	v_fma_f32 v44, -v43, v50, v3
	v_fmac_f32_e32 v44, 0x80000000, v51
	ds_read_u16 v46, v2 offset:10880
	v_lshlrev_b32_e32 v3, 2, v0
	v_add_u32_e32 v45, s0, v3
	ds_read2_b32 v[50:51], v45 offset0:40 offset1:104
	v_add_u32_e32 v3, 32, v3
	s_waitcnt lgkmcnt(0)
	v_mul_f32_e32 v45, 0x3fb8aa3b, v51
	v_lshlrev_b32_e32 v51, 16, v46
	ds_read_b128 v[46:49], v3 offset:63104
	v_exp_f32_e32 v45, v45
	v_mul_f32_e32 v62, v50, v51
	ds_read_b128 v[50:53], v3 offset:63120
	ds_read_b128 v[54:57], v3 offset:63136
	ds_read_b128 v[58:61], v3 offset:63152
	v_cndmask_b32_e64 v45, v45, 1.0, vcc
	s_waitcnt lgkmcnt(3)
	v_mul_f32_e32 v46, v4, v46
	v_fma_f32 v45, v45, v62, -v46
	v_fma_f32 v45, -v5, v47, v45
	v_fma_f32 v45, -v6, v48, v45
	v_fma_f32 v45, -v7, v49, v45
	s_waitcnt lgkmcnt(2)
	v_fma_f32 v45, -v8, v50, v45
	v_fma_f32 v45, -v9, v51, v45
	v_fma_f32 v45, -v10, v52, v45
	v_fma_f32 v45, -v11, v53, v45
	s_waitcnt lgkmcnt(1)
	v_fma_f32 v45, -v12, v54, v45
	v_fma_f32 v45, -v13, v55, v45
	v_fma_f32 v45, -v14, v56, v45
	v_fma_f32 v45, -v15, v57, v45
	ds_read_b128 v[46:49], v3 offset:63168
	s_waitcnt lgkmcnt(1)
	v_fma_f32 v45, -v16, v58, v45
	v_fma_f32 v45, -v17, v59, v45
	v_fma_f32 v45, -v18, v60, v45
	v_fma_f32 v45, -v19, v61, v45
	ds_read_b128 v[50:53], v3 offset:63184
	s_waitcnt lgkmcnt(1)
	v_fma_f32 v45, -v20, v46, v45
	v_fma_f32 v45, -v21, v47, v45
	v_fma_f32 v45, -v22, v48, v45
	v_fma_f32 v45, -v23, v49, v45
	ds_read_b128 v[46:49], v3 offset:63200
	s_waitcnt lgkmcnt(1)
	v_fma_f32 v45, -v24, v50, v45
	v_fma_f32 v45, -v25, v51, v45
	v_fma_f32 v45, -v26, v52, v45
	v_fma_f32 v45, -v27, v53, v45
	ds_read_b128 v[50:53], v3 offset:63216
	s_waitcnt lgkmcnt(1)
	v_fma_f32 v45, -v28, v46, v45
	v_fma_f32 v45, -v29, v47, v45
	v_fma_f32 v45, -v30, v48, v45
	v_fma_f32 v45, -v31, v49, v45
	ds_read_b128 v[46:49], v3 offset:63232
	s_waitcnt lgkmcnt(1)
	v_fma_f32 v45, -v32, v50, v45
	v_fma_f32 v45, -v33, v51, v45
	v_fma_f32 v45, -v35, v52, v45
	v_fma_f32 v45, -v36, v53, v45
	ds_read_b128 v[50:53], v3 offset:63248
	s_waitcnt lgkmcnt(1)
	v_fma_f32 v3, -v37, v46, v45
	v_fma_f32 v3, -v38, v47, v3
	v_fma_f32 v3, -v39, v48, v3
	v_fma_f32 v3, -v40, v49, v3
	s_waitcnt lgkmcnt(0)
	v_fma_f32 v3, -v41, v50, v3
	v_fma_f32 v3, -v42, v51, v3
	v_fma_f32 v3, -v43, v52, v3
	v_fma_f32 v45, -v44, v53, v3
	ds_read_u16 v47, v2 offset:11152
	v_lshlrev_b32_e32 v3, 2, v0
	v_add_u32_e32 v46, s0, v3
	ds_read2_b32 v[50:51], v46 offset0:41 offset1:105
	v_add_u32_e32 v3, 32, v3
	s_waitcnt lgkmcnt(0)
	v_mul_f32_e32 v46, 0x3fb8aa3b, v51
	v_exp_f32_e32 v46, v46
	v_lshlrev_b32_e32 v51, 16, v47
	v_mul_f32_e32 v63, v50, v51
	v_cndmask_b32_e64 v62, v46, 1.0, vcc
	ds_read_b128 v[46:49], v3 offset:63376
	ds_read_b128 v[50:53], v3 offset:63392
	ds_read_b128 v[54:57], v3 offset:63408
	ds_read_b128 v[58:61], v3 offset:63424
	s_waitcnt lgkmcnt(3)
; DEVI float bf2f(bf16_t b) { return __uint_as_float(((unsigned)b) << 16); }
; DEVI void prep_item(const Params& p, int j, int n, int h, char* smem) {
;     ...
;     for (int i = 0; i < 64; ++i) {
;       const float* amz = am + zero;
;       const float* sbz = sbeta + zero;
;       const float eg = __expf(sbz[64 + i]);
;       float acc = bf2f(*(const unsigned short*)(src + i * 272)) * sbz[i] * (isu ? 1.0f : eg);
; #pragma unroll
;       for (int j4 = 0; j4 < (i + 3) / 4; ++j4) {
;         const f32x4 a = *(const f32x4*)(amz + i * 68 + j4 * 4);
;         acc -= a[0] * x[j4 * 4 + 0];
;         acc -= a[1] * x[j4 * 4 + 1];
;         acc -= a[2] * x[j4 * 4 + 2];
;         acc -= a[3] * x[j4 * 4 + 3];
;       }
;       asm volatile("" : "+v"(zero), "+v"(acc));
;       x[i] = acc;
;     }
	v_mul_f32_e32 v46, v4, v46
	v_fma_f32 v46, v62, v63, -v46
	v_fma_f32 v46, -v5, v47, v46
	v_fma_f32 v46, -v6, v48, v46
	v_fma_f32 v46, -v7, v49, v46
	s_waitcnt lgkmcnt(2)
	v_fma_f32 v46, -v8, v50, v46
	v_fma_f32 v46, -v9, v51, v46
	v_fma_f32 v46, -v10, v52, v46
	v_fma_f32 v46, -v11, v53, v46
	s_waitcnt lgkmcnt(1)
	v_fma_f32 v46, -v12, v54, v46
	v_fma_f32 v46, -v13, v55, v46
	v_fma_f32 v46, -v14, v56, v46
	v_fma_f32 v46, -v15, v57, v46
	s_waitcnt lgkmcnt(0)
	v_fma_f32 v50, -v16, v58, v46
	ds_read_b128 v[46:49], v3 offset:63440
	v_fma_f32 v50, -v17, v59, v50
	v_fma_f32 v50, -v18, v60, v50
	v_fma_f32 v54, -v19, v61, v50
	ds_read_b128 v[50:53], v3 offset:63456
	s_waitcnt lgkmcnt(1)
	v_fma_f32 v46, -v20, v46, v54
	v_fma_f32 v46, -v21, v47, v46
	v_fma_f32 v46, -v22, v48, v46
	v_fma_f32 v46, -v23, v49, v46
	s_waitcnt lgkmcnt(0)
	v_fma_f32 v50, -v24, v50, v46
	ds_read_b128 v[46:49], v3 offset:63472
	v_fma_f32 v50, -v25, v51, v50
	v_fma_f32 v50, -v26, v52, v50
	v_fma_f32 v54, -v27, v53, v50
	ds_read_b128 v[50:53], v3 offset:63488
	s_waitcnt lgkmcnt(1)
	v_fma_f32 v46, -v28, v46, v54
	v_fma_f32 v46, -v29, v47, v46
	v_fma_f32 v46, -v30, v48, v46
	v_fma_f32 v46, -v31, v49, v46
	s_waitcnt lgkmcnt(0)
	v_fma_f32 v50, -v32, v50, v46
	ds_read_b128 v[46:49], v3 offset:63504
	v_fma_f32 v50, -v33, v51, v50
	v_fma_f32 v50, -v35, v52, v50
	v_fma_f32 v54, -v36, v53, v50
	ds_read_b128 v[50:53], v3 offset:63520
	s_waitcnt lgkmcnt(1)
	v_fma_f32 v46, -v37, v46, v54
	v_fma_f32 v46, -v38, v47, v46
	v_fma_f32 v46, -v39, v48, v46
	v_fma_f32 v54, -v40, v49, v46
	ds_read_b128 v[46:49], v3 offset:63536
	s_waitcnt lgkmcnt(1)
	v_fma_f32 v3, -v41, v50, v54
	v_fma_f32 v3, -v42, v51, v3
	v_fma_f32 v3, -v43, v52, v3
	v_fma_f32 v3, -v44, v53, v3
	s_waitcnt lgkmcnt(0)
	v_fma_f32 v46, -v45, v46, v3
	v_fmac_f32_e32 v46, 0x80000000, v47
	v_fmac_f32_e32 v46, 0x80000000, v48
	v_fmac_f32_e32 v46, 0x80000000, v49
	ds_read_u16 v48, v2 offset:11424
	v_lshlrev_b32_e32 v3, 2, v0
	v_add_u32_e32 v47, s0, v3
	ds_read2_b32 v[52:53], v47 offset0:42 offset1:106
	v_add_u32_e32 v3, 32, v3
	s_waitcnt lgkmcnt(0)
	v_mul_f32_e32 v47, 0x3fb8aa3b, v53
	v_lshlrev_b32_e32 v53, 16, v48
	ds_read_b128 v[48:51], v3 offset:63648
	v_exp_f32_e32 v47, v47
	v_mul_f32_e32 v64, v52, v53
	ds_read_b128 v[52:55], v3 offset:63664
	ds_read_b128 v[56:59], v3 offset:63680
	ds_read_b128 v[60:63], v3 offset:63696
	v_cndmask_b32_e64 v47, v47, 1.0, vcc
	s_waitcnt lgkmcnt(3)
	v_mul_f32_e32 v48, v4, v48
	v_fma_f32 v47, v47, v64, -v48
	v_fma_f32 v47, -v5, v49, v47
	v_fma_f32 v47, -v6, v50, v47
	v_fma_f32 v47, -v7, v51, v47
	s_waitcnt lgkmcnt(2)
	v_fma_f32 v47, -v8, v52, v47
	v_fma_f32 v47, -v9, v53, v47
	v_fma_f32 v47, -v10, v54, v47
	v_fma_f32 v47, -v11, v55, v47
	s_waitcnt lgkmcnt(1)
	v_fma_f32 v47, -v12, v56, v47
	v_fma_f32 v47, -v13, v57, v47
	v_fma_f32 v47, -v14, v58, v47
	v_fma_f32 v47, -v15, v59, v47
	ds_read_b128 v[48:51], v3 offset:63712
	s_waitcnt lgkmcnt(1)
	v_fma_f32 v47, -v16, v60, v47
	v_fma_f32 v47, -v17, v61, v47
	v_fma_f32 v47, -v18, v62, v47
	v_fma_f32 v47, -v19, v63, v47
	ds_read_b128 v[52:55], v3 offset:63728
	s_waitcnt lgkmcnt(1)
	v_fma_f32 v47, -v20, v48, v47
	v_fma_f32 v47, -v21, v49, v47
	v_fma_f32 v47, -v22, v50, v47
	v_fma_f32 v47, -v23, v51, v47
	ds_read_b128 v[48:51], v3 offset:63744
	s_waitcnt lgkmcnt(1)
	v_fma_f32 v47, -v24, v52, v47
	v_fma_f32 v47, -v25, v53, v47
	v_fma_f32 v47, -v26, v54, v47
	v_fma_f32 v47, -v27, v55, v47
	ds_read_b128 v[52:55], v3 offset:63760
	s_waitcnt lgkmcnt(1)
	v_fma_f32 v47, -v28, v48, v47
	v_fma_f32 v47, -v29, v49, v47
	v_fma_f32 v47, -v30, v50, v47
	v_fma_f32 v47, -v31, v51, v47
	ds_read_b128 v[48:51], v3 offset:63776
	s_waitcnt lgkmcnt(1)
	v_fma_f32 v47, -v32, v52, v47
	v_fma_f32 v47, -v33, v53, v47
	v_fma_f32 v47, -v35, v54, v47
	v_fma_f32 v47, -v36, v55, v47
	ds_read_b128 v[52:55], v3 offset:63792
	s_waitcnt lgkmcnt(1)
	v_fma_f32 v47, -v37, v48, v47
	v_fma_f32 v47, -v38, v49, v47
	v_fma_f32 v47, -v39, v50, v47
	v_fma_f32 v47, -v40, v51, v47
	ds_read_b128 v[48:51], v3 offset:63808
	s_waitcnt lgkmcnt(1)
	v_fma_f32 v3, -v41, v52, v47
	v_fma_f32 v3, -v42, v53, v3
	v_fma_f32 v3, -v43, v54, v3
	v_fma_f32 v3, -v44, v55, v3
	s_waitcnt lgkmcnt(0)
	v_fma_f32 v3, -v45, v48, v3
	v_fma_f32 v47, -v46, v49, v3
	v_fmac_f32_e32 v47, 0x80000000, v50
	v_fmac_f32_e32 v47, 0x80000000, v51
	ds_read_u16 v49, v2 offset:11696
	v_lshlrev_b32_e32 v3, 2, v0
	v_add_u32_e32 v48, s0, v3
	ds_read2_b32 v[52:53], v48 offset0:43 offset1:107
	v_add_u32_e32 v3, 32, v3
	s_waitcnt lgkmcnt(0)
	v_mul_f32_e32 v48, 0x3fb8aa3b, v53
	v_exp_f32_e32 v48, v48
	v_lshlrev_b32_e32 v53, 16, v49
	v_mul_f32_e32 v65, v52, v53
	v_cndmask_b32_e64 v64, v48, 1.0, vcc
	ds_read_b128 v[48:51], v3 offset:63920
	ds_read_b128 v[52:55], v3 offset:63936
	ds_read_b128 v[56:59], v3 offset:63952
	ds_read_b128 v[60:63], v3 offset:63968
	s_waitcnt lgkmcnt(3)
	v_mul_f32_e32 v48, v4, v48
	v_fma_f32 v48, v64, v65, -v48
	v_fma_f32 v48, -v5, v49, v48
	v_fma_f32 v48, -v6, v50, v48
	v_fma_f32 v48, -v7, v51, v48
	s_waitcnt lgkmcnt(2)
	v_fma_f32 v48, -v8, v52, v48
	v_fma_f32 v48, -v9, v53, v48
	v_fma_f32 v48, -v10, v54, v48
	v_fma_f32 v48, -v11, v55, v48
	s_waitcnt lgkmcnt(1)
	v_fma_f32 v48, -v12, v56, v48
	v_fma_f32 v48, -v13, v57, v48
	v_fma_f32 v48, -v14, v58, v48
	v_fma_f32 v48, -v15, v59, v48
	s_waitcnt lgkmcnt(0)
	v_fma_f32 v52, -v16, v60, v48
	ds_read_b128 v[48:51], v3 offset:63984
	v_fma_f32 v52, -v17, v61, v52
	v_fma_f32 v52, -v18, v62, v52
	v_fma_f32 v56, -v19, v63, v52
	ds_read_b128 v[52:55], v3 offset:64000
	s_waitcnt lgkmcnt(1)
	v_fma_f32 v48, -v20, v48, v56
	v_fma_f32 v48, -v21, v49, v48
	v_fma_f32 v48, -v22, v50, v48
	v_fma_f32 v48, -v23, v51, v48
	s_waitcnt lgkmcnt(0)
; DEVI float bf2f(bf16_t b) { return __uint_as_float(((unsigned)b) << 16); }
; DEVI void prep_item(const Params& p, int j, int n, int h, char* smem) {
;     ...
;     for (int i = 0; i < 64; ++i) {
;       const float* amz = am + zero;
;       const float* sbz = sbeta + zero;
;       const float eg = __expf(sbz[64 + i]);
;       float acc = bf2f(*(const unsigned short*)(src + i * 272)) * sbz[i] * (isu ? 1.0f : eg);
; #pragma unroll
;       for (int j4 = 0; j4 < (i + 3) / 4; ++j4) {
;         const f32x4 a = *(const f32x4*)(amz + i * 68 + j4 * 4);
;         acc -= a[0] * x[j4 * 4 + 0];
;         acc -= a[1] * x[j4 * 4 + 1];
;         acc -= a[2] * x[j4 * 4 + 2];
;         acc -= a[3] * x[j4 * 4 + 3];
;       }
;       asm volatile("" : "+v"(zero), "+v"(acc));
;       x[i] = acc;
;     }
	v_fma_f32 v52, -v24, v52, v48
	ds_read_b128 v[48:51], v3 offset:64016
	v_fma_f32 v52, -v25, v53, v52
	v_fma_f32 v52, -v26, v54, v52
	v_fma_f32 v56, -v27, v55, v52
	ds_read_b128 v[52:55], v3 offset:64032
	s_waitcnt lgkmcnt(1)
	v_fma_f32 v48, -v28, v48, v56
	v_fma_f32 v48, -v29, v49, v48
	v_fma_f32 v48, -v30, v50, v48
	v_fma_f32 v48, -v31, v51, v48
	s_waitcnt lgkmcnt(0)
	v_fma_f32 v52, -v32, v52, v48
	ds_read_b128 v[48:51], v3 offset:64048
	v_fma_f32 v52, -v33, v53, v52
	v_fma_f32 v52, -v35, v54, v52
	v_fma_f32 v56, -v36, v55, v52
	ds_read_b128 v[52:55], v3 offset:64064
	s_waitcnt lgkmcnt(1)
	v_fma_f32 v48, -v37, v48, v56
	v_fma_f32 v48, -v38, v49, v48
	v_fma_f32 v48, -v39, v50, v48
	v_fma_f32 v56, -v40, v51, v48
	ds_read_b128 v[48:51], v3 offset:64080
	s_waitcnt lgkmcnt(1)
	v_fma_f32 v3, -v41, v52, v56
	v_fma_f32 v3, -v42, v53, v3
	v_fma_f32 v3, -v43, v54, v3
	v_fma_f32 v3, -v44, v55, v3
	s_waitcnt lgkmcnt(0)
	v_fma_f32 v3, -v45, v48, v3
	v_fma_f32 v3, -v46, v49, v3
	v_fma_f32 v48, -v47, v50, v3
	v_fmac_f32_e32 v48, 0x80000000, v51
	ds_read_u16 v50, v2 offset:11968
	v_lshlrev_b32_e32 v3, 2, v0
	v_add_u32_e32 v49, s0, v3
	ds_read2_b32 v[54:55], v49 offset0:44 offset1:108
	v_add_u32_e32 v3, 32, v3
	s_waitcnt lgkmcnt(0)
	v_mul_f32_e32 v49, 0x3fb8aa3b, v55
	v_lshlrev_b32_e32 v55, 16, v50
	ds_read_b128 v[50:53], v3 offset:64192
	v_exp_f32_e32 v49, v49
	v_mul_f32_e32 v66, v54, v55
	ds_read_b128 v[54:57], v3 offset:64208
	ds_read_b128 v[58:61], v3 offset:64224
	ds_read_b128 v[62:65], v3 offset:64240
	v_cndmask_b32_e64 v49, v49, 1.0, vcc
	s_waitcnt lgkmcnt(3)
	v_mul_f32_e32 v50, v4, v50
	v_fma_f32 v49, v49, v66, -v50
	v_fma_f32 v49, -v5, v51, v49
	v_fma_f32 v49, -v6, v52, v49
	v_fma_f32 v49, -v7, v53, v49
	s_waitcnt lgkmcnt(2)
	v_fma_f32 v49, -v8, v54, v49
	v_fma_f32 v49, -v9, v55, v49
	v_fma_f32 v49, -v10, v56, v49
	v_fma_f32 v49, -v11, v57, v49
	s_waitcnt lgkmcnt(1)
	v_fma_f32 v49, -v12, v58, v49
	v_fma_f32 v49, -v13, v59, v49
	v_fma_f32 v49, -v14, v60, v49
	v_fma_f32 v49, -v15, v61, v49
	ds_read_b128 v[50:53], v3 offset:64256
	s_waitcnt lgkmcnt(1)
	v_fma_f32 v49, -v16, v62, v49
	v_fma_f32 v49, -v17, v63, v49
	v_fma_f32 v49, -v18, v64, v49
	v_fma_f32 v49, -v19, v65, v49
	ds_read_b128 v[54:57], v3 offset:64272
	s_waitcnt lgkmcnt(1)
	v_fma_f32 v49, -v20, v50, v49
	v_fma_f32 v49, -v21, v51, v49
	v_fma_f32 v49, -v22, v52, v49
	v_fma_f32 v49, -v23, v53, v49
	ds_read_b128 v[50:53], v3 offset:64288
	s_waitcnt lgkmcnt(1)
	v_fma_f32 v49, -v24, v54, v49
	v_fma_f32 v49, -v25, v55, v49
	v_fma_f32 v49, -v26, v56, v49
	v_fma_f32 v49, -v27, v57, v49
	ds_read_b128 v[54:57], v3 offset:64304
	s_waitcnt lgkmcnt(1)
	v_fma_f32 v49, -v28, v50, v49
	v_fma_f32 v49, -v29, v51, v49
	v_fma_f32 v49, -v30, v52, v49
	v_fma_f32 v49, -v31, v53, v49
	ds_read_b128 v[50:53], v3 offset:64320
	s_waitcnt lgkmcnt(1)
	v_fma_f32 v49, -v32, v54, v49
	v_fma_f32 v49, -v33, v55, v49
	v_fma_f32 v49, -v35, v56, v49
	v_fma_f32 v49, -v36, v57, v49
	ds_read_b128 v[54:57], v3 offset:64336
	s_waitcnt lgkmcnt(1)
	v_fma_f32 v49, -v37, v50, v49
	v_fma_f32 v49, -v38, v51, v49
	v_fma_f32 v49, -v39, v52, v49
	v_fma_f32 v49, -v40, v53, v49
	ds_read_b128 v[50:53], v3 offset:64352
	s_waitcnt lgkmcnt(1)
	v_fma_f32 v3, -v41, v54, v49
	v_fma_f32 v3, -v42, v55, v3
	v_fma_f32 v3, -v43, v56, v3
	v_fma_f32 v3, -v44, v57, v3
	s_waitcnt lgkmcnt(0)
	v_fma_f32 v3, -v45, v50, v3
	v_fma_f32 v3, -v46, v51, v3
	v_fma_f32 v3, -v47, v52, v3
	v_fma_f32 v49, -v48, v53, v3
	ds_read_u16 v51, v2 offset:12240
	v_lshlrev_b32_e32 v3, 2, v0
	v_add_u32_e32 v50, s0, v3
	ds_read2_b32 v[54:55], v50 offset0:45 offset1:109
	v_add_u32_e32 v3, 32, v3
	s_waitcnt lgkmcnt(0)
	v_mul_f32_e32 v50, 0x3fb8aa3b, v55
	v_exp_f32_e32 v50, v50
	v_lshlrev_b32_e32 v55, 16, v51
	v_mul_f32_e32 v67, v54, v55
	v_cndmask_b32_e64 v66, v50, 1.0, vcc
	ds_read_b128 v[50:53], v3 offset:64464
	ds_read_b128 v[54:57], v3 offset:64480
	ds_read_b128 v[58:61], v3 offset:64496
	ds_read_b128 v[62:65], v3 offset:64512
	s_waitcnt lgkmcnt(3)
	v_mul_f32_e32 v50, v4, v50
	v_fma_f32 v50, v66, v67, -v50
	v_fma_f32 v50, -v5, v51, v50
	v_fma_f32 v50, -v6, v52, v50
	v_fma_f32 v50, -v7, v53, v50
	s_waitcnt lgkmcnt(2)
	v_fma_f32 v50, -v8, v54, v50
	v_fma_f32 v50, -v9, v55, v50
	v_fma_f32 v50, -v10, v56, v50
	v_fma_f32 v50, -v11, v57, v50
	s_waitcnt lgkmcnt(1)
	v_fma_f32 v50, -v12, v58, v50
	v_fma_f32 v50, -v13, v59, v50
	v_fma_f32 v50, -v14, v60, v50
	v_fma_f32 v50, -v15, v61, v50
	s_waitcnt lgkmcnt(0)
	v_fma_f32 v54, -v16, v62, v50
	ds_read_b128 v[50:53], v3 offset:64528
	v_fma_f32 v54, -v17, v63, v54
	v_fma_f32 v54, -v18, v64, v54
	v_fma_f32 v58, -v19, v65, v54
	ds_read_b128 v[54:57], v3 offset:64544
	s_waitcnt lgkmcnt(1)
	v_fma_f32 v50, -v20, v50, v58
	v_fma_f32 v50, -v21, v51, v50
	v_fma_f32 v50, -v22, v52, v50
	v_fma_f32 v50, -v23, v53, v50
	s_waitcnt lgkmcnt(0)
	v_fma_f32 v54, -v24, v54, v50
	ds_read_b128 v[50:53], v3 offset:64560
	v_fma_f32 v54, -v25, v55, v54
	v_fma_f32 v54, -v26, v56, v54
	v_fma_f32 v58, -v27, v57, v54
	ds_read_b128 v[54:57], v3 offset:64576
	s_waitcnt lgkmcnt(1)
	v_fma_f32 v50, -v28, v50, v58
	v_fma_f32 v50, -v29, v51, v50
	v_fma_f32 v50, -v30, v52, v50
	v_fma_f32 v50, -v31, v53, v50
	s_waitcnt lgkmcnt(0)
	v_fma_f32 v54, -v32, v54, v50
	ds_read_b128 v[50:53], v3 offset:64592
	v_fma_f32 v54, -v33, v55, v54
	v_fma_f32 v54, -v35, v56, v54
	v_fma_f32 v58, -v36, v57, v54
	ds_read_b128 v[54:57], v3 offset:64608
	s_waitcnt lgkmcnt(1)
	v_fma_f32 v50, -v37, v50, v58
	v_fma_f32 v50, -v38, v51, v50
	v_fma_f32 v50, -v39, v52, v50
	v_fma_f32 v50, -v40, v53, v50
	s_waitcnt lgkmcnt(0)
; DEVI float bf2f(bf16_t b) { return __uint_as_float(((unsigned)b) << 16); }
; DEVI void prep_item(const Params& p, int j, int n, int h, char* smem) {
;     ...
;     for (int i = 0; i < 64; ++i) {
;       const float* amz = am + zero;
;       const float* sbz = sbeta + zero;
;       const float eg = __expf(sbz[64 + i]);
;       float acc = bf2f(*(const unsigned short*)(src + i * 272)) * sbz[i] * (isu ? 1.0f : eg);
; #pragma unroll
;       for (int j4 = 0; j4 < (i + 3) / 4; ++j4) {
;         const f32x4 a = *(const f32x4*)(amz + i * 68 + j4 * 4);
;         acc -= a[0] * x[j4 * 4 + 0];
;         acc -= a[1] * x[j4 * 4 + 1];
;         acc -= a[2] * x[j4 * 4 + 2];
;         acc -= a[3] * x[j4 * 4 + 3];
;       }
;       asm volatile("" : "+v"(zero), "+v"(acc));
;       x[i] = acc;
;     }
	v_fma_f32 v54, -v41, v54, v50
	ds_read_b128 v[50:53], v3 offset:64624
	v_fma_f32 v54, -v42, v55, v54
	v_fma_f32 v54, -v43, v56, v54
	v_fma_f32 v58, -v44, v57, v54
	ds_read_b128 v[54:57], v3 offset:64640
	s_waitcnt lgkmcnt(1)
	v_fma_f32 v3, -v45, v50, v58
	v_fma_f32 v3, -v46, v51, v3
	v_fma_f32 v3, -v47, v52, v3
	v_fma_f32 v3, -v48, v53, v3
	s_waitcnt lgkmcnt(0)
	v_fma_f32 v50, -v49, v54, v3
	v_fmac_f32_e32 v50, 0x80000000, v55
	v_fmac_f32_e32 v50, 0x80000000, v56
	v_fmac_f32_e32 v50, 0x80000000, v57
	ds_read_u16 v52, v2 offset:12512
	v_lshlrev_b32_e32 v3, 2, v0
	v_add_u32_e32 v51, s0, v3
	ds_read2_b32 v[56:57], v51 offset0:46 offset1:110
	v_add_u32_e32 v3, 32, v3
	s_waitcnt lgkmcnt(0)
	v_mul_f32_e32 v51, 0x3fb8aa3b, v57
	v_lshlrev_b32_e32 v57, 16, v52
	ds_read_b128 v[52:55], v3 offset:64736
	v_exp_f32_e32 v51, v51
	v_mul_f32_e32 v68, v56, v57
	ds_read_b128 v[56:59], v3 offset:64752
	ds_read_b128 v[60:63], v3 offset:64768
	ds_read_b128 v[64:67], v3 offset:64784
	v_cndmask_b32_e64 v51, v51, 1.0, vcc
	s_waitcnt lgkmcnt(3)
	v_mul_f32_e32 v52, v4, v52
	v_fma_f32 v51, v51, v68, -v52
	v_fma_f32 v51, -v5, v53, v51
	v_fma_f32 v51, -v6, v54, v51
	v_fma_f32 v51, -v7, v55, v51
	s_waitcnt lgkmcnt(2)
	v_fma_f32 v51, -v8, v56, v51
	v_fma_f32 v51, -v9, v57, v51
	v_fma_f32 v51, -v10, v58, v51
	v_fma_f32 v51, -v11, v59, v51
	s_waitcnt lgkmcnt(1)
	v_fma_f32 v51, -v12, v60, v51
	v_fma_f32 v51, -v13, v61, v51
	v_fma_f32 v51, -v14, v62, v51
	v_fma_f32 v51, -v15, v63, v51
	ds_read_b128 v[52:55], v3 offset:64800
	s_waitcnt lgkmcnt(1)
	v_fma_f32 v51, -v16, v64, v51
	v_fma_f32 v51, -v17, v65, v51
	v_fma_f32 v51, -v18, v66, v51
	v_fma_f32 v51, -v19, v67, v51
	ds_read_b128 v[56:59], v3 offset:64816
	s_waitcnt lgkmcnt(1)
	v_fma_f32 v51, -v20, v52, v51
	v_fma_f32 v51, -v21, v53, v51
	v_fma_f32 v51, -v22, v54, v51
	v_fma_f32 v51, -v23, v55, v51
	ds_read_b128 v[52:55], v3 offset:64832
	s_waitcnt lgkmcnt(1)
	v_fma_f32 v51, -v24, v56, v51
	v_fma_f32 v51, -v25, v57, v51
	v_fma_f32 v51, -v26, v58, v51
	v_fma_f32 v51, -v27, v59, v51
	ds_read_b128 v[56:59], v3 offset:64848
	s_waitcnt lgkmcnt(1)
	v_fma_f32 v51, -v28, v52, v51
	v_fma_f32 v51, -v29, v53, v51
	v_fma_f32 v51, -v30, v54, v51
	v_fma_f32 v51, -v31, v55, v51
	ds_read_b128 v[52:55], v3 offset:64864
	s_waitcnt lgkmcnt(1)
	v_fma_f32 v51, -v32, v56, v51
	v_fma_f32 v51, -v33, v57, v51
	v_fma_f32 v51, -v35, v58, v51
	v_fma_f32 v51, -v36, v59, v51
	ds_read_b128 v[56:59], v3 offset:64880
	s_waitcnt lgkmcnt(1)
	v_fma_f32 v51, -v37, v52, v51
	v_fma_f32 v51, -v38, v53, v51
	v_fma_f32 v51, -v39, v54, v51
	v_fma_f32 v51, -v40, v55, v51
	ds_read_b128 v[52:55], v3 offset:64896
	s_waitcnt lgkmcnt(1)
	v_fma_f32 v51, -v41, v56, v51
	v_fma_f32 v51, -v42, v57, v51
	v_fma_f32 v51, -v43, v58, v51
	v_fma_f32 v51, -v44, v59, v51
	ds_read_b128 v[56:59], v3 offset:64912
	s_waitcnt lgkmcnt(1)
	v_fma_f32 v3, -v45, v52, v51
	v_fma_f32 v3, -v46, v53, v3
	v_fma_f32 v3, -v47, v54, v3
	v_fma_f32 v3, -v48, v55, v3
	s_waitcnt lgkmcnt(0)
	v_fma_f32 v3, -v49, v56, v3
	v_fma_f32 v51, -v50, v57, v3
	v_fmac_f32_e32 v51, 0x80000000, v58
	v_fmac_f32_e32 v51, 0x80000000, v59
	ds_read_u16 v53, v2 offset:12784
	v_lshlrev_b32_e32 v3, 2, v0
	v_add_u32_e32 v52, s0, v3
	ds_read2_b32 v[56:57], v52 offset0:47 offset1:111
	v_add_u32_e32 v3, 32, v3
	s_waitcnt lgkmcnt(0)
	v_mul_f32_e32 v52, 0x3fb8aa3b, v57
	v_exp_f32_e32 v52, v52
	v_lshlrev_b32_e32 v57, 16, v53
	v_mul_f32_e32 v69, v56, v57
	v_cndmask_b32_e64 v68, v52, 1.0, vcc
	ds_read_b128 v[52:55], v3 offset:65008
	ds_read_b128 v[56:59], v3 offset:65024
	ds_read_b128 v[60:63], v3 offset:65040
	ds_read_b128 v[64:67], v3 offset:65056
	s_waitcnt lgkmcnt(3)
	v_mul_f32_e32 v52, v4, v52
	v_fma_f32 v52, v68, v69, -v52
	v_fma_f32 v52, -v5, v53, v52
	v_fma_f32 v52, -v6, v54, v52
	v_fma_f32 v52, -v7, v55, v52
	s_waitcnt lgkmcnt(2)
	v_fma_f32 v52, -v8, v56, v52
	v_fma_f32 v52, -v9, v57, v52
	v_fma_f32 v52, -v10, v58, v52
	v_fma_f32 v52, -v11, v59, v52
	s_waitcnt lgkmcnt(1)
	v_fma_f32 v52, -v12, v60, v52
	v_fma_f32 v52, -v13, v61, v52
	v_fma_f32 v52, -v14, v62, v52
	v_fma_f32 v52, -v15, v63, v52
	s_waitcnt lgkmcnt(0)
	v_fma_f32 v56, -v16, v64, v52
	ds_read_b128 v[52:55], v3 offset:65072
	v_fma_f32 v56, -v17, v65, v56
	v_fma_f32 v56, -v18, v66, v56
	v_fma_f32 v60, -v19, v67, v56
	ds_read_b128 v[56:59], v3 offset:65088
	s_waitcnt lgkmcnt(1)
	v_fma_f32 v52, -v20, v52, v60
	v_fma_f32 v52, -v21, v53, v52
	v_fma_f32 v52, -v22, v54, v52
	v_fma_f32 v52, -v23, v55, v52
	s_waitcnt lgkmcnt(0)
	v_fma_f32 v56, -v24, v56, v52
	ds_read_b128 v[52:55], v3 offset:65104
	v_fma_f32 v56, -v25, v57, v56
	v_fma_f32 v56, -v26, v58, v56
	v_fma_f32 v60, -v27, v59, v56
	ds_read_b128 v[56:59], v3 offset:65120
	s_waitcnt lgkmcnt(1)
	v_fma_f32 v52, -v28, v52, v60
	v_fma_f32 v52, -v29, v53, v52
	v_fma_f32 v52, -v30, v54, v52
	v_fma_f32 v52, -v31, v55, v52
	s_waitcnt lgkmcnt(0)
	v_fma_f32 v56, -v32, v56, v52
	ds_read_b128 v[52:55], v3 offset:65136
	v_fma_f32 v56, -v33, v57, v56
	v_fma_f32 v56, -v35, v58, v56
	v_fma_f32 v60, -v36, v59, v56
	ds_read_b128 v[56:59], v3 offset:65152
	s_waitcnt lgkmcnt(1)
	v_fma_f32 v52, -v37, v52, v60
	v_fma_f32 v52, -v38, v53, v52
	v_fma_f32 v52, -v39, v54, v52
	v_fma_f32 v52, -v40, v55, v52
	s_waitcnt lgkmcnt(0)
	v_fma_f32 v56, -v41, v56, v52
	ds_read_b128 v[52:55], v3 offset:65168
	v_fma_f32 v56, -v42, v57, v56
	v_fma_f32 v56, -v43, v58, v56
	v_fma_f32 v60, -v44, v59, v56
	ds_read_b128 v[56:59], v3 offset:65184
	s_waitcnt lgkmcnt(1)
	v_fma_f32 v3, -v45, v52, v60
	v_fma_f32 v3, -v46, v53, v3
	v_fma_f32 v3, -v47, v54, v3
	v_fma_f32 v3, -v48, v55, v3
	s_waitcnt lgkmcnt(0)
; DEVI float bf2f(bf16_t b) { return __uint_as_float(((unsigned)b) << 16); }
; DEVI void prep_item(const Params& p, int j, int n, int h, char* smem) {
;     ...
;     for (int i = 0; i < 64; ++i) {
;       const float* amz = am + zero;
;       const float* sbz = sbeta + zero;
;       const float eg = __expf(sbz[64 + i]);
;       float acc = bf2f(*(const unsigned short*)(src + i * 272)) * sbz[i] * (isu ? 1.0f : eg);
; #pragma unroll
;       for (int j4 = 0; j4 < (i + 3) / 4; ++j4) {
;         const f32x4 a = *(const f32x4*)(amz + i * 68 + j4 * 4);
;         acc -= a[0] * x[j4 * 4 + 0];
;         acc -= a[1] * x[j4 * 4 + 1];
;         acc -= a[2] * x[j4 * 4 + 2];
;         acc -= a[3] * x[j4 * 4 + 3];
;       }
;       asm volatile("" : "+v"(zero), "+v"(acc));
;       x[i] = acc;
;     }
	v_fma_f32 v3, -v49, v56, v3
	v_fma_f32 v3, -v50, v57, v3
	v_fma_f32 v52, -v51, v58, v3
	v_fmac_f32_e32 v52, 0x80000000, v59
	ds_read_u16 v54, v2 offset:13056
	v_lshlrev_b32_e32 v3, 2, v0
	v_add_u32_e32 v53, s0, v3
	ds_read2_b32 v[58:59], v53 offset0:48 offset1:112
	v_add_u32_e32 v3, 32, v3
	s_waitcnt lgkmcnt(0)
	v_mul_f32_e32 v53, 0x3fb8aa3b, v59
	v_lshlrev_b32_e32 v59, 16, v54
	ds_read_b128 v[54:57], v3 offset:65280
	v_exp_f32_e32 v53, v53
	v_mul_f32_e32 v70, v58, v59
	ds_read_b128 v[58:61], v3 offset:65296
	ds_read_b128 v[62:65], v3 offset:65312
	ds_read_b128 v[66:69], v3 offset:65328
	v_cndmask_b32_e64 v53, v53, 1.0, vcc
	s_waitcnt lgkmcnt(3)
	v_mul_f32_e32 v54, v4, v54
	v_fma_f32 v53, v53, v70, -v54
	v_fma_f32 v53, -v5, v55, v53
	v_fma_f32 v53, -v6, v56, v53
	v_fma_f32 v53, -v7, v57, v53
	s_waitcnt lgkmcnt(2)
	v_fma_f32 v53, -v8, v58, v53
	v_fma_f32 v53, -v9, v59, v53
	v_fma_f32 v53, -v10, v60, v53
	v_fma_f32 v53, -v11, v61, v53
	s_waitcnt lgkmcnt(1)
	v_fma_f32 v53, -v12, v62, v53
	v_fma_f32 v53, -v13, v63, v53
	v_fma_f32 v53, -v14, v64, v53
	v_fma_f32 v53, -v15, v65, v53
	ds_read_b128 v[54:57], v3 offset:65344
	s_waitcnt lgkmcnt(1)
	v_fma_f32 v53, -v16, v66, v53
	v_fma_f32 v53, -v17, v67, v53
	v_fma_f32 v53, -v18, v68, v53
	v_fma_f32 v53, -v19, v69, v53
	ds_read_b128 v[58:61], v3 offset:65360
	s_waitcnt lgkmcnt(1)
	v_fma_f32 v53, -v20, v54, v53
	v_fma_f32 v53, -v21, v55, v53
	v_fma_f32 v53, -v22, v56, v53
	v_fma_f32 v53, -v23, v57, v53
	ds_read_b128 v[54:57], v3 offset:65376
	s_waitcnt lgkmcnt(1)
	v_fma_f32 v53, -v24, v58, v53
	v_fma_f32 v53, -v25, v59, v53
	v_fma_f32 v53, -v26, v60, v53
	v_fma_f32 v53, -v27, v61, v53
	ds_read_b128 v[58:61], v3 offset:65392
	s_waitcnt lgkmcnt(1)
	v_fma_f32 v53, -v28, v54, v53
	v_fma_f32 v53, -v29, v55, v53
	v_fma_f32 v53, -v30, v56, v53
	v_fma_f32 v53, -v31, v57, v53
	ds_read_b128 v[54:57], v3 offset:65408
	s_waitcnt lgkmcnt(1)
	v_fma_f32 v53, -v32, v58, v53
	v_fma_f32 v53, -v33, v59, v53
	v_fma_f32 v53, -v35, v60, v53
	v_fma_f32 v53, -v36, v61, v53
	ds_read_b128 v[58:61], v3 offset:65424
	s_waitcnt lgkmcnt(1)
	v_fma_f32 v53, -v37, v54, v53
	v_fma_f32 v53, -v38, v55, v53
	v_fma_f32 v53, -v39, v56, v53
	v_fma_f32 v53, -v40, v57, v53
	ds_read_b128 v[54:57], v3 offset:65440
	s_waitcnt lgkmcnt(1)
	v_fma_f32 v53, -v41, v58, v53
	v_fma_f32 v53, -v42, v59, v53
	v_fma_f32 v53, -v43, v60, v53
	v_fma_f32 v53, -v44, v61, v53
	ds_read_b128 v[58:61], v3 offset:65456
	s_waitcnt lgkmcnt(1)
	v_fma_f32 v3, -v45, v54, v53
	v_fma_f32 v3, -v46, v55, v3
	v_fma_f32 v3, -v47, v56, v3
	v_fma_f32 v3, -v48, v57, v3
	s_waitcnt lgkmcnt(0)
	v_fma_f32 v3, -v49, v58, v3
	v_fma_f32 v3, -v50, v59, v3
	v_fma_f32 v3, -v51, v60, v3
	v_fma_f32 v53, -v52, v61, v3
	ds_read_u16 v55, v2 offset:13328
	v_lshlrev_b32_e32 v3, 2, v0
	v_add_u32_e32 v54, s0, v3
	ds_read2_b32 v[58:59], v54 offset0:49 offset1:113
	v_add_u32_e32 v3, 32, v3
	v_add_u32_e32 v3, 0xcc00, v3
	s_waitcnt lgkmcnt(0)
	v_mul_f32_e32 v54, 0x3fb8aa3b, v59
	v_exp_f32_e32 v54, v54
	v_lshlrev_b32_e32 v59, 16, v55
	v_mul_f32_e32 v71, v58, v59
	v_cndmask_b32_e64 v70, v54, 1.0, vcc
	ds_read_b128 v[54:57], v3 offset:13328
	ds_read_b128 v[58:61], v3 offset:13344
	ds_read_b128 v[62:65], v3 offset:13360
	ds_read_b128 v[66:69], v3 offset:13376
	s_waitcnt lgkmcnt(3)
	v_mul_f32_e32 v54, v4, v54
	v_fma_f32 v54, v70, v71, -v54
	v_fma_f32 v54, -v5, v55, v54
	v_fma_f32 v54, -v6, v56, v54
	v_fma_f32 v54, -v7, v57, v54
	s_waitcnt lgkmcnt(2)
	v_fma_f32 v54, -v8, v58, v54
	v_fma_f32 v54, -v9, v59, v54
	v_fma_f32 v54, -v10, v60, v54
	v_fma_f32 v54, -v11, v61, v54
	s_waitcnt lgkmcnt(1)
	v_fma_f32 v54, -v12, v62, v54
	v_fma_f32 v54, -v13, v63, v54
	v_fma_f32 v54, -v14, v64, v54
	v_fma_f32 v54, -v15, v65, v54
	s_waitcnt lgkmcnt(0)
	v_fma_f32 v58, -v16, v66, v54
	ds_read_b128 v[54:57], v3 offset:13392
	v_fma_f32 v58, -v17, v67, v58
	v_fma_f32 v58, -v18, v68, v58
	v_fma_f32 v62, -v19, v69, v58
	ds_read_b128 v[58:61], v3 offset:13408
	s_waitcnt lgkmcnt(1)
	v_fma_f32 v54, -v20, v54, v62
	v_fma_f32 v54, -v21, v55, v54
	v_fma_f32 v54, -v22, v56, v54
	v_fma_f32 v54, -v23, v57, v54
	s_waitcnt lgkmcnt(0)
	v_fma_f32 v58, -v24, v58, v54
	ds_read_b128 v[54:57], v3 offset:13424
	v_fma_f32 v58, -v25, v59, v58
	v_fma_f32 v58, -v26, v60, v58
	v_fma_f32 v62, -v27, v61, v58
	ds_read_b128 v[58:61], v3 offset:13440
	s_waitcnt lgkmcnt(1)
	v_fma_f32 v54, -v28, v54, v62
	v_fma_f32 v54, -v29, v55, v54
	v_fma_f32 v54, -v30, v56, v54
	v_fma_f32 v54, -v31, v57, v54
	s_waitcnt lgkmcnt(0)
	v_fma_f32 v58, -v32, v58, v54
	ds_read_b128 v[54:57], v3 offset:13456
	v_fma_f32 v58, -v33, v59, v58
	v_fma_f32 v58, -v35, v60, v58
	v_fma_f32 v62, -v36, v61, v58
	ds_read_b128 v[58:61], v3 offset:13472
	s_waitcnt lgkmcnt(1)
	v_fma_f32 v54, -v37, v54, v62
	v_fma_f32 v54, -v38, v55, v54
	v_fma_f32 v54, -v39, v56, v54
	v_fma_f32 v54, -v40, v57, v54
	s_waitcnt lgkmcnt(0)
	v_fma_f32 v58, -v41, v58, v54
	ds_read_b128 v[54:57], v3 offset:13488
	v_fma_f32 v58, -v42, v59, v58
	v_fma_f32 v58, -v43, v60, v58
	v_fma_f32 v62, -v44, v61, v58
	ds_read_b128 v[58:61], v3 offset:13504
	s_waitcnt lgkmcnt(1)
	v_fma_f32 v54, -v45, v54, v62
	v_fma_f32 v54, -v46, v55, v54
	v_fma_f32 v54, -v47, v56, v54
	v_fma_f32 v62, -v48, v57, v54
	ds_read_b128 v[54:57], v3 offset:13520
	s_waitcnt lgkmcnt(1)
	v_fma_f32 v3, -v49, v58, v62
	v_fma_f32 v3, -v50, v59, v3
	v_fma_f32 v3, -v51, v60, v3
	v_fma_f32 v3, -v52, v61, v3
	s_waitcnt lgkmcnt(0)
	v_fma_f32 v54, -v53, v54, v3
	v_fmac_f32_e32 v54, 0x80000000, v55
	v_fmac_f32_e32 v54, 0x80000000, v56
	v_fmac_f32_e32 v54, 0x80000000, v57
	ds_read_u16 v56, v2 offset:13600
	v_lshlrev_b32_e32 v3, 2, v0
	v_add_u32_e32 v55, s0, v3
	ds_read2_b32 v[60:61], v55 offset0:50 offset1:114
	v_add_u32_e32 v3, 32, v3
	v_add_u32_e32 v3, 0xcc00, v3
	s_waitcnt lgkmcnt(0)
; DEVI float bf2f(bf16_t b) { return __uint_as_float(((unsigned)b) << 16); }
; DEVI void prep_item(const Params& p, int j, int n, int h, char* smem) {
;     ...
; #pragma unroll
;     for (int i = 0; i < 64; ++i) {
;       const float* amz = am + zero;
;       const float* sbz = sbeta + zero;
;       const float eg = __expf(sbz[64 + i]);
;       float acc = bf2f(*(const unsigned short*)(src + i * 272)) * sbz[i] * (isu ? 1.0f : eg);
; #pragma unroll
;       for (int j4 = 0; j4 < (i + 3) / 4; ++j4) {
;         const f32x4 a = *(const f32x4*)(amz + i * 68 + j4 * 4);
;         acc -= a[0] * x[j4 * 4 + 0];
;         acc -= a[1] * x[j4 * 4 + 1];
;         acc -= a[2] * x[j4 * 4 + 2];
;         acc -= a[3] * x[j4 * 4 + 3];
;       }
;       asm volatile("" : "+v"(zero), "+v"(acc));
;       x[i] = acc;
;     }
	v_mul_f32_e32 v55, 0x3fb8aa3b, v61
	v_lshlrev_b32_e32 v61, 16, v56
	ds_read_b128 v[56:59], v3 offset:13600
	v_exp_f32_e32 v55, v55
	v_mul_f32_e32 v72, v60, v61
	ds_read_b128 v[60:63], v3 offset:13616
	ds_read_b128 v[64:67], v3 offset:13632
	ds_read_b128 v[68:71], v3 offset:13648
	v_cndmask_b32_e64 v55, v55, 1.0, vcc
	s_waitcnt lgkmcnt(3)
	v_mul_f32_e32 v56, v4, v56
	v_fma_f32 v55, v55, v72, -v56
	v_fma_f32 v55, -v5, v57, v55
	v_fma_f32 v55, -v6, v58, v55
	v_fma_f32 v55, -v7, v59, v55
	s_waitcnt lgkmcnt(2)
	v_fma_f32 v55, -v8, v60, v55
	v_fma_f32 v55, -v9, v61, v55
	v_fma_f32 v55, -v10, v62, v55
	v_fma_f32 v55, -v11, v63, v55
	s_waitcnt lgkmcnt(1)
	v_fma_f32 v55, -v12, v64, v55
	v_fma_f32 v55, -v13, v65, v55
	v_fma_f32 v55, -v14, v66, v55
	v_fma_f32 v55, -v15, v67, v55
	ds_read_b128 v[56:59], v3 offset:13664
	s_waitcnt lgkmcnt(1)
	v_fma_f32 v55, -v16, v68, v55
	v_fma_f32 v55, -v17, v69, v55
	v_fma_f32 v55, -v18, v70, v55
	v_fma_f32 v55, -v19, v71, v55
	ds_read_b128 v[60:63], v3 offset:13680
	s_waitcnt lgkmcnt(1)
	v_fma_f32 v55, -v20, v56, v55
	v_fma_f32 v55, -v21, v57, v55
	v_fma_f32 v55, -v22, v58, v55
	v_fma_f32 v55, -v23, v59, v55
	ds_read_b128 v[56:59], v3 offset:13696
	s_waitcnt lgkmcnt(1)
	v_fma_f32 v55, -v24, v60, v55
	v_fma_f32 v55, -v25, v61, v55
	v_fma_f32 v55, -v26, v62, v55
	v_fma_f32 v55, -v27, v63, v55
	ds_read_b128 v[60:63], v3 offset:13712
	s_waitcnt lgkmcnt(1)
	v_fma_f32 v55, -v28, v56, v55
	v_fma_f32 v55, -v29, v57, v55
	v_fma_f32 v55, -v30, v58, v55
	v_fma_f32 v55, -v31, v59, v55
	ds_read_b128 v[56:59], v3 offset:13728
	s_waitcnt lgkmcnt(1)
	v_fma_f32 v55, -v32, v60, v55
	v_fma_f32 v55, -v33, v61, v55
	v_fma_f32 v55, -v35, v62, v55
	v_fma_f32 v55, -v36, v63, v55
	ds_read_b128 v[60:63], v3 offset:13744
	s_waitcnt lgkmcnt(1)
	v_fma_f32 v55, -v37, v56, v55
	v_fma_f32 v55, -v38, v57, v55
	v_fma_f32 v55, -v39, v58, v55
	v_fma_f32 v55, -v40, v59, v55
	ds_read_b128 v[56:59], v3 offset:13760
	s_waitcnt lgkmcnt(1)
	v_fma_f32 v55, -v41, v60, v55
	v_fma_f32 v55, -v42, v61, v55
	v_fma_f32 v55, -v43, v62, v55
	v_fma_f32 v55, -v44, v63, v55
	ds_read_b128 v[60:63], v3 offset:13776
	s_waitcnt lgkmcnt(1)
	v_fma_f32 v55, -v45, v56, v55
	v_fma_f32 v55, -v46, v57, v55
	v_fma_f32 v55, -v47, v58, v55
	v_fma_f32 v55, -v48, v59, v55
	ds_read_b128 v[56:59], v3 offset:13792
	s_waitcnt lgkmcnt(1)
	v_fma_f32 v3, -v49, v60, v55
	v_fma_f32 v3, -v50, v61, v3
	v_fma_f32 v3, -v51, v62, v3
	v_fma_f32 v3, -v52, v63, v3
	s_waitcnt lgkmcnt(0)
	v_fma_f32 v3, -v53, v56, v3
	v_fma_f32 v55, -v54, v57, v3
	v_fmac_f32_e32 v55, 0x80000000, v58
	v_fmac_f32_e32 v55, 0x80000000, v59
	ds_read_u16 v57, v2 offset:13872
	v_lshlrev_b32_e32 v3, 2, v0
	v_add_u32_e32 v56, s0, v3
	ds_read2_b32 v[60:61], v56 offset0:51 offset1:115
	v_add_u32_e32 v3, 32, v3
	v_add_u32_e32 v3, 0xcc00, v3
	s_waitcnt lgkmcnt(0)
	v_mul_f32_e32 v56, 0x3fb8aa3b, v61
	v_exp_f32_e32 v56, v56
	v_lshlrev_b32_e32 v61, 16, v57
	v_mul_f32_e32 v73, v60, v61
	v_cndmask_b32_e64 v72, v56, 1.0, vcc
	ds_read_b128 v[56:59], v3 offset:13872
	ds_read_b128 v[60:63], v3 offset:13888
	ds_read_b128 v[64:67], v3 offset:13904
	ds_read_b128 v[68:71], v3 offset:13920
	s_waitcnt lgkmcnt(3)
	v_mul_f32_e32 v56, v4, v56
	v_fma_f32 v56, v72, v73, -v56
	v_fma_f32 v56, -v5, v57, v56
	v_fma_f32 v56, -v6, v58, v56
	v_fma_f32 v56, -v7, v59, v56
	s_waitcnt lgkmcnt(2)
	v_fma_f32 v56, -v8, v60, v56
	v_fma_f32 v56, -v9, v61, v56
	v_fma_f32 v56, -v10, v62, v56
	v_fma_f32 v56, -v11, v63, v56
	s_waitcnt lgkmcnt(1)
	v_fma_f32 v56, -v12, v64, v56
	v_fma_f32 v56, -v13, v65, v56
	v_fma_f32 v56, -v14, v66, v56
	v_fma_f32 v56, -v15, v67, v56
	s_waitcnt lgkmcnt(0)
	v_fma_f32 v60, -v16, v68, v56
	ds_read_b128 v[56:59], v3 offset:13936
	v_fma_f32 v60, -v17, v69, v60
	v_fma_f32 v60, -v18, v70, v60
	v_fma_f32 v64, -v19, v71, v60
	ds_read_b128 v[60:63], v3 offset:13952
	s_waitcnt lgkmcnt(1)
	v_fma_f32 v56, -v20, v56, v64
	v_fma_f32 v56, -v21, v57, v56
	v_fma_f32 v56, -v22, v58, v56
	v_fma_f32 v56, -v23, v59, v56
	s_waitcnt lgkmcnt(0)
	v_fma_f32 v60, -v24, v60, v56
	ds_read_b128 v[56:59], v3 offset:13968
	v_fma_f32 v60, -v25, v61, v60
	v_fma_f32 v60, -v26, v62, v60
	v_fma_f32 v64, -v27, v63, v60
	ds_read_b128 v[60:63], v3 offset:13984
	s_waitcnt lgkmcnt(1)
	v_fma_f32 v56, -v28, v56, v64
	v_fma_f32 v56, -v29, v57, v56
	v_fma_f32 v56, -v30, v58, v56
	v_fma_f32 v56, -v31, v59, v56
	s_waitcnt lgkmcnt(0)
	v_fma_f32 v60, -v32, v60, v56
	ds_read_b128 v[56:59], v3 offset:14000
	v_fma_f32 v60, -v33, v61, v60
	v_fma_f32 v60, -v35, v62, v60
	v_fma_f32 v64, -v36, v63, v60
	ds_read_b128 v[60:63], v3 offset:14016
	s_waitcnt lgkmcnt(1)
	v_fma_f32 v56, -v37, v56, v64
	v_fma_f32 v56, -v38, v57, v56
	v_fma_f32 v56, -v39, v58, v56
	v_fma_f32 v56, -v40, v59, v56
	s_waitcnt lgkmcnt(0)
	v_fma_f32 v60, -v41, v60, v56
	ds_read_b128 v[56:59], v3 offset:14032
	v_fma_f32 v60, -v42, v61, v60
	v_fma_f32 v60, -v43, v62, v60
	v_fma_f32 v64, -v44, v63, v60
	ds_read_b128 v[60:63], v3 offset:14048
	s_waitcnt lgkmcnt(1)
	v_fma_f32 v56, -v45, v56, v64
	v_fma_f32 v56, -v46, v57, v56
	v_fma_f32 v56, -v47, v58, v56
	v_fma_f32 v64, -v48, v59, v56
	ds_read_b128 v[56:59], v3 offset:14064
	s_waitcnt lgkmcnt(1)
	v_fma_f32 v3, -v49, v60, v64
	v_fma_f32 v3, -v50, v61, v3
	v_fma_f32 v3, -v51, v62, v3
	v_fma_f32 v3, -v52, v63, v3
	s_waitcnt lgkmcnt(0)
	v_fma_f32 v3, -v53, v56, v3
	v_fma_f32 v3, -v54, v57, v3
	v_fma_f32 v56, -v55, v58, v3
	v_fmac_f32_e32 v56, 0x80000000, v59
	ds_read_u16 v58, v2 offset:14144
	v_lshlrev_b32_e32 v3, 2, v0
	v_add_u32_e32 v57, s0, v3
	ds_read2_b32 v[62:63], v57 offset0:52 offset1:116
	v_add_u32_e32 v3, 32, v3
	v_add_u32_e32 v3, 0xcc00, v3
	s_waitcnt lgkmcnt(0)
; DEVI float bf2f(bf16_t b) { return __uint_as_float(((unsigned)b) << 16); }
; DEVI void prep_item(const Params& p, int j, int n, int h, char* smem) {
;     ...
; #pragma unroll
;     for (int i = 0; i < 64; ++i) {
;       const float* amz = am + zero;
;       const float* sbz = sbeta + zero;
;       const float eg = __expf(sbz[64 + i]);
;       float acc = bf2f(*(const unsigned short*)(src + i * 272)) * sbz[i] * (isu ? 1.0f : eg);
; #pragma unroll
;       for (int j4 = 0; j4 < (i + 3) / 4; ++j4) {
;         const f32x4 a = *(const f32x4*)(amz + i * 68 + j4 * 4);
;         acc -= a[0] * x[j4 * 4 + 0];
;         acc -= a[1] * x[j4 * 4 + 1];
;         acc -= a[2] * x[j4 * 4 + 2];
;         acc -= a[3] * x[j4 * 4 + 3];
;       }
;       asm volatile("" : "+v"(zero), "+v"(acc));
;       x[i] = acc;
;     }
	v_mul_f32_e32 v57, 0x3fb8aa3b, v63
	v_lshlrev_b32_e32 v63, 16, v58
	ds_read_b128 v[58:61], v3 offset:14144
	v_exp_f32_e32 v57, v57
	v_mul_f32_e32 v74, v62, v63
	ds_read_b128 v[62:65], v3 offset:14160
	ds_read_b128 v[66:69], v3 offset:14176
	ds_read_b128 v[70:73], v3 offset:14192
	v_cndmask_b32_e64 v57, v57, 1.0, vcc
	s_waitcnt lgkmcnt(3)
	v_mul_f32_e32 v58, v4, v58
	v_fma_f32 v57, v57, v74, -v58
	v_fma_f32 v57, -v5, v59, v57
	v_fma_f32 v57, -v6, v60, v57
	v_fma_f32 v57, -v7, v61, v57
	s_waitcnt lgkmcnt(2)
	v_fma_f32 v57, -v8, v62, v57
	v_fma_f32 v57, -v9, v63, v57
	v_fma_f32 v57, -v10, v64, v57
	v_fma_f32 v57, -v11, v65, v57
	s_waitcnt lgkmcnt(1)
	v_fma_f32 v57, -v12, v66, v57
	v_fma_f32 v57, -v13, v67, v57
	v_fma_f32 v57, -v14, v68, v57
	v_fma_f32 v57, -v15, v69, v57
	ds_read_b128 v[58:61], v3 offset:14208
	s_waitcnt lgkmcnt(1)
	v_fma_f32 v57, -v16, v70, v57
	v_fma_f32 v57, -v17, v71, v57
	v_fma_f32 v57, -v18, v72, v57
	v_fma_f32 v57, -v19, v73, v57
	ds_read_b128 v[62:65], v3 offset:14224
	s_waitcnt lgkmcnt(1)
	v_fma_f32 v57, -v20, v58, v57
	v_fma_f32 v57, -v21, v59, v57
	v_fma_f32 v57, -v22, v60, v57
	v_fma_f32 v57, -v23, v61, v57
	ds_read_b128 v[58:61], v3 offset:14240
	s_waitcnt lgkmcnt(1)
	v_fma_f32 v57, -v24, v62, v57
	v_fma_f32 v57, -v25, v63, v57
	v_fma_f32 v57, -v26, v64, v57
	v_fma_f32 v57, -v27, v65, v57
	ds_read_b128 v[62:65], v3 offset:14256
	s_waitcnt lgkmcnt(1)
	v_fma_f32 v57, -v28, v58, v57
	v_fma_f32 v57, -v29, v59, v57
	v_fma_f32 v57, -v30, v60, v57
	v_fma_f32 v57, -v31, v61, v57
	ds_read_b128 v[58:61], v3 offset:14272
	s_waitcnt lgkmcnt(1)
	v_fma_f32 v57, -v32, v62, v57
	v_fma_f32 v57, -v33, v63, v57
	v_fma_f32 v57, -v35, v64, v57
	v_fma_f32 v57, -v36, v65, v57
	ds_read_b128 v[62:65], v3 offset:14288
	s_waitcnt lgkmcnt(1)
	v_fma_f32 v57, -v37, v58, v57
	v_fma_f32 v57, -v38, v59, v57
	v_fma_f32 v57, -v39, v60, v57
	v_fma_f32 v57, -v40, v61, v57
	ds_read_b128 v[58:61], v3 offset:14304
	s_waitcnt lgkmcnt(1)
	v_fma_f32 v57, -v41, v62, v57
	v_fma_f32 v57, -v42, v63, v57
	v_fma_f32 v57, -v43, v64, v57
	v_fma_f32 v57, -v44, v65, v57
	ds_read_b128 v[62:65], v3 offset:14320
	s_waitcnt lgkmcnt(1)
	v_fma_f32 v57, -v45, v58, v57
	v_fma_f32 v57, -v46, v59, v57
	v_fma_f32 v57, -v47, v60, v57
	v_fma_f32 v57, -v48, v61, v57
	ds_read_b128 v[58:61], v3 offset:14336
	s_waitcnt lgkmcnt(1)
	v_fma_f32 v3, -v49, v62, v57
	v_fma_f32 v3, -v50, v63, v3
	v_fma_f32 v3, -v51, v64, v3
	v_fma_f32 v3, -v52, v65, v3
	s_waitcnt lgkmcnt(0)
	v_fma_f32 v3, -v53, v58, v3
	v_fma_f32 v3, -v54, v59, v3
	v_fma_f32 v3, -v55, v60, v3
	v_fma_f32 v57, -v56, v61, v3
	ds_read_u16 v59, v2 offset:14416
	v_lshlrev_b32_e32 v3, 2, v0
	v_add_u32_e32 v58, s0, v3
	ds_read2_b32 v[62:63], v58 offset0:53 offset1:117
	v_add_u32_e32 v3, 32, v3
	v_add_u32_e32 v3, 0xcc00, v3
	s_waitcnt lgkmcnt(0)
	v_mul_f32_e32 v58, 0x3fb8aa3b, v63
	v_exp_f32_e32 v58, v58
	v_lshlrev_b32_e32 v63, 16, v59
	v_mul_f32_e32 v75, v62, v63
	v_cndmask_b32_e64 v74, v58, 1.0, vcc
	ds_read_b128 v[58:61], v3 offset:14416
	ds_read_b128 v[62:65], v3 offset:14432
	ds_read_b128 v[66:69], v3 offset:14448
	ds_read_b128 v[70:73], v3 offset:14464
	s_waitcnt lgkmcnt(3)
	v_mul_f32_e32 v58, v4, v58
	v_fma_f32 v58, v74, v75, -v58
	v_fma_f32 v58, -v5, v59, v58
	v_fma_f32 v58, -v6, v60, v58
	v_fma_f32 v58, -v7, v61, v58
	s_waitcnt lgkmcnt(2)
	v_fma_f32 v58, -v8, v62, v58
	v_fma_f32 v58, -v9, v63, v58
	v_fma_f32 v58, -v10, v64, v58
	v_fma_f32 v58, -v11, v65, v58
	s_waitcnt lgkmcnt(1)
	v_fma_f32 v58, -v12, v66, v58
	v_fma_f32 v58, -v13, v67, v58
	v_fma_f32 v58, -v14, v68, v58
	v_fma_f32 v58, -v15, v69, v58
	s_waitcnt lgkmcnt(0)
	v_fma_f32 v62, -v16, v70, v58
	ds_read_b128 v[58:61], v3 offset:14480
	v_fma_f32 v62, -v17, v71, v62
	v_fma_f32 v62, -v18, v72, v62
	v_fma_f32 v66, -v19, v73, v62
	ds_read_b128 v[62:65], v3 offset:14496
	s_waitcnt lgkmcnt(1)
	v_fma_f32 v58, -v20, v58, v66
	v_fma_f32 v58, -v21, v59, v58
	v_fma_f32 v58, -v22, v60, v58
	v_fma_f32 v58, -v23, v61, v58
	s_waitcnt lgkmcnt(0)
	v_fma_f32 v62, -v24, v62, v58
	ds_read_b128 v[58:61], v3 offset:14512
	v_fma_f32 v62, -v25, v63, v62
	v_fma_f32 v62, -v26, v64, v62
	v_fma_f32 v66, -v27, v65, v62
	ds_read_b128 v[62:65], v3 offset:14528
	s_waitcnt lgkmcnt(1)
	v_fma_f32 v58, -v28, v58, v66
	v_fma_f32 v58, -v29, v59, v58
	v_fma_f32 v58, -v30, v60, v58
	v_fma_f32 v58, -v31, v61, v58
	s_waitcnt lgkmcnt(0)
	v_fma_f32 v62, -v32, v62, v58
	ds_read_b128 v[58:61], v3 offset:14544
	v_fma_f32 v62, -v33, v63, v62
	v_fma_f32 v62, -v35, v64, v62
	v_fma_f32 v66, -v36, v65, v62
	ds_read_b128 v[62:65], v3 offset:14560
	s_waitcnt lgkmcnt(1)
	v_fma_f32 v58, -v37, v58, v66
	v_fma_f32 v58, -v38, v59, v58
	v_fma_f32 v58, -v39, v60, v58
	v_fma_f32 v58, -v40, v61, v58
	s_waitcnt lgkmcnt(0)
	v_fma_f32 v62, -v41, v62, v58
	ds_read_b128 v[58:61], v3 offset:14576
	v_fma_f32 v62, -v42, v63, v62
	v_fma_f32 v62, -v43, v64, v62
	v_fma_f32 v66, -v44, v65, v62
	ds_read_b128 v[62:65], v3 offset:14592
	s_waitcnt lgkmcnt(1)
	v_fma_f32 v58, -v45, v58, v66
	v_fma_f32 v58, -v46, v59, v58
	v_fma_f32 v58, -v47, v60, v58
	v_fma_f32 v58, -v48, v61, v58
	s_waitcnt lgkmcnt(0)
	v_fma_f32 v62, -v49, v62, v58
	ds_read_b128 v[58:61], v3 offset:14608
	v_fma_f32 v62, -v50, v63, v62
	v_fma_f32 v62, -v51, v64, v62
	v_fma_f32 v66, -v52, v65, v62
	ds_read_b128 v[62:65], v3 offset:14624
	s_waitcnt lgkmcnt(1)
	v_fma_f32 v3, -v53, v58, v66
	v_fma_f32 v3, -v54, v59, v3
	v_fma_f32 v3, -v55, v60, v3
	v_fma_f32 v3, -v56, v61, v3
	s_waitcnt lgkmcnt(0)
; DEVI float bf2f(bf16_t b) { return __uint_as_float(((unsigned)b) << 16); }
; DEVI void prep_item(const Params& p, int j, int n, int h, char* smem) {
;     ...
; #pragma unroll
;     for (int i = 0; i < 64; ++i) {
;       const float* amz = am + zero;
;       const float* sbz = sbeta + zero;
;       const float eg = __expf(sbz[64 + i]);
;       float acc = bf2f(*(const unsigned short*)(src + i * 272)) * sbz[i] * (isu ? 1.0f : eg);
; #pragma unroll
;       for (int j4 = 0; j4 < (i + 3) / 4; ++j4) {
;         const f32x4 a = *(const f32x4*)(amz + i * 68 + j4 * 4);
;         acc -= a[0] * x[j4 * 4 + 0];
;         acc -= a[1] * x[j4 * 4 + 1];
;         acc -= a[2] * x[j4 * 4 + 2];
;         acc -= a[3] * x[j4 * 4 + 3];
;       }
;       asm volatile("" : "+v"(zero), "+v"(acc));
;       x[i] = acc;
;     }
	v_fma_f32 v58, -v57, v62, v3
	v_fmac_f32_e32 v58, 0x80000000, v63
	v_fmac_f32_e32 v58, 0x80000000, v64
	v_fmac_f32_e32 v58, 0x80000000, v65
	ds_read_u16 v60, v2 offset:14688
	v_lshlrev_b32_e32 v3, 2, v0
	v_add_u32_e32 v59, s0, v3
	ds_read2_b32 v[64:65], v59 offset0:54 offset1:118
	v_add_u32_e32 v3, 32, v3
	v_add_u32_e32 v3, 0xcc00, v3
	s_waitcnt lgkmcnt(0)
	v_mul_f32_e32 v59, 0x3fb8aa3b, v65
	v_lshlrev_b32_e32 v65, 16, v60
	ds_read_b128 v[60:63], v3 offset:14688
	v_exp_f32_e32 v59, v59
	v_mul_f32_e32 v76, v64, v65
	ds_read_b128 v[64:67], v3 offset:14704
	ds_read_b128 v[68:71], v3 offset:14720
	ds_read_b128 v[72:75], v3 offset:14736
	v_cndmask_b32_e64 v59, v59, 1.0, vcc
	s_waitcnt lgkmcnt(3)
	v_mul_f32_e32 v60, v4, v60
	v_fma_f32 v59, v59, v76, -v60
	v_fma_f32 v59, -v5, v61, v59
	v_fma_f32 v59, -v6, v62, v59
	v_fma_f32 v59, -v7, v63, v59
	s_waitcnt lgkmcnt(2)
	v_fma_f32 v59, -v8, v64, v59
	v_fma_f32 v59, -v9, v65, v59
	v_fma_f32 v59, -v10, v66, v59
	v_fma_f32 v59, -v11, v67, v59
	s_waitcnt lgkmcnt(1)
	v_fma_f32 v59, -v12, v68, v59
	v_fma_f32 v59, -v13, v69, v59
	v_fma_f32 v59, -v14, v70, v59
	v_fma_f32 v59, -v15, v71, v59
	ds_read_b128 v[60:63], v3 offset:14752
	s_waitcnt lgkmcnt(1)
	v_fma_f32 v59, -v16, v72, v59
	v_fma_f32 v59, -v17, v73, v59
	v_fma_f32 v59, -v18, v74, v59
	v_fma_f32 v59, -v19, v75, v59
	ds_read_b128 v[64:67], v3 offset:14768
	s_waitcnt lgkmcnt(1)
	v_fma_f32 v59, -v20, v60, v59
	v_fma_f32 v59, -v21, v61, v59
	v_fma_f32 v59, -v22, v62, v59
	v_fma_f32 v59, -v23, v63, v59
	ds_read_b128 v[60:63], v3 offset:14784
	s_waitcnt lgkmcnt(1)
	v_fma_f32 v59, -v24, v64, v59
	v_fma_f32 v59, -v25, v65, v59
	v_fma_f32 v59, -v26, v66, v59
	v_fma_f32 v59, -v27, v67, v59
	ds_read_b128 v[64:67], v3 offset:14800
	s_waitcnt lgkmcnt(1)
	v_fma_f32 v59, -v28, v60, v59
	v_fma_f32 v59, -v29, v61, v59
	v_fma_f32 v59, -v30, v62, v59
	v_fma_f32 v59, -v31, v63, v59
	ds_read_b128 v[60:63], v3 offset:14816
	s_waitcnt lgkmcnt(1)
	v_fma_f32 v59, -v32, v64, v59
	v_fma_f32 v59, -v33, v65, v59
	v_fma_f32 v59, -v35, v66, v59
	v_fma_f32 v59, -v36, v67, v59
	ds_read_b128 v[64:67], v3 offset:14832
	s_waitcnt lgkmcnt(1)
	v_fma_f32 v59, -v37, v60, v59
	v_fma_f32 v59, -v38, v61, v59
	v_fma_f32 v59, -v39, v62, v59
	v_fma_f32 v59, -v40, v63, v59
	ds_read_b128 v[60:63], v3 offset:14848
	s_waitcnt lgkmcnt(1)
	v_fma_f32 v59, -v41, v64, v59
	v_fma_f32 v59, -v42, v65, v59
	v_fma_f32 v59, -v43, v66, v59
	v_fma_f32 v59, -v44, v67, v59
	ds_read_b128 v[64:67], v3 offset:14864
	s_waitcnt lgkmcnt(1)
	v_fma_f32 v59, -v45, v60, v59
	v_fma_f32 v59, -v46, v61, v59
	v_fma_f32 v59, -v47, v62, v59
	v_fma_f32 v59, -v48, v63, v59
	ds_read_b128 v[60:63], v3 offset:14880
	s_waitcnt lgkmcnt(1)
	v_fma_f32 v59, -v49, v64, v59
	v_fma_f32 v59, -v50, v65, v59
	v_fma_f32 v59, -v51, v66, v59
	v_fma_f32 v59, -v52, v67, v59
	ds_read_b128 v[64:67], v3 offset:14896
	s_waitcnt lgkmcnt(1)
	v_fma_f32 v3, -v53, v60, v59
	v_fma_f32 v3, -v54, v61, v3
	v_fma_f32 v3, -v55, v62, v3
	v_fma_f32 v3, -v56, v63, v3
	s_waitcnt lgkmcnt(0)
	v_fma_f32 v3, -v57, v64, v3
	v_fma_f32 v59, -v58, v65, v3
	v_fmac_f32_e32 v59, 0x80000000, v66
	v_fmac_f32_e32 v59, 0x80000000, v67
	ds_read_u16 v61, v2 offset:14960
	v_lshlrev_b32_e32 v3, 2, v0
	v_add_u32_e32 v60, s0, v3
	ds_read2_b32 v[64:65], v60 offset0:55 offset1:119
	v_add_u32_e32 v3, 32, v3
	v_add_u32_e32 v3, 0xcc00, v3
	s_waitcnt lgkmcnt(0)
	v_mul_f32_e32 v60, 0x3fb8aa3b, v65
	v_exp_f32_e32 v60, v60
	v_lshlrev_b32_e32 v65, 16, v61
	v_mul_f32_e32 v77, v64, v65
	v_cndmask_b32_e64 v76, v60, 1.0, vcc
	ds_read_b128 v[60:63], v3 offset:14960
	ds_read_b128 v[64:67], v3 offset:14976
	ds_read_b128 v[68:71], v3 offset:14992
	ds_read_b128 v[72:75], v3 offset:15008
	s_waitcnt lgkmcnt(3)
	v_mul_f32_e32 v60, v4, v60
	v_fma_f32 v60, v76, v77, -v60
	v_fma_f32 v60, -v5, v61, v60
	v_fma_f32 v60, -v6, v62, v60
	v_fma_f32 v60, -v7, v63, v60
	s_waitcnt lgkmcnt(2)
	v_fma_f32 v60, -v8, v64, v60
	v_fma_f32 v60, -v9, v65, v60
	v_fma_f32 v60, -v10, v66, v60
	v_fma_f32 v60, -v11, v67, v60
	s_waitcnt lgkmcnt(1)
	v_fma_f32 v60, -v12, v68, v60
	v_fma_f32 v60, -v13, v69, v60
	v_fma_f32 v60, -v14, v70, v60
	v_fma_f32 v60, -v15, v71, v60
	s_waitcnt lgkmcnt(0)
	v_fma_f32 v64, -v16, v72, v60
	ds_read_b128 v[60:63], v3 offset:15024
	v_fma_f32 v64, -v17, v73, v64
	v_fma_f32 v64, -v18, v74, v64
	v_fma_f32 v68, -v19, v75, v64
	ds_read_b128 v[64:67], v3 offset:15040
	s_waitcnt lgkmcnt(1)
	v_fma_f32 v60, -v20, v60, v68
	v_fma_f32 v60, -v21, v61, v60
	v_fma_f32 v60, -v22, v62, v60
	v_fma_f32 v60, -v23, v63, v60
	s_waitcnt lgkmcnt(0)
	v_fma_f32 v64, -v24, v64, v60
	ds_read_b128 v[60:63], v3 offset:15056
	v_fma_f32 v64, -v25, v65, v64
	v_fma_f32 v64, -v26, v66, v64
	v_fma_f32 v68, -v27, v67, v64
	ds_read_b128 v[64:67], v3 offset:15072
	s_waitcnt lgkmcnt(1)
	v_fma_f32 v60, -v28, v60, v68
	v_fma_f32 v60, -v29, v61, v60
	v_fma_f32 v60, -v30, v62, v60
	v_fma_f32 v60, -v31, v63, v60
	s_waitcnt lgkmcnt(0)
	v_fma_f32 v64, -v32, v64, v60
	ds_read_b128 v[60:63], v3 offset:15088
	v_fma_f32 v64, -v33, v65, v64
	v_fma_f32 v64, -v35, v66, v64
	v_fma_f32 v68, -v36, v67, v64
	ds_read_b128 v[64:67], v3 offset:15104
	s_waitcnt lgkmcnt(1)
	v_fma_f32 v60, -v37, v60, v68
	v_fma_f32 v60, -v38, v61, v60
	v_fma_f32 v60, -v39, v62, v60
	v_fma_f32 v60, -v40, v63, v60
	s_waitcnt lgkmcnt(0)
	v_fma_f32 v64, -v41, v64, v60
	ds_read_b128 v[60:63], v3 offset:15120
	v_fma_f32 v64, -v42, v65, v64
	v_fma_f32 v64, -v43, v66, v64
	v_fma_f32 v68, -v44, v67, v64
	ds_read_b128 v[64:67], v3 offset:15136
	s_waitcnt lgkmcnt(1)
	v_fma_f32 v60, -v45, v60, v68
	v_fma_f32 v60, -v46, v61, v60
	v_fma_f32 v60, -v47, v62, v60
	v_fma_f32 v60, -v48, v63, v60
	s_waitcnt lgkmcnt(0)
; DEVI float bf2f(bf16_t b) { return __uint_as_float(((unsigned)b) << 16); }
; DEVI void prep_item(const Params& p, int j, int n, int h, char* smem) {
;     ...
; #pragma unroll
;     for (int i = 0; i < 64; ++i) {
;       const float* amz = am + zero;
;       const float* sbz = sbeta + zero;
;       const float eg = __expf(sbz[64 + i]);
;       float acc = bf2f(*(const unsigned short*)(src + i * 272)) * sbz[i] * (isu ? 1.0f : eg);
; #pragma unroll
;       for (int j4 = 0; j4 < (i + 3) / 4; ++j4) {
;         const f32x4 a = *(const f32x4*)(amz + i * 68 + j4 * 4);
;         acc -= a[0] * x[j4 * 4 + 0];
;         acc -= a[1] * x[j4 * 4 + 1];
;         acc -= a[2] * x[j4 * 4 + 2];
;         acc -= a[3] * x[j4 * 4 + 3];
;       }
;       asm volatile("" : "+v"(zero), "+v"(acc));
;       x[i] = acc;
;     }
	v_fma_f32 v64, -v49, v64, v60
	ds_read_b128 v[60:63], v3 offset:15152
	v_fma_f32 v64, -v50, v65, v64
	v_fma_f32 v64, -v51, v66, v64
	v_fma_f32 v68, -v52, v67, v64
	ds_read_b128 v[64:67], v3 offset:15168
	s_waitcnt lgkmcnt(1)
	v_fma_f32 v3, -v53, v60, v68
	v_fma_f32 v3, -v54, v61, v3
	v_fma_f32 v3, -v55, v62, v3
	v_fma_f32 v3, -v56, v63, v3
	s_waitcnt lgkmcnt(0)
	v_fma_f32 v3, -v57, v64, v3
	v_fma_f32 v3, -v58, v65, v3
	v_fma_f32 v60, -v59, v66, v3
	v_fmac_f32_e32 v60, 0x80000000, v67
	ds_read_u16 v62, v2 offset:15232
	v_lshlrev_b32_e32 v3, 2, v0
	v_add_u32_e32 v61, s0, v3
	ds_read2_b32 v[66:67], v61 offset0:56 offset1:120
	v_add_u32_e32 v3, 32, v3
	v_add_u32_e32 v3, 0xcc00, v3
	s_waitcnt lgkmcnt(0)
	v_mul_f32_e32 v61, 0x3fb8aa3b, v67
	v_lshlrev_b32_e32 v67, 16, v62
	ds_read_b128 v[62:65], v3 offset:15232
	v_exp_f32_e32 v61, v61
	v_mul_f32_e32 v78, v66, v67
	ds_read_b128 v[66:69], v3 offset:15248
	ds_read_b128 v[70:73], v3 offset:15264
	ds_read_b128 v[74:77], v3 offset:15280
	v_cndmask_b32_e64 v61, v61, 1.0, vcc
	s_waitcnt lgkmcnt(3)
	v_mul_f32_e32 v62, v4, v62
	v_fma_f32 v61, v61, v78, -v62
	v_fma_f32 v61, -v5, v63, v61
	v_fma_f32 v61, -v6, v64, v61
	v_fma_f32 v61, -v7, v65, v61
	s_waitcnt lgkmcnt(2)
	v_fma_f32 v61, -v8, v66, v61
	v_fma_f32 v61, -v9, v67, v61
	v_fma_f32 v61, -v10, v68, v61
	v_fma_f32 v61, -v11, v69, v61
	s_waitcnt lgkmcnt(1)
	v_fma_f32 v61, -v12, v70, v61
	v_fma_f32 v61, -v13, v71, v61
	v_fma_f32 v61, -v14, v72, v61
	v_fma_f32 v61, -v15, v73, v61
	ds_read_b128 v[62:65], v3 offset:15296
	s_waitcnt lgkmcnt(1)
	v_fma_f32 v61, -v16, v74, v61
	v_fma_f32 v61, -v17, v75, v61
	v_fma_f32 v61, -v18, v76, v61
	v_fma_f32 v61, -v19, v77, v61
	ds_read_b128 v[66:69], v3 offset:15312
	s_waitcnt lgkmcnt(1)
	v_fma_f32 v61, -v20, v62, v61
	v_fma_f32 v61, -v21, v63, v61
	v_fma_f32 v61, -v22, v64, v61
	v_fma_f32 v61, -v23, v65, v61
	ds_read_b128 v[62:65], v3 offset:15328
	s_waitcnt lgkmcnt(1)
	v_fma_f32 v61, -v24, v66, v61
	v_fma_f32 v61, -v25, v67, v61
	v_fma_f32 v61, -v26, v68, v61
	v_fma_f32 v61, -v27, v69, v61
	ds_read_b128 v[66:69], v3 offset:15344
	s_waitcnt lgkmcnt(1)
	v_fma_f32 v61, -v28, v62, v61
	v_fma_f32 v61, -v29, v63, v61
	v_fma_f32 v61, -v30, v64, v61
	v_fma_f32 v61, -v31, v65, v61
	ds_read_b128 v[62:65], v3 offset:15360
	s_waitcnt lgkmcnt(1)
	v_fma_f32 v61, -v32, v66, v61
	v_fma_f32 v61, -v33, v67, v61
	v_fma_f32 v61, -v35, v68, v61
	v_fma_f32 v61, -v36, v69, v61
	ds_read_b128 v[66:69], v3 offset:15376
	s_waitcnt lgkmcnt(1)
	v_fma_f32 v61, -v37, v62, v61
	v_fma_f32 v61, -v38, v63, v61
	v_fma_f32 v61, -v39, v64, v61
	v_fma_f32 v61, -v40, v65, v61
	ds_read_b128 v[62:65], v3 offset:15392
	s_waitcnt lgkmcnt(1)
	v_fma_f32 v61, -v41, v66, v61
	v_fma_f32 v61, -v42, v67, v61
	v_fma_f32 v61, -v43, v68, v61
	v_fma_f32 v61, -v44, v69, v61
	ds_read_b128 v[66:69], v3 offset:15408
	s_waitcnt lgkmcnt(1)
	v_fma_f32 v61, -v45, v62, v61
	v_fma_f32 v61, -v46, v63, v61
	v_fma_f32 v61, -v47, v64, v61
	v_fma_f32 v61, -v48, v65, v61
	ds_read_b128 v[62:65], v3 offset:15424
	s_waitcnt lgkmcnt(1)
	v_fma_f32 v61, -v49, v66, v61
	v_fma_f32 v61, -v50, v67, v61
	v_fma_f32 v61, -v51, v68, v61
	v_fma_f32 v61, -v52, v69, v61
	ds_read_b128 v[66:69], v3 offset:15440
	s_waitcnt lgkmcnt(1)
	v_fma_f32 v3, -v53, v62, v61
	v_fma_f32 v3, -v54, v63, v3
	v_fma_f32 v3, -v55, v64, v3
	v_fma_f32 v3, -v56, v65, v3
	s_waitcnt lgkmcnt(0)
	v_fma_f32 v3, -v57, v66, v3
	v_fma_f32 v3, -v58, v67, v3
	v_fma_f32 v3, -v59, v68, v3
	v_fma_f32 v61, -v60, v69, v3
	ds_read_u16 v63, v2 offset:15504
	v_lshlrev_b32_e32 v3, 2, v0
	v_add_u32_e32 v62, s0, v3
	ds_read2_b32 v[66:67], v62 offset0:57 offset1:121
	v_add_u32_e32 v3, 32, v3
	v_add_u32_e32 v3, 0xcc00, v3
	s_waitcnt lgkmcnt(0)
	v_mul_f32_e32 v62, 0x3fb8aa3b, v67
	v_exp_f32_e32 v62, v62
	v_lshlrev_b32_e32 v67, 16, v63
	v_mul_f32_e32 v79, v66, v67
	v_cndmask_b32_e64 v78, v62, 1.0, vcc
	ds_read_b128 v[62:65], v3 offset:15504
	ds_read_b128 v[66:69], v3 offset:15520
	ds_read_b128 v[70:73], v3 offset:15536
	ds_read_b128 v[74:77], v3 offset:15552
	s_waitcnt lgkmcnt(3)
	v_mul_f32_e32 v62, v4, v62
	v_fma_f32 v62, v78, v79, -v62
	v_fma_f32 v62, -v5, v63, v62
	v_fma_f32 v62, -v6, v64, v62
	v_fma_f32 v62, -v7, v65, v62
	s_waitcnt lgkmcnt(2)
	v_fma_f32 v62, -v8, v66, v62
	v_fma_f32 v62, -v9, v67, v62
	v_fma_f32 v62, -v10, v68, v62
	v_fma_f32 v62, -v11, v69, v62
	s_waitcnt lgkmcnt(1)
	v_fma_f32 v62, -v12, v70, v62
	v_fma_f32 v62, -v13, v71, v62
	v_fma_f32 v62, -v14, v72, v62
	v_fma_f32 v62, -v15, v73, v62
	s_waitcnt lgkmcnt(0)
	v_fma_f32 v66, -v16, v74, v62
	ds_read_b128 v[62:65], v3 offset:15568
	v_fma_f32 v66, -v17, v75, v66
	v_fma_f32 v66, -v18, v76, v66
	v_fma_f32 v70, -v19, v77, v66
	ds_read_b128 v[66:69], v3 offset:15584
	s_waitcnt lgkmcnt(1)
	v_fma_f32 v62, -v20, v62, v70
	v_fma_f32 v62, -v21, v63, v62
	v_fma_f32 v62, -v22, v64, v62
	v_fma_f32 v62, -v23, v65, v62
	s_waitcnt lgkmcnt(0)
	v_fma_f32 v66, -v24, v66, v62
	ds_read_b128 v[62:65], v3 offset:15600
	v_fma_f32 v66, -v25, v67, v66
	v_fma_f32 v66, -v26, v68, v66
	v_fma_f32 v70, -v27, v69, v66
	ds_read_b128 v[66:69], v3 offset:15616
	s_waitcnt lgkmcnt(1)
	v_fma_f32 v62, -v28, v62, v70
	v_fma_f32 v62, -v29, v63, v62
	v_fma_f32 v62, -v30, v64, v62
	v_fma_f32 v62, -v31, v65, v62
	s_waitcnt lgkmcnt(0)
	v_fma_f32 v66, -v32, v66, v62
	ds_read_b128 v[62:65], v3 offset:15632
	v_fma_f32 v66, -v33, v67, v66
	v_fma_f32 v66, -v35, v68, v66
	v_fma_f32 v70, -v36, v69, v66
	ds_read_b128 v[66:69], v3 offset:15648
	s_waitcnt lgkmcnt(1)
	v_fma_f32 v62, -v37, v62, v70
	v_fma_f32 v62, -v38, v63, v62
	v_fma_f32 v62, -v39, v64, v62
	v_fma_f32 v62, -v40, v65, v62
	s_waitcnt lgkmcnt(0)
; DEVI float bf2f(bf16_t b) { return __uint_as_float(((unsigned)b) << 16); }
; DEVI void prep_item(const Params& p, int j, int n, int h, char* smem) {
;     ...
; #pragma unroll
;     for (int i = 0; i < 64; ++i) {
;       const float* amz = am + zero;
;       const float* sbz = sbeta + zero;
;       const float eg = __expf(sbz[64 + i]);
;       float acc = bf2f(*(const unsigned short*)(src + i * 272)) * sbz[i] * (isu ? 1.0f : eg);
; #pragma unroll
;       for (int j4 = 0; j4 < (i + 3) / 4; ++j4) {
;         const f32x4 a = *(const f32x4*)(amz + i * 68 + j4 * 4);
;         acc -= a[0] * x[j4 * 4 + 0];
;         acc -= a[1] * x[j4 * 4 + 1];
;         acc -= a[2] * x[j4 * 4 + 2];
;         acc -= a[3] * x[j4 * 4 + 3];
;       }
;       asm volatile("" : "+v"(zero), "+v"(acc));
;       x[i] = acc;
;     }
	v_fma_f32 v66, -v41, v66, v62
	ds_read_b128 v[62:65], v3 offset:15664
	v_fma_f32 v66, -v42, v67, v66
	v_fma_f32 v66, -v43, v68, v66
	v_fma_f32 v70, -v44, v69, v66
	ds_read_b128 v[66:69], v3 offset:15680
	s_waitcnt lgkmcnt(1)
	v_fma_f32 v62, -v45, v62, v70
	v_fma_f32 v62, -v46, v63, v62
	v_fma_f32 v62, -v47, v64, v62
	v_fma_f32 v62, -v48, v65, v62
	s_waitcnt lgkmcnt(0)
	v_fma_f32 v66, -v49, v66, v62
	ds_read_b128 v[62:65], v3 offset:15696
	v_fma_f32 v66, -v50, v67, v66
	v_fma_f32 v66, -v51, v68, v66
	v_fma_f32 v70, -v52, v69, v66
	ds_read_b128 v[66:69], v3 offset:15712
	s_waitcnt lgkmcnt(1)
	v_fma_f32 v62, -v53, v62, v70
	v_fma_f32 v62, -v54, v63, v62
	v_fma_f32 v62, -v55, v64, v62
	v_fma_f32 v70, -v56, v65, v62
	ds_read_b128 v[62:65], v3 offset:15728
	s_waitcnt lgkmcnt(1)
	v_fma_f32 v3, -v57, v66, v70
	v_fma_f32 v3, -v58, v67, v3
	v_fma_f32 v3, -v59, v68, v3
	v_fma_f32 v3, -v60, v69, v3
	s_waitcnt lgkmcnt(0)
	v_fma_f32 v62, -v61, v62, v3
	v_fmac_f32_e32 v62, 0x80000000, v63
	v_fmac_f32_e32 v62, 0x80000000, v64
	v_fmac_f32_e32 v62, 0x80000000, v65
	ds_read_u16 v64, v2 offset:15776
	v_lshlrev_b32_e32 v3, 2, v0
	v_add_u32_e32 v63, s0, v3
	ds_read2_b32 v[68:69], v63 offset0:58 offset1:122
	v_add_u32_e32 v3, 32, v3
	v_add_u32_e32 v3, 0xcc00, v3
	s_waitcnt lgkmcnt(0)
	v_mul_f32_e32 v63, 0x3fb8aa3b, v69
	v_lshlrev_b32_e32 v69, 16, v64
	ds_read_b128 v[64:67], v3 offset:15776
	v_exp_f32_e32 v63, v63
	v_mul_f32_e32 v80, v68, v69
	ds_read_b128 v[68:71], v3 offset:15792
	ds_read_b128 v[72:75], v3 offset:15808
	ds_read_b128 v[76:79], v3 offset:15824
	v_cndmask_b32_e64 v63, v63, 1.0, vcc
	s_waitcnt lgkmcnt(3)
	v_mul_f32_e32 v64, v4, v64
	v_fma_f32 v63, v63, v80, -v64
	v_fma_f32 v63, -v5, v65, v63
	v_fma_f32 v63, -v6, v66, v63
	v_fma_f32 v63, -v7, v67, v63
	s_waitcnt lgkmcnt(2)
	v_fma_f32 v63, -v8, v68, v63
	v_fma_f32 v63, -v9, v69, v63
	v_fma_f32 v63, -v10, v70, v63
	v_fma_f32 v63, -v11, v71, v63
	s_waitcnt lgkmcnt(1)
	v_fma_f32 v63, -v12, v72, v63
	v_fma_f32 v63, -v13, v73, v63
	v_fma_f32 v63, -v14, v74, v63
	v_fma_f32 v63, -v15, v75, v63
	ds_read_b128 v[64:67], v3 offset:15840
	s_waitcnt lgkmcnt(1)
	v_fma_f32 v63, -v16, v76, v63
	v_fma_f32 v63, -v17, v77, v63
	v_fma_f32 v63, -v18, v78, v63
	v_fma_f32 v63, -v19, v79, v63
	ds_read_b128 v[68:71], v3 offset:15856
	s_waitcnt lgkmcnt(1)
	v_fma_f32 v63, -v20, v64, v63
	v_fma_f32 v63, -v21, v65, v63
	v_fma_f32 v63, -v22, v66, v63
	v_fma_f32 v63, -v23, v67, v63
	ds_read_b128 v[64:67], v3 offset:15872
	s_waitcnt lgkmcnt(1)
	v_fma_f32 v63, -v24, v68, v63
	v_fma_f32 v63, -v25, v69, v63
	v_fma_f32 v63, -v26, v70, v63
	v_fma_f32 v63, -v27, v71, v63
	ds_read_b128 v[68:71], v3 offset:15888
	s_waitcnt lgkmcnt(1)
	v_fma_f32 v63, -v28, v64, v63
	v_fma_f32 v63, -v29, v65, v63
	v_fma_f32 v63, -v30, v66, v63
	v_fma_f32 v63, -v31, v67, v63
	ds_read_b128 v[64:67], v3 offset:15904
	s_waitcnt lgkmcnt(1)
	v_fma_f32 v63, -v32, v68, v63
	v_fma_f32 v63, -v33, v69, v63
	v_fma_f32 v63, -v35, v70, v63
	v_fma_f32 v63, -v36, v71, v63
	ds_read_b128 v[68:71], v3 offset:15920
	s_waitcnt lgkmcnt(1)
	v_fma_f32 v63, -v37, v64, v63
	v_fma_f32 v63, -v38, v65, v63
	v_fma_f32 v63, -v39, v66, v63
	v_fma_f32 v63, -v40, v67, v63
	ds_read_b128 v[64:67], v3 offset:15936
	s_waitcnt lgkmcnt(1)
	v_fma_f32 v63, -v41, v68, v63
	v_fma_f32 v63, -v42, v69, v63
	v_fma_f32 v63, -v43, v70, v63
	v_fma_f32 v63, -v44, v71, v63
	ds_read_b128 v[68:71], v3 offset:15952
	s_waitcnt lgkmcnt(1)
	v_fma_f32 v63, -v45, v64, v63
	v_fma_f32 v63, -v46, v65, v63
	v_fma_f32 v63, -v47, v66, v63
	v_fma_f32 v63, -v48, v67, v63
	ds_read_b128 v[64:67], v3 offset:15968
	s_waitcnt lgkmcnt(1)
	v_fma_f32 v63, -v49, v68, v63
	v_fma_f32 v63, -v50, v69, v63
	v_fma_f32 v63, -v51, v70, v63
	v_fma_f32 v63, -v52, v71, v63
	ds_read_b128 v[68:71], v3 offset:15984
	s_waitcnt lgkmcnt(1)
	v_fma_f32 v63, -v53, v64, v63
	v_fma_f32 v63, -v54, v65, v63
	v_fma_f32 v63, -v55, v66, v63
	v_fma_f32 v63, -v56, v67, v63
	ds_read_b128 v[64:67], v3 offset:16000
	s_waitcnt lgkmcnt(1)
	v_fma_f32 v3, -v57, v68, v63
	v_fma_f32 v3, -v58, v69, v3
	v_fma_f32 v3, -v59, v70, v3
	v_fma_f32 v3, -v60, v71, v3
	s_waitcnt lgkmcnt(0)
	v_fma_f32 v3, -v61, v64, v3
	v_fma_f32 v63, -v62, v65, v3
	v_fmac_f32_e32 v63, 0x80000000, v66
	v_fmac_f32_e32 v63, 0x80000000, v67
	ds_read_u16 v65, v2 offset:16048
	v_lshlrev_b32_e32 v3, 2, v0
	v_add_u32_e32 v64, s0, v3
	ds_read2_b32 v[68:69], v64 offset0:59 offset1:123
	v_add_u32_e32 v3, 32, v3
	v_add_u32_e32 v3, 0xcc00, v3
	s_waitcnt lgkmcnt(0)
	v_mul_f32_e32 v64, 0x3fb8aa3b, v69
	v_exp_f32_e32 v64, v64
	v_lshlrev_b32_e32 v69, 16, v65
	v_mul_f32_e32 v81, v68, v69
	v_cndmask_b32_e64 v80, v64, 1.0, vcc
	ds_read_b128 v[64:67], v3 offset:16048
	ds_read_b128 v[68:71], v3 offset:16064
	ds_read_b128 v[72:75], v3 offset:16080
	ds_read_b128 v[76:79], v3 offset:16096
	s_waitcnt lgkmcnt(3)
	v_mul_f32_e32 v64, v4, v64
	v_fma_f32 v64, v80, v81, -v64
	v_fma_f32 v64, -v5, v65, v64
	v_fma_f32 v64, -v6, v66, v64
	v_fma_f32 v64, -v7, v67, v64
	s_waitcnt lgkmcnt(2)
	v_fma_f32 v64, -v8, v68, v64
	v_fma_f32 v64, -v9, v69, v64
	v_fma_f32 v64, -v10, v70, v64
	v_fma_f32 v64, -v11, v71, v64
	s_waitcnt lgkmcnt(1)
	v_fma_f32 v64, -v12, v72, v64
	v_fma_f32 v64, -v13, v73, v64
	v_fma_f32 v64, -v14, v74, v64
	v_fma_f32 v64, -v15, v75, v64
	s_waitcnt lgkmcnt(0)
	v_fma_f32 v68, -v16, v76, v64
	ds_read_b128 v[64:67], v3 offset:16112
	v_fma_f32 v68, -v17, v77, v68
	v_fma_f32 v68, -v18, v78, v68
	v_fma_f32 v72, -v19, v79, v68
	ds_read_b128 v[68:71], v3 offset:16128
	s_waitcnt lgkmcnt(1)
	v_fma_f32 v64, -v20, v64, v72
	v_fma_f32 v64, -v21, v65, v64
	v_fma_f32 v64, -v22, v66, v64
	v_fma_f32 v64, -v23, v67, v64
	s_waitcnt lgkmcnt(0)
; DEVI float bf2f(bf16_t b) { return __uint_as_float(((unsigned)b) << 16); }
; DEVI void prep_item(const Params& p, int j, int n, int h, char* smem) {
;     ...
; #pragma unroll
;     for (int i = 0; i < 64; ++i) {
;       const float* amz = am + zero;
;       const float* sbz = sbeta + zero;
;       const float eg = __expf(sbz[64 + i]);
;       float acc = bf2f(*(const unsigned short*)(src + i * 272)) * sbz[i] * (isu ? 1.0f : eg);
; #pragma unroll
;       for (int j4 = 0; j4 < (i + 3) / 4; ++j4) {
;         const f32x4 a = *(const f32x4*)(amz + i * 68 + j4 * 4);
;         acc -= a[0] * x[j4 * 4 + 0];
;         acc -= a[1] * x[j4 * 4 + 1];
;         acc -= a[2] * x[j4 * 4 + 2];
;         acc -= a[3] * x[j4 * 4 + 3];
;       }
;       asm volatile("" : "+v"(zero), "+v"(acc));
;       x[i] = acc;
;     }
	v_fma_f32 v68, -v24, v68, v64
	ds_read_b128 v[64:67], v3 offset:16144
	v_fma_f32 v68, -v25, v69, v68
	v_fma_f32 v68, -v26, v70, v68
	v_fma_f32 v72, -v27, v71, v68
	ds_read_b128 v[68:71], v3 offset:16160
	s_waitcnt lgkmcnt(1)
	v_fma_f32 v64, -v28, v64, v72
	v_fma_f32 v64, -v29, v65, v64
	v_fma_f32 v64, -v30, v66, v64
	v_fma_f32 v64, -v31, v67, v64
	s_waitcnt lgkmcnt(0)
	v_fma_f32 v68, -v32, v68, v64
	ds_read_b128 v[64:67], v3 offset:16176
	v_fma_f32 v68, -v33, v69, v68
	v_fma_f32 v68, -v35, v70, v68
	v_fma_f32 v72, -v36, v71, v68
	ds_read_b128 v[68:71], v3 offset:16192
	s_waitcnt lgkmcnt(1)
	v_fma_f32 v64, -v37, v64, v72
	v_fma_f32 v64, -v38, v65, v64
	v_fma_f32 v64, -v39, v66, v64
	v_fma_f32 v64, -v40, v67, v64
	s_waitcnt lgkmcnt(0)
	v_fma_f32 v68, -v41, v68, v64
	ds_read_b128 v[64:67], v3 offset:16208
	v_fma_f32 v68, -v42, v69, v68
	v_fma_f32 v68, -v43, v70, v68
	v_fma_f32 v72, -v44, v71, v68
	ds_read_b128 v[68:71], v3 offset:16224
	s_waitcnt lgkmcnt(1)
	v_fma_f32 v64, -v45, v64, v72
	v_fma_f32 v64, -v46, v65, v64
	v_fma_f32 v64, -v47, v66, v64
	v_fma_f32 v64, -v48, v67, v64
	s_waitcnt lgkmcnt(0)
	v_fma_f32 v68, -v49, v68, v64
	ds_read_b128 v[64:67], v3 offset:16240
	v_fma_f32 v68, -v50, v69, v68
	v_fma_f32 v68, -v51, v70, v68
	v_fma_f32 v72, -v52, v71, v68
	ds_read_b128 v[68:71], v3 offset:16256
	s_waitcnt lgkmcnt(1)
	v_fma_f32 v64, -v53, v64, v72
	v_fma_f32 v64, -v54, v65, v64
	v_fma_f32 v64, -v55, v66, v64
	v_fma_f32 v72, -v56, v67, v64
	ds_read_b128 v[64:67], v3 offset:16272
	s_waitcnt lgkmcnt(1)
	v_fma_f32 v3, -v57, v68, v72
	v_fma_f32 v3, -v58, v69, v3
	v_fma_f32 v3, -v59, v70, v3
	v_fma_f32 v3, -v60, v71, v3
	s_waitcnt lgkmcnt(0)
	v_fma_f32 v3, -v61, v64, v3
	v_fma_f32 v3, -v62, v65, v3
	v_fma_f32 v64, -v63, v66, v3
	v_fmac_f32_e32 v64, 0x80000000, v67
	ds_read_u16 v66, v2 offset:16320
	v_lshlrev_b32_e32 v3, 2, v0
	v_add_u32_e32 v65, s0, v3
	ds_read2_b32 v[70:71], v65 offset0:60 offset1:124
	v_add_u32_e32 v3, 32, v3
	v_add_u32_e32 v3, 0xcc00, v3
	s_waitcnt lgkmcnt(0)
	v_mul_f32_e32 v65, 0x3fb8aa3b, v71
	v_lshlrev_b32_e32 v71, 16, v66
	ds_read_b128 v[66:69], v3 offset:16320
	v_exp_f32_e32 v65, v65
	v_mul_f32_e32 v82, v70, v71
	ds_read_b128 v[70:73], v3 offset:16336
	ds_read_b128 v[74:77], v3 offset:16352
	ds_read_b128 v[78:81], v3 offset:16368
	v_cndmask_b32_e64 v65, v65, 1.0, vcc
	s_waitcnt lgkmcnt(3)
	v_mul_f32_e32 v66, v4, v66
	v_fma_f32 v65, v65, v82, -v66
	v_fma_f32 v65, -v5, v67, v65
	v_fma_f32 v65, -v6, v68, v65
	v_fma_f32 v65, -v7, v69, v65
	s_waitcnt lgkmcnt(2)
	v_fma_f32 v65, -v8, v70, v65
	v_fma_f32 v65, -v9, v71, v65
	v_fma_f32 v65, -v10, v72, v65
	v_fma_f32 v65, -v11, v73, v65
	s_waitcnt lgkmcnt(1)
	v_fma_f32 v65, -v12, v74, v65
	v_fma_f32 v65, -v13, v75, v65
	v_fma_f32 v65, -v14, v76, v65
	v_fma_f32 v65, -v15, v77, v65
	ds_read_b128 v[66:69], v3 offset:16384
	s_waitcnt lgkmcnt(1)
	v_fma_f32 v65, -v16, v78, v65
	v_fma_f32 v65, -v17, v79, v65
	v_fma_f32 v65, -v18, v80, v65
	v_fma_f32 v65, -v19, v81, v65
	ds_read_b128 v[70:73], v3 offset:16400
	s_waitcnt lgkmcnt(1)
	v_fma_f32 v65, -v20, v66, v65
	v_fma_f32 v65, -v21, v67, v65
	v_fma_f32 v65, -v22, v68, v65
	v_fma_f32 v65, -v23, v69, v65
	ds_read_b128 v[66:69], v3 offset:16416
	s_waitcnt lgkmcnt(1)
	v_fma_f32 v65, -v24, v70, v65
	v_fma_f32 v65, -v25, v71, v65
	v_fma_f32 v65, -v26, v72, v65
	v_fma_f32 v65, -v27, v73, v65
	ds_read_b128 v[70:73], v3 offset:16432
	s_waitcnt lgkmcnt(1)
	v_fma_f32 v65, -v28, v66, v65
	v_fma_f32 v65, -v29, v67, v65
	v_fma_f32 v65, -v30, v68, v65
	v_fma_f32 v65, -v31, v69, v65
	ds_read_b128 v[66:69], v3 offset:16448
	s_waitcnt lgkmcnt(1)
	v_fma_f32 v65, -v32, v70, v65
	v_fma_f32 v65, -v33, v71, v65
	v_fma_f32 v65, -v35, v72, v65
	v_fma_f32 v65, -v36, v73, v65
	ds_read_b128 v[70:73], v3 offset:16464
	s_waitcnt lgkmcnt(1)
	v_fma_f32 v65, -v37, v66, v65
	v_fma_f32 v65, -v38, v67, v65
	v_fma_f32 v65, -v39, v68, v65
	v_fma_f32 v65, -v40, v69, v65
	ds_read_b128 v[66:69], v3 offset:16480
	s_waitcnt lgkmcnt(1)
	v_fma_f32 v65, -v41, v70, v65
	v_fma_f32 v65, -v42, v71, v65
	v_fma_f32 v65, -v43, v72, v65
	v_fma_f32 v65, -v44, v73, v65
	ds_read_b128 v[70:73], v3 offset:16496
	s_waitcnt lgkmcnt(1)
	v_fma_f32 v65, -v45, v66, v65
	v_fma_f32 v65, -v46, v67, v65
	v_fma_f32 v65, -v47, v68, v65
	v_fma_f32 v65, -v48, v69, v65
	ds_read_b128 v[66:69], v3 offset:16512
	s_waitcnt lgkmcnt(1)
	v_fma_f32 v65, -v49, v70, v65
	v_fma_f32 v65, -v50, v71, v65
	v_fma_f32 v65, -v51, v72, v65
	v_fma_f32 v65, -v52, v73, v65
	ds_read_b128 v[70:73], v3 offset:16528
	s_waitcnt lgkmcnt(1)
	v_fma_f32 v65, -v53, v66, v65
	v_fma_f32 v65, -v54, v67, v65
	v_fma_f32 v65, -v55, v68, v65
	v_fma_f32 v65, -v56, v69, v65
	ds_read_b128 v[66:69], v3 offset:16544
	s_waitcnt lgkmcnt(1)
	v_fma_f32 v3, -v57, v70, v65
	v_fma_f32 v3, -v58, v71, v3
	v_fma_f32 v3, -v59, v72, v3
	v_fma_f32 v3, -v60, v73, v3
	s_waitcnt lgkmcnt(0)
	v_fma_f32 v3, -v61, v66, v3
	v_fma_f32 v3, -v62, v67, v3
	v_fma_f32 v3, -v63, v68, v3
	v_fma_f32 v65, -v64, v69, v3
	ds_read_u16 v67, v2 offset:16592
	v_lshlrev_b32_e32 v3, 2, v0
	v_add_u32_e32 v66, s0, v3
	ds_read2_b32 v[70:71], v66 offset0:61 offset1:125
	v_add_u32_e32 v3, 32, v3
	v_add_u32_e32 v3, 0xcc00, v3
	s_waitcnt lgkmcnt(0)
	v_mul_f32_e32 v66, 0x3fb8aa3b, v71
	v_exp_f32_e32 v66, v66
	v_lshlrev_b32_e32 v71, 16, v67
	v_mul_f32_e32 v83, v70, v71
	v_cndmask_b32_e64 v82, v66, 1.0, vcc
	ds_read_b128 v[66:69], v3 offset:16592
	ds_read_b128 v[70:73], v3 offset:16608
	ds_read_b128 v[74:77], v3 offset:16624
	ds_read_b128 v[78:81], v3 offset:16640
	s_waitcnt lgkmcnt(3)
	v_mul_f32_e32 v66, v4, v66
	v_fma_f32 v66, v82, v83, -v66
	v_fma_f32 v66, -v5, v67, v66
	v_fma_f32 v66, -v6, v68, v66
	v_fma_f32 v66, -v7, v69, v66
	s_waitcnt lgkmcnt(2)
; DEVI float bf2f(bf16_t b) { return __uint_as_float(((unsigned)b) << 16); }
; DEVI void prep_item(const Params& p, int j, int n, int h, char* smem) {
;     ...
; #pragma unroll
;     for (int i = 0; i < 64; ++i) {
;       const float* amz = am + zero;
;       const float* sbz = sbeta + zero;
;       const float eg = __expf(sbz[64 + i]);
;       float acc = bf2f(*(const unsigned short*)(src + i * 272)) * sbz[i] * (isu ? 1.0f : eg);
; #pragma unroll
;       for (int j4 = 0; j4 < (i + 3) / 4; ++j4) {
;         const f32x4 a = *(const f32x4*)(amz + i * 68 + j4 * 4);
;         acc -= a[0] * x[j4 * 4 + 0];
;         acc -= a[1] * x[j4 * 4 + 1];
;         acc -= a[2] * x[j4 * 4 + 2];
;         acc -= a[3] * x[j4 * 4 + 3];
;       }
;       asm volatile("" : "+v"(zero), "+v"(acc));
;       x[i] = acc;
;     }
	v_fma_f32 v66, -v8, v70, v66
	v_fma_f32 v66, -v9, v71, v66
	v_fma_f32 v66, -v10, v72, v66
	v_fma_f32 v66, -v11, v73, v66
	s_waitcnt lgkmcnt(1)
	v_fma_f32 v66, -v12, v74, v66
	v_fma_f32 v66, -v13, v75, v66
	v_fma_f32 v66, -v14, v76, v66
	v_fma_f32 v66, -v15, v77, v66
	s_waitcnt lgkmcnt(0)
	v_fma_f32 v70, -v16, v78, v66
	ds_read_b128 v[66:69], v3 offset:16656
	v_fma_f32 v70, -v17, v79, v70
	v_fma_f32 v70, -v18, v80, v70
	v_fma_f32 v74, -v19, v81, v70
	ds_read_b128 v[70:73], v3 offset:16672
	s_waitcnt lgkmcnt(1)
	v_fma_f32 v66, -v20, v66, v74
	v_fma_f32 v66, -v21, v67, v66
	v_fma_f32 v66, -v22, v68, v66
	v_fma_f32 v66, -v23, v69, v66
	s_waitcnt lgkmcnt(0)
	v_fma_f32 v70, -v24, v70, v66
	ds_read_b128 v[66:69], v3 offset:16688
	v_fma_f32 v70, -v25, v71, v70
	v_fma_f32 v70, -v26, v72, v70
	v_fma_f32 v74, -v27, v73, v70
	ds_read_b128 v[70:73], v3 offset:16704
	s_waitcnt lgkmcnt(1)
	v_fma_f32 v66, -v28, v66, v74
	v_fma_f32 v66, -v29, v67, v66
	v_fma_f32 v66, -v30, v68, v66
	v_fma_f32 v66, -v31, v69, v66
	s_waitcnt lgkmcnt(0)
	v_fma_f32 v70, -v32, v70, v66
	ds_read_b128 v[66:69], v3 offset:16720
	v_fma_f32 v70, -v33, v71, v70
	v_fma_f32 v70, -v35, v72, v70
	v_fma_f32 v74, -v36, v73, v70
	ds_read_b128 v[70:73], v3 offset:16736
	s_waitcnt lgkmcnt(1)
	v_fma_f32 v66, -v37, v66, v74
	v_fma_f32 v66, -v38, v67, v66
	v_fma_f32 v66, -v39, v68, v66
	v_fma_f32 v66, -v40, v69, v66
	s_waitcnt lgkmcnt(0)
	v_fma_f32 v70, -v41, v70, v66
	ds_read_b128 v[66:69], v3 offset:16752
	v_fma_f32 v70, -v42, v71, v70
	v_fma_f32 v70, -v43, v72, v70
	v_fma_f32 v74, -v44, v73, v70
	ds_read_b128 v[70:73], v3 offset:16768
	s_waitcnt lgkmcnt(1)
	v_fma_f32 v66, -v45, v66, v74
	v_fma_f32 v66, -v46, v67, v66
	v_fma_f32 v66, -v47, v68, v66
	v_fma_f32 v66, -v48, v69, v66
	s_waitcnt lgkmcnt(0)
	v_fma_f32 v70, -v49, v70, v66
	ds_read_b128 v[66:69], v3 offset:16784
	v_fma_f32 v70, -v50, v71, v70
	v_fma_f32 v70, -v51, v72, v70
	v_fma_f32 v74, -v52, v73, v70
	ds_read_b128 v[70:73], v3 offset:16800
	s_waitcnt lgkmcnt(1)
	v_fma_f32 v66, -v53, v66, v74
	v_fma_f32 v66, -v54, v67, v66
	v_fma_f32 v66, -v55, v68, v66
	v_fma_f32 v66, -v56, v69, v66
	s_waitcnt lgkmcnt(0)
	v_fma_f32 v70, -v57, v70, v66
	ds_read_b128 v[66:69], v3 offset:16816
	v_fma_f32 v70, -v58, v71, v70
	v_fma_f32 v70, -v59, v72, v70
	v_fma_f32 v74, -v60, v73, v70
	ds_read_b128 v[70:73], v3 offset:16832
	s_waitcnt lgkmcnt(1)
	v_fma_f32 v3, -v61, v66, v74
	v_fma_f32 v3, -v62, v67, v3
	v_fma_f32 v3, -v63, v68, v3
	v_fma_f32 v3, -v64, v69, v3
	s_waitcnt lgkmcnt(0)
	v_fma_f32 v66, -v65, v70, v3
	v_fmac_f32_e32 v66, 0x80000000, v71
	v_fmac_f32_e32 v66, 0x80000000, v72
	v_fmac_f32_e32 v66, 0x80000000, v73
	ds_read_u16 v68, v2 offset:16864
	v_lshlrev_b32_e32 v3, 2, v0
	v_add_u32_e32 v67, s0, v3
	ds_read2_b32 v[72:73], v67 offset0:62 offset1:126
	v_add_u32_e32 v3, 32, v3
	v_add_u32_e32 v3, 0xcc00, v3
	s_waitcnt lgkmcnt(0)
	v_mul_f32_e32 v67, 0x3fb8aa3b, v73
	v_lshlrev_b32_e32 v73, 16, v68
	ds_read_b128 v[68:71], v3 offset:16864
	v_exp_f32_e32 v67, v67
	v_mul_f32_e32 v84, v72, v73
	ds_read_b128 v[72:75], v3 offset:16880
	ds_read_b128 v[76:79], v3 offset:16896
	ds_read_b128 v[80:83], v3 offset:16912
	v_cndmask_b32_e64 v67, v67, 1.0, vcc
	s_waitcnt lgkmcnt(3)
	v_mul_f32_e32 v68, v4, v68
	v_fma_f32 v67, v67, v84, -v68
	v_fma_f32 v67, -v5, v69, v67
	v_fma_f32 v67, -v6, v70, v67
	v_fma_f32 v67, -v7, v71, v67
	s_waitcnt lgkmcnt(2)
	v_fma_f32 v67, -v8, v72, v67
	v_fma_f32 v67, -v9, v73, v67
	v_fma_f32 v67, -v10, v74, v67
	v_fma_f32 v67, -v11, v75, v67
	s_waitcnt lgkmcnt(1)
	v_fma_f32 v67, -v12, v76, v67
	v_fma_f32 v67, -v13, v77, v67
	v_fma_f32 v67, -v14, v78, v67
	v_fma_f32 v67, -v15, v79, v67
	ds_read_b128 v[68:71], v3 offset:16928
	s_waitcnt lgkmcnt(1)
	v_fma_f32 v67, -v16, v80, v67
	v_fma_f32 v67, -v17, v81, v67
	v_fma_f32 v67, -v18, v82, v67
	v_fma_f32 v67, -v19, v83, v67
	ds_read_b128 v[72:75], v3 offset:16944
	s_waitcnt lgkmcnt(1)
	v_fma_f32 v67, -v20, v68, v67
	v_fma_f32 v67, -v21, v69, v67
	v_fma_f32 v67, -v22, v70, v67
	v_fma_f32 v67, -v23, v71, v67
	ds_read_b128 v[68:71], v3 offset:16960
	s_waitcnt lgkmcnt(1)
	v_fma_f32 v67, -v24, v72, v67
	v_fma_f32 v67, -v25, v73, v67
	v_fma_f32 v67, -v26, v74, v67
	v_fma_f32 v67, -v27, v75, v67
	ds_read_b128 v[72:75], v3 offset:16976
	s_waitcnt lgkmcnt(1)
	v_fma_f32 v67, -v28, v68, v67
	v_fma_f32 v67, -v29, v69, v67
	v_fma_f32 v67, -v30, v70, v67
	v_fma_f32 v67, -v31, v71, v67
	ds_read_b128 v[68:71], v3 offset:16992
	s_waitcnt lgkmcnt(1)
	v_fma_f32 v67, -v32, v72, v67
	v_fma_f32 v67, -v33, v73, v67
	v_fma_f32 v67, -v35, v74, v67
	v_fma_f32 v67, -v36, v75, v67
	ds_read_b128 v[72:75], v3 offset:17008
	s_waitcnt lgkmcnt(1)
	v_fma_f32 v67, -v37, v68, v67
	v_fma_f32 v67, -v38, v69, v67
	v_fma_f32 v67, -v39, v70, v67
	v_fma_f32 v67, -v40, v71, v67
	ds_read_b128 v[68:71], v3 offset:17024
	s_waitcnt lgkmcnt(1)
	v_fma_f32 v67, -v41, v72, v67
	v_fma_f32 v67, -v42, v73, v67
	v_fma_f32 v67, -v43, v74, v67
	v_fma_f32 v67, -v44, v75, v67
	ds_read_b128 v[72:75], v3 offset:17040
	s_waitcnt lgkmcnt(1)
	v_fma_f32 v67, -v45, v68, v67
	v_fma_f32 v67, -v46, v69, v67
	v_fma_f32 v67, -v47, v70, v67
	v_fma_f32 v67, -v48, v71, v67
	ds_read_b128 v[68:71], v3 offset:17056
	s_waitcnt lgkmcnt(1)
	v_fma_f32 v67, -v49, v72, v67
	v_fma_f32 v67, -v50, v73, v67
	v_fma_f32 v67, -v51, v74, v67
	v_fma_f32 v67, -v52, v75, v67
	ds_read_b128 v[72:75], v3 offset:17072
	s_waitcnt lgkmcnt(1)
	v_fma_f32 v67, -v53, v68, v67
	v_fma_f32 v67, -v54, v69, v67
	v_fma_f32 v67, -v55, v70, v67
	v_fma_f32 v67, -v56, v71, v67
	ds_read_b128 v[68:71], v3 offset:17088
	s_waitcnt lgkmcnt(1)
; DEVI float bf2f(bf16_t b) { return __uint_as_float(((unsigned)b) << 16); }
; DEVI void prep_item(const Params& p, int j, int n, int h, char* smem) {
;     ...
; #pragma unroll
;     for (int i = 0; i < 64; ++i) {
;       const float* amz = am + zero;
;       const float* sbz = sbeta + zero;
;       const float eg = __expf(sbz[64 + i]);
;       float acc = bf2f(*(const unsigned short*)(src + i * 272)) * sbz[i] * (isu ? 1.0f : eg);
; #pragma unroll
;       for (int j4 = 0; j4 < (i + 3) / 4; ++j4) {
;         const f32x4 a = *(const f32x4*)(amz + i * 68 + j4 * 4);
;         acc -= a[0] * x[j4 * 4 + 0];
;         acc -= a[1] * x[j4 * 4 + 1];
;         acc -= a[2] * x[j4 * 4 + 2];
;         acc -= a[3] * x[j4 * 4 + 3];
;       }
;       asm volatile("" : "+v"(zero), "+v"(acc));
;       x[i] = acc;
;     }
;     bf16_t* dst = r1 + (isu ? 2048 : 1024) + h * 128 + (c & 127);
	v_fma_f32 v67, -v57, v72, v67
	v_fma_f32 v67, -v58, v73, v67
	v_fma_f32 v67, -v59, v74, v67
	v_fma_f32 v67, -v60, v75, v67
	ds_read_b128 v[72:75], v3 offset:17104
	s_waitcnt lgkmcnt(1)
	v_fma_f32 v3, -v61, v68, v67
	v_fma_f32 v3, -v62, v69, v3
	v_fma_f32 v3, -v63, v70, v3
	v_fma_f32 v3, -v64, v71, v3
	s_waitcnt lgkmcnt(0)
	v_fma_f32 v3, -v65, v72, v3
	v_fma_f32 v67, -v66, v73, v3
	v_fmac_f32_e32 v67, 0x80000000, v74
	v_fmac_f32_e32 v67, 0x80000000, v75
	ds_read_u16 v2, v2 offset:17136
	v_lshlrev_b32_e32 v3, 2, v0
	v_add_u32_e32 v68, s0, v3
	ds_read2_b32 v[72:73], v68 offset0:63 offset1:127
	v_add_u32_e32 v3, 32, v3
	v_add_u32_e32 v3, 0xcc00, v3
	s_waitcnt lgkmcnt(1)
	v_lshlrev_b32_e32 v2, 16, v2
	v_readlane_b32 s0, v247, 26
	s_waitcnt lgkmcnt(0)
	v_mul_f32_e32 v68, 0x3fb8aa3b, v73
	v_exp_f32_e32 v68, v68
	v_mul_f32_e32 v2, v72, v2
	v_readlane_b32 s1, v247, 27
	v_cndmask_b32_e64 v84, v68, 1.0, vcc
	ds_read_b128 v[68:71], v3 offset:17136
	ds_read_b128 v[72:75], v3 offset:17152
	ds_read_b128 v[76:79], v3 offset:17168
	ds_read_b128 v[80:83], v3 offset:17184
	s_waitcnt lgkmcnt(3)
	v_mul_f32_e32 v68, v4, v68
	v_fma_f32 v2, v84, v2, -v68
	v_fma_f32 v2, -v5, v69, v2
	v_fma_f32 v2, -v6, v70, v2
	v_fma_f32 v2, -v7, v71, v2
	s_waitcnt lgkmcnt(2)
	v_fma_f32 v2, -v8, v72, v2
	v_fma_f32 v2, -v9, v73, v2
	v_fma_f32 v2, -v10, v74, v2
	v_fma_f32 v2, -v11, v75, v2
	s_waitcnt lgkmcnt(1)
	v_fma_f32 v2, -v12, v76, v2
	v_fma_f32 v2, -v13, v77, v2
	v_fma_f32 v2, -v14, v78, v2
	v_fma_f32 v2, -v15, v79, v2
	ds_read_b128 v[68:71], v3 offset:17200
	s_waitcnt lgkmcnt(1)
	v_fma_f32 v2, -v16, v80, v2
	v_fma_f32 v2, -v17, v81, v2
	v_fma_f32 v2, -v18, v82, v2
	v_fma_f32 v2, -v19, v83, v2
	ds_read_b128 v[72:75], v3 offset:17216
	s_waitcnt lgkmcnt(1)
	v_fma_f32 v2, -v20, v68, v2
	v_fma_f32 v2, -v21, v69, v2
	v_fma_f32 v2, -v22, v70, v2
	v_fma_f32 v2, -v23, v71, v2
	ds_read_b128 v[68:71], v3 offset:17232
	s_waitcnt lgkmcnt(1)
	v_fma_f32 v2, -v24, v72, v2
	v_fma_f32 v2, -v25, v73, v2
	v_fma_f32 v2, -v26, v74, v2
	v_fma_f32 v2, -v27, v75, v2
	ds_read_b128 v[72:75], v3 offset:17248
	s_waitcnt lgkmcnt(1)
	v_fma_f32 v2, -v28, v68, v2
	v_fma_f32 v2, -v29, v69, v2
	v_fma_f32 v2, -v30, v70, v2
	v_fma_f32 v2, -v31, v71, v2
	ds_read_b128 v[68:71], v3 offset:17264
	s_waitcnt lgkmcnt(1)
	v_fma_f32 v2, -v32, v72, v2
	v_fma_f32 v2, -v33, v73, v2
	v_fma_f32 v2, -v35, v74, v2
	v_fma_f32 v2, -v36, v75, v2
	ds_read_b128 v[72:75], v3 offset:17280
	s_waitcnt lgkmcnt(1)
	v_fma_f32 v2, -v37, v68, v2
	v_fma_f32 v2, -v38, v69, v2
	v_fma_f32 v2, -v39, v70, v2
	v_fma_f32 v2, -v40, v71, v2
	ds_read_b128 v[68:71], v3 offset:17296
	s_waitcnt lgkmcnt(1)
	v_fma_f32 v2, -v41, v72, v2
	v_fma_f32 v2, -v42, v73, v2
	v_fma_f32 v2, -v43, v74, v2
	v_fma_f32 v2, -v44, v75, v2
	ds_read_b128 v[72:75], v3 offset:17312
	s_waitcnt lgkmcnt(1)
	v_fma_f32 v2, -v45, v68, v2
	v_fma_f32 v2, -v46, v69, v2
	v_fma_f32 v2, -v47, v70, v2
	v_fma_f32 v2, -v48, v71, v2
	ds_read_b128 v[68:71], v3 offset:17328
	s_waitcnt lgkmcnt(1)
	v_fma_f32 v2, -v49, v72, v2
	v_fma_f32 v2, -v50, v73, v2
	v_fma_f32 v2, -v51, v74, v2
	v_fma_f32 v2, -v52, v75, v2
	ds_read_b128 v[72:75], v3 offset:17344
	s_waitcnt lgkmcnt(1)
	v_fma_f32 v2, -v53, v68, v2
	v_fma_f32 v2, -v54, v69, v2
	v_fma_f32 v2, -v55, v70, v2
	v_fma_f32 v2, -v56, v71, v2
	ds_read_b128 v[68:71], v3 offset:17360
	s_waitcnt lgkmcnt(1)
	v_fma_f32 v2, -v57, v72, v2
	v_fma_f32 v2, -v58, v73, v2
	v_fma_f32 v2, -v59, v74, v2
	v_fma_f32 v2, -v60, v75, v2
	ds_read_b128 v[72:75], v3 offset:17376
	s_waitcnt lgkmcnt(1)
	v_fma_f32 v2, -v61, v68, v2
	v_fma_f32 v2, -v62, v69, v2
	v_fma_f32 v2, -v63, v70, v2
	v_fma_f32 v2, -v64, v71, v2
	s_waitcnt lgkmcnt(0)
	v_fma_f32 v2, -v65, v72, v2
	v_fma_f32 v2, -v66, v73, v2
	v_fma_f32 v68, -v67, v74, v2
	v_fmac_f32_e32 v68, 0x80000000, v75
	s_nop 0
	v_cndmask_b32_e32 v0, v220, v221, vcc
	v_lshl_add_u64 v[2:3], s[0:1], 0, v[0:1]
	v_and_b32_e32 v0, 0x7f, v34
	v_and_b32_e32 v85, 0x63, v0
	v_and_b32_e32 v86, 12, v0
	v_lshl_or_b32 v85, v86, 1, v85
	v_and_b32_e32 v86, 16, v0
	v_lshrrev_b32_e32 v86, 2, v86
	v_or_b32_e32 v85, v85, v86
	v_cndmask_b32_e32 v0, v85, v0, vcc
	v_lshl_add_u64 v[2:3], v[2:3], 0, s[62:63]
	v_lshlrev_b32_e32 v0, 1, v0
	v_lshl_add_u64 v[2:3], v[2:3], 0, v[0:1]
	s_cbranch_scc1 .LBB0_1295
; DEVI bf16_t f2bf(float a) { return (bf16_t)(pack2(a, 0.f) & 0xffff); }
; DEVI void prep_item(const Params& p, int j, int n, int h, char* smem) {
;     ...
;     bf16_t* dst = r1 + (isu ? 2048 : 1024) + h * 128 + (c & 127);
; #pragma unroll
;     for (int i = 0; i < 64; ++i) {
;       const int t = t0 + i;
;       if (t >= 0) dst[(size_t)t * 3072] = f2bf(x[i]);
;     }
	v_cvt_pk_bf16_f32 v0, v4, s0
	v_mad_u64_u32 v[70:71], s[0:1], s45, v222, v[2:3]
	s_sub_i32 s0, s43, 47
	global_store_short v[70:71], v0, off
	v_cvt_pk_bf16_f32 v0, v5, s0
	v_mad_u64_u32 v[4:5], s[0:1], s0, v222, v[2:3]
	s_sub_i32 s0, s43, 46
	global_store_short v[4:5], v0, off
	v_cvt_pk_bf16_f32 v0, v6, s0
	v_mad_u64_u32 v[4:5], s[0:1], s0, v222, v[2:3]
	s_sub_i32 s0, s43, 45
	global_store_short v[4:5], v0, off
	v_cvt_pk_bf16_f32 v0, v7, s0
	v_mad_u64_u32 v[4:5], s[0:1], s0, v222, v[2:3]
	s_sub_i32 s0, s43, 44
	global_store_short v[4:5], v0, off
	v_cvt_pk_bf16_f32 v0, v8, s0
	v_mad_u64_u32 v[4:5], s[0:1], s0, v222, v[2:3]
	s_sub_i32 s0, s43, 43
	global_store_short v[4:5], v0, off
	v_cvt_pk_bf16_f32 v0, v9, s0
	v_mad_u64_u32 v[4:5], s[0:1], s0, v222, v[2:3]
	s_sub_i32 s0, s43, 42
	global_store_short v[4:5], v0, off
	v_cvt_pk_bf16_f32 v0, v10, s0
	v_mad_u64_u32 v[4:5], s[0:1], s0, v222, v[2:3]
	s_sub_i32 s0, s43, 41
	global_store_short v[4:5], v0, off
	v_cvt_pk_bf16_f32 v0, v11, s0
	v_mad_u64_u32 v[4:5], s[0:1], s0, v222, v[2:3]
	s_sub_i32 s0, s43, 40
	global_store_short v[4:5], v0, off
	v_cvt_pk_bf16_f32 v0, v12, s0
	v_mad_u64_u32 v[4:5], s[0:1], s0, v222, v[2:3]
	s_sub_i32 s0, s43, 39
	global_store_short v[4:5], v0, off
	v_cvt_pk_bf16_f32 v0, v13, s0
	v_mad_u64_u32 v[4:5], s[0:1], s0, v222, v[2:3]
	s_sub_i32 s0, s43, 38
	global_store_short v[4:5], v0, off
	v_cvt_pk_bf16_f32 v0, v14, s0
	v_mad_u64_u32 v[4:5], s[0:1], s0, v222, v[2:3]
	s_sub_i32 s0, s43, 37
	global_store_short v[4:5], v0, off
	v_cvt_pk_bf16_f32 v0, v15, s0
	v_mad_u64_u32 v[4:5], s[0:1], s0, v222, v[2:3]
	s_sub_i32 s0, s43, 36
	global_store_short v[4:5], v0, off
	v_cvt_pk_bf16_f32 v0, v16, s0
	v_mad_u64_u32 v[4:5], s[0:1], s0, v222, v[2:3]
	s_sub_i32 s0, s43, 35
	global_store_short v[4:5], v0, off
	v_cvt_pk_bf16_f32 v0, v17, s0
	v_mad_u64_u32 v[4:5], s[0:1], s0, v222, v[2:3]
	s_sub_i32 s0, s43, 34
	global_store_short v[4:5], v0, off
	v_cvt_pk_bf16_f32 v0, v18, s0
	v_mad_u64_u32 v[4:5], s[0:1], s0, v222, v[2:3]
	s_sub_i32 s0, s43, 33
	global_store_short v[4:5], v0, off
	v_cvt_pk_bf16_f32 v0, v19, s0
	v_mad_u64_u32 v[4:5], s[0:1], s0, v222, v[2:3]
	s_sub_i32 s0, s43, 32
	global_store_short v[4:5], v0, off
	v_cvt_pk_bf16_f32 v0, v20, s0
	v_mad_u64_u32 v[4:5], s[0:1], s0, v222, v[2:3]
	s_sub_i32 s0, s43, 31
	global_store_short v[4:5], v0, off
	v_cvt_pk_bf16_f32 v0, v21, s0
	v_mad_u64_u32 v[4:5], s[0:1], s0, v222, v[2:3]
	s_sub_i32 s0, s43, 30
	global_store_short v[4:5], v0, off
	v_cvt_pk_bf16_f32 v0, v22, s0
	v_mad_u64_u32 v[4:5], s[0:1], s0, v222, v[2:3]
	s_sub_i32 s0, s43, 29
	global_store_short v[4:5], v0, off
	v_cvt_pk_bf16_f32 v0, v23, s0
	v_mad_u64_u32 v[4:5], s[0:1], s0, v222, v[2:3]
	s_sub_i32 s0, s43, 28
	global_store_short v[4:5], v0, off
	v_cvt_pk_bf16_f32 v0, v24, s0
	v_mad_u64_u32 v[4:5], s[0:1], s0, v222, v[2:3]
	s_sub_i32 s0, s43, 27
	global_store_short v[4:5], v0, off
	v_cvt_pk_bf16_f32 v0, v25, s0
	v_mad_u64_u32 v[4:5], s[0:1], s0, v222, v[2:3]
	s_sub_i32 s0, s43, 26
	global_store_short v[4:5], v0, off
	v_cvt_pk_bf16_f32 v0, v26, s0
	v_mad_u64_u32 v[4:5], s[0:1], s0, v222, v[2:3]
	s_sub_i32 s0, s43, 25
	global_store_short v[4:5], v0, off
	v_cvt_pk_bf16_f32 v0, v27, s0
	v_mad_u64_u32 v[4:5], s[0:1], s0, v222, v[2:3]
	s_sub_i32 s0, s43, 24
	global_store_short v[4:5], v0, off
	v_cvt_pk_bf16_f32 v0, v28, s0
	v_mad_u64_u32 v[4:5], s[0:1], s0, v222, v[2:3]
	s_sub_i32 s0, s43, 23
	global_store_short v[4:5], v0, off
	v_cvt_pk_bf16_f32 v0, v29, s0
	v_mad_u64_u32 v[4:5], s[0:1], s0, v222, v[2:3]
	s_sub_i32 s0, s43, 22
	global_store_short v[4:5], v0, off
	v_cvt_pk_bf16_f32 v0, v30, s0
	v_mad_u64_u32 v[4:5], s[0:1], s0, v222, v[2:3]
	s_sub_i32 s0, s43, 21
	global_store_short v[4:5], v0, off
	v_cvt_pk_bf16_f32 v0, v31, s0
	v_mad_u64_u32 v[4:5], s[0:1], s0, v222, v[2:3]
	s_sub_i32 s0, s43, 20
	global_store_short v[4:5], v0, off
	v_cvt_pk_bf16_f32 v0, v32, s0
	v_mad_u64_u32 v[4:5], s[0:1], s0, v222, v[2:3]
	s_sub_i32 s0, s43, 19
	global_store_short v[4:5], v0, off
	v_cvt_pk_bf16_f32 v0, v33, s0
	v_mad_u64_u32 v[4:5], s[0:1], s0, v222, v[2:3]
	s_sub_i32 s0, s43, 18
	global_store_short v[4:5], v0, off
	v_cvt_pk_bf16_f32 v0, v35, s0
	v_mad_u64_u32 v[4:5], s[0:1], s0, v222, v[2:3]
	s_sub_i32 s0, s43, 17
	global_store_short v[4:5], v0, off
	v_cvt_pk_bf16_f32 v0, v36, s0
	v_mad_u64_u32 v[4:5], s[0:1], s0, v222, v[2:3]
	s_add_i32 s0, s43, -16
	global_store_short v[4:5], v0, off
	v_cvt_pk_bf16_f32 v0, v37, s0
	v_mad_u64_u32 v[4:5], s[0:1], s0, v222, v[2:3]
	s_add_i32 s0, s43, -15
	global_store_short v[4:5], v0, off
	v_cvt_pk_bf16_f32 v0, v38, s0
	v_mad_u64_u32 v[4:5], s[0:1], s0, v222, v[2:3]
	s_add_i32 s0, s43, -14
	global_store_short v[4:5], v0, off
	v_cvt_pk_bf16_f32 v0, v39, s0
	v_mad_u64_u32 v[4:5], s[0:1], s0, v222, v[2:3]
	s_add_i32 s0, s43, -13
	global_store_short v[4:5], v0, off
	v_cvt_pk_bf16_f32 v0, v40, s0
	v_mad_u64_u32 v[4:5], s[0:1], s0, v222, v[2:3]
	s_add_i32 s0, s43, -12
	global_store_short v[4:5], v0, off
	v_cvt_pk_bf16_f32 v0, v41, s0
	v_mad_u64_u32 v[4:5], s[0:1], s0, v222, v[2:3]
	s_add_i32 s0, s43, -11
	global_store_short v[4:5], v0, off
	v_cvt_pk_bf16_f32 v0, v42, s0
	v_mad_u64_u32 v[4:5], s[0:1], s0, v222, v[2:3]
	s_add_i32 s0, s43, -10
	global_store_short v[4:5], v0, off
	v_cvt_pk_bf16_f32 v0, v43, s0
	v_mad_u64_u32 v[4:5], s[0:1], s0, v222, v[2:3]
	s_add_i32 s0, s43, -9
	global_store_short v[4:5], v0, off
	v_cvt_pk_bf16_f32 v0, v44, s0
	v_mad_u64_u32 v[4:5], s[0:1], s0, v222, v[2:3]
	s_add_i32 s0, s43, -8
	global_store_short v[4:5], v0, off
	v_cvt_pk_bf16_f32 v0, v45, s0
	v_mad_u64_u32 v[4:5], s[0:1], s0, v222, v[2:3]
	s_add_i32 s0, s43, -7
	global_store_short v[4:5], v0, off
	v_cvt_pk_bf16_f32 v0, v46, s0
	v_mad_u64_u32 v[4:5], s[0:1], s0, v222, v[2:3]
	s_add_i32 s0, s43, -6
	global_store_short v[4:5], v0, off
	v_cvt_pk_bf16_f32 v0, v47, s0
	v_mad_u64_u32 v[4:5], s[0:1], s0, v222, v[2:3]
	s_add_i32 s0, s43, -5
	global_store_short v[4:5], v0, off
	v_cvt_pk_bf16_f32 v0, v48, s0
	v_mad_u64_u32 v[4:5], s[0:1], s0, v222, v[2:3]
	s_add_i32 s0, s43, -4
	global_store_short v[4:5], v0, off
	v_cvt_pk_bf16_f32 v0, v49, s0
	v_mad_u64_u32 v[4:5], s[0:1], s0, v222, v[2:3]
	s_add_i32 s0, s43, -3
	global_store_short v[4:5], v0, off
	v_cvt_pk_bf16_f32 v0, v50, s0
	v_mad_u64_u32 v[4:5], s[0:1], s0, v222, v[2:3]
	s_add_i32 s0, s43, -2
	global_store_short v[4:5], v0, off
	v_cvt_pk_bf16_f32 v0, v51, s0
	v_mad_u64_u32 v[4:5], s[0:1], s0, v222, v[2:3]
	s_add_i32 s0, s43, -1
	global_store_short v[4:5], v0, off
	v_cvt_pk_bf16_f32 v0, v52, s0
	v_mad_u64_u32 v[4:5], s[0:1], s0, v222, v[2:3]
	global_store_short v[4:5], v0, off
